# K-loops: first iteration peeled with C=0 MFMAs (no accumulator zeroing), loop-counter SALU hoisted ahead of the last phase barrier, setprio/waitcnt trimmed at phase heads; FFN-out GEMMs walk row panel
# speedup vs baseline: 1.0044x; 1.0044x over previous
.LBB0_114:
	s_lshl_b32 s26, s20, 20
	s_and_b64 s[50:51], s[22:23], exec
	s_cselect_b32 s50, s26, s55
	s_lshl_b32 s27, s48, 20
	s_and_b64 s[56:57], s[22:23], exec
	s_cselect_b32 s51, s27, s52
	s_addk_i32 s52, 0x100
	s_add_i32 s53, s55, 0x100
	s_mov_b32 s54, -2
	s_waitcnt vmcnt(0)
	v_add_u32_e32 v132, s55, v143
	v_add_u32_e32 v133, s55, v144
	ds_read_b128 v[150:153], v145
	ds_read_b128 v[154:157], v145 offset:1024
	ds_read_b128 v[158:161], v145 offset:2048
	ds_read_b128 v[162:165], v145 offset:3072
	ds_read_b128 v[166:169], v146
	ds_read_b128 v[170:173], v146 offset:1024
	ds_read_b128 v[174:177], v146 offset:2048
	ds_read_b128 v[178:181], v146 offset:3072
	s_cmp_eq_u32 s54, 28
	s_cselect_b32 s57, s50, s53
	s_cselect_b32 s56, s51, s52
	s_or_b32 s55, s57, 0x80
	s_add_i32 m0, s35, 0xc000
	ds_read_b128 v[182:185], v147
	ds_read_b128 v[186:189], v147 offset:1024
	ds_read_b128 v[190:193], v147 offset:2048
	ds_read_b128 v[194:197], v147 offset:3072
	ds_read_b128 v[198:201], v147 offset:4096
	ds_read_b128 v[212:215], v147 offset:5120
	ds_read_b128 v[218:221], v147 offset:6144
	ds_read_b128 v[222:225], v147 offset:7168
	global_load_lds_dwordx4 v133, s[4:5]
	s_add_i32 m0, s35, 0xe000
	s_nop 0
	global_load_lds_dwordx4 v132, s[4:5]
	s_waitcnt vmcnt(8)
	s_waitcnt lgkmcnt(0)
	s_setprio 1
	s_barrier
	v_mfma_f32_16x16x32_bf16 v[126:129], v[150:153], v[182:185], 0
	v_mfma_f32_16x16x32_bf16 v[122:125], v[158:161], v[182:185], 0
	v_mfma_f32_16x16x32_bf16 v[110:113], v[150:153], v[190:193], 0
	v_mfma_f32_16x16x32_bf16 v[106:109], v[158:161], v[190:193], 0
	v_mfma_f32_16x16x32_bf16 v[94:97], v[150:153], v[198:201], 0
	v_mfma_f32_16x16x32_bf16 v[90:93], v[158:161], v[198:201], 0
	v_mfma_f32_16x16x32_bf16 v[78:81], v[150:153], v[218:221], 0
	v_mfma_f32_16x16x32_bf16 v[74:77], v[158:161], v[218:221], 0
	v_mfma_f32_16x16x32_bf16 v[126:129], v[154:157], v[186:189], v[126:129]
	v_mfma_f32_16x16x32_bf16 v[122:125], v[162:165], v[186:189], v[122:125]
	v_mfma_f32_16x16x32_bf16 v[110:113], v[154:157], v[194:197], v[110:113]
	v_mfma_f32_16x16x32_bf16 v[106:109], v[162:165], v[194:197], v[106:109]
	v_mfma_f32_16x16x32_bf16 v[94:97], v[154:157], v[212:215], v[94:97]
	v_mfma_f32_16x16x32_bf16 v[90:93], v[162:165], v[212:215], v[90:93]
	v_mfma_f32_16x16x32_bf16 v[78:81], v[154:157], v[222:225], v[78:81]
	v_mfma_f32_16x16x32_bf16 v[74:77], v[162:165], v[222:225], v[74:77]
	s_setprio 0
	s_setprio 1
	v_mfma_f32_16x16x32_bf16 v[118:121], v[166:169], v[182:185], 0
	v_mfma_f32_16x16x32_bf16 v[114:117], v[174:177], v[182:185], 0
	v_mfma_f32_16x16x32_bf16 v[102:105], v[166:169], v[190:193], 0
	v_mfma_f32_16x16x32_bf16 v[98:101], v[174:177], v[190:193], 0
	v_mfma_f32_16x16x32_bf16 v[86:89], v[166:169], v[198:201], 0
	v_mfma_f32_16x16x32_bf16 v[82:85], v[174:177], v[198:201], 0
	v_mfma_f32_16x16x32_bf16 v[70:73], v[166:169], v[218:221], 0
	v_mfma_f32_16x16x32_bf16 v[66:69], v[174:177], v[218:221], 0
	v_mfma_f32_16x16x32_bf16 v[118:121], v[170:173], v[186:189], v[118:121]
	v_mfma_f32_16x16x32_bf16 v[114:117], v[178:181], v[186:189], v[114:117]
	v_mfma_f32_16x16x32_bf16 v[102:105], v[170:173], v[194:197], v[102:105]
	v_mfma_f32_16x16x32_bf16 v[98:101], v[178:181], v[194:197], v[98:101]
	v_mfma_f32_16x16x32_bf16 v[86:89], v[170:173], v[212:215], v[86:89]
	v_mfma_f32_16x16x32_bf16 v[82:85], v[178:181], v[212:215], v[82:85]
	v_mfma_f32_16x16x32_bf16 v[70:73], v[170:173], v[222:225], v[70:73]
	v_mfma_f32_16x16x32_bf16 v[66:69], v[178:181], v[222:225], v[66:69]
	s_setprio 0
	s_barrier
	s_mov_b32 m0, s25
	v_add_u32_e32 v134, s56, v137
	ds_read_b128 v[182:185], v147 offset:16384
	ds_read_b128 v[186:189], v147 offset:17408
	ds_read_b128 v[190:193], v147 offset:18432
	ds_read_b128 v[194:197], v147 offset:19456
	ds_read_b128 v[198:201], v147 offset:20480
	ds_read_b128 v[212:215], v147 offset:21504
	ds_read_b128 v[218:221], v147 offset:22528
	ds_read_b128 v[222:225], v147 offset:23552
	global_load_lds_dwordx4 v134, s[6:7]
	v_add_u32_e32 v134, s56, v139
	s_mov_b32 m0, s30
	s_add_i32 s58, s56, 0x80000
	global_load_lds_dwordx4 v134, s[6:7]
	v_add_u32_e32 v134, s58, v137
	s_mov_b32 m0, s31
	s_nop 0
	global_load_lds_dwordx4 v134, s[6:7]
	v_add_u32_e32 v134, s58, v139
	s_mov_b32 m0, s34
	s_nop 0
	global_load_lds_dwordx4 v134, s[6:7]
	v_add_u32_e32 v134, s57, v136
	s_mov_b32 m0, s35
	s_nop 0
	global_load_lds_dwordx4 v134, s[4:5]
	v_add_u32_e32 v134, s57, v138
	s_mov_b32 m0, s36
	s_nop 0
	global_load_lds_dwordx4 v134, s[4:5]
	s_waitcnt vmcnt(8)
	s_waitcnt lgkmcnt(0)
	s_setprio 1
	s_barrier
	v_mfma_f32_16x16x32_bf16 v[62:65], v[150:153], v[182:185], 0
	v_mfma_f32_16x16x32_bf16 v[58:61], v[158:161], v[182:185], 0
	v_mfma_f32_16x16x32_bf16 v[46:49], v[150:153], v[190:193], 0
	v_mfma_f32_16x16x32_bf16 v[42:45], v[158:161], v[190:193], 0
	v_mfma_f32_16x16x32_bf16 v[30:33], v[150:153], v[198:201], 0
	v_mfma_f32_16x16x32_bf16 v[26:29], v[158:161], v[198:201], 0
	v_mfma_f32_16x16x32_bf16 v[14:17], v[150:153], v[218:221], 0
	v_mfma_f32_16x16x32_bf16 v[10:13], v[158:161], v[218:221], 0
	v_mfma_f32_16x16x32_bf16 v[62:65], v[154:157], v[186:189], v[62:65]
	v_mfma_f32_16x16x32_bf16 v[58:61], v[162:165], v[186:189], v[58:61]
	v_mfma_f32_16x16x32_bf16 v[46:49], v[154:157], v[194:197], v[46:49]
	v_mfma_f32_16x16x32_bf16 v[42:45], v[162:165], v[194:197], v[42:45]
	v_mfma_f32_16x16x32_bf16 v[30:33], v[154:157], v[212:215], v[30:33]
	v_mfma_f32_16x16x32_bf16 v[26:29], v[162:165], v[212:215], v[26:29]
	v_mfma_f32_16x16x32_bf16 v[14:17], v[154:157], v[222:225], v[14:17]
	v_mfma_f32_16x16x32_bf16 v[10:13], v[162:165], v[222:225], v[10:13]
	s_setprio 0
	s_setprio 1
	v_mfma_f32_16x16x32_bf16 v[54:57], v[166:169], v[182:185], 0
	v_mfma_f32_16x16x32_bf16 v[50:53], v[174:177], v[182:185], 0
	v_mfma_f32_16x16x32_bf16 v[38:41], v[166:169], v[190:193], 0
	v_mfma_f32_16x16x32_bf16 v[34:37], v[174:177], v[190:193], 0
	v_mfma_f32_16x16x32_bf16 v[22:25], v[166:169], v[198:201], 0
	v_mfma_f32_16x16x32_bf16 v[18:21], v[174:177], v[198:201], 0
	v_mfma_f32_16x16x32_bf16 v[6:9], v[166:169], v[218:221], 0
	v_mfma_f32_16x16x32_bf16 v[2:5], v[174:177], v[218:221], 0
	v_mfma_f32_16x16x32_bf16 v[54:57], v[170:173], v[186:189], v[54:57]
	v_mfma_f32_16x16x32_bf16 v[50:53], v[178:181], v[186:189], v[50:53]
	v_mfma_f32_16x16x32_bf16 v[38:41], v[170:173], v[194:197], v[38:41]
	v_mfma_f32_16x16x32_bf16 v[34:37], v[178:181], v[194:197], v[34:37]
	v_mfma_f32_16x16x32_bf16 v[22:25], v[170:173], v[212:215], v[22:25]
	v_mfma_f32_16x16x32_bf16 v[18:21], v[178:181], v[212:215], v[18:21]
	v_mfma_f32_16x16x32_bf16 v[6:9], v[170:173], v[222:225], v[6:9]
	v_mfma_f32_16x16x32_bf16 v[2:5], v[178:181], v[222:225], v[2:5]
	s_setprio 0
	s_barrier
	ds_read_b128 v[150:153], v148
	ds_read_b128 v[154:157], v148 offset:1024
	ds_read_b128 v[158:161], v148 offset:2048
	ds_read_b128 v[162:165], v148 offset:3072
	ds_read_b128 v[166:169], v149
	ds_read_b128 v[170:173], v149 offset:1024
	ds_read_b128 v[174:177], v149 offset:2048
	ds_read_b128 v[178:181], v149 offset:3072
	s_add_i32 s57, s57, 0x80000
	s_mov_b32 m0, s37
	v_add_u32_e32 v134, s57, v136
	ds_read_b128 v[182:185], v147 offset:32768
	ds_read_b128 v[186:189], v147 offset:33792
	ds_read_b128 v[190:193], v147 offset:34816
	ds_read_b128 v[194:197], v147 offset:35840
	ds_read_b128 v[198:201], v147 offset:36864
	ds_read_b128 v[212:215], v147 offset:37888
	ds_read_b128 v[218:221], v147 offset:38912
	ds_read_b128 v[222:225], v147 offset:39936
	global_load_lds_dwordx4 v134, s[4:5]
	v_add_u32_e32 v134, s57, v138
	s_mov_b32 m0, s38
	s_nop 0
	global_load_lds_dwordx4 v134, s[4:5]
	s_waitcnt vmcnt(8)
	s_waitcnt lgkmcnt(0)
	s_setprio 1
	s_barrier
	v_mfma_f32_16x16x32_bf16 v[126:129], v[150:153], v[182:185], v[126:129]
	v_mfma_f32_16x16x32_bf16 v[122:125], v[158:161], v[182:185], v[122:125]
	v_mfma_f32_16x16x32_bf16 v[110:113], v[150:153], v[190:193], v[110:113]
	v_mfma_f32_16x16x32_bf16 v[106:109], v[158:161], v[190:193], v[106:109]
	v_mfma_f32_16x16x32_bf16 v[94:97], v[150:153], v[198:201], v[94:97]
	v_mfma_f32_16x16x32_bf16 v[90:93], v[158:161], v[198:201], v[90:93]
	v_mfma_f32_16x16x32_bf16 v[78:81], v[150:153], v[218:221], v[78:81]
	v_mfma_f32_16x16x32_bf16 v[74:77], v[158:161], v[218:221], v[74:77]
	v_mfma_f32_16x16x32_bf16 v[126:129], v[154:157], v[186:189], v[126:129]
	v_mfma_f32_16x16x32_bf16 v[122:125], v[162:165], v[186:189], v[122:125]
	v_mfma_f32_16x16x32_bf16 v[110:113], v[154:157], v[194:197], v[110:113]
	v_mfma_f32_16x16x32_bf16 v[106:109], v[162:165], v[194:197], v[106:109]
	v_mfma_f32_16x16x32_bf16 v[94:97], v[154:157], v[212:215], v[94:97]
	v_mfma_f32_16x16x32_bf16 v[90:93], v[162:165], v[212:215], v[90:93]
	v_mfma_f32_16x16x32_bf16 v[78:81], v[154:157], v[222:225], v[78:81]
	v_mfma_f32_16x16x32_bf16 v[74:77], v[162:165], v[222:225], v[74:77]
	s_setprio 0
	s_setprio 1
	v_mfma_f32_16x16x32_bf16 v[118:121], v[166:169], v[182:185], v[118:121]
	v_mfma_f32_16x16x32_bf16 v[114:117], v[174:177], v[182:185], v[114:117]
	v_mfma_f32_16x16x32_bf16 v[102:105], v[166:169], v[190:193], v[102:105]
	v_mfma_f32_16x16x32_bf16 v[98:101], v[174:177], v[190:193], v[98:101]
	v_mfma_f32_16x16x32_bf16 v[86:89], v[166:169], v[198:201], v[86:89]
	v_mfma_f32_16x16x32_bf16 v[82:85], v[174:177], v[198:201], v[82:85]
	v_mfma_f32_16x16x32_bf16 v[70:73], v[166:169], v[218:221], v[70:73]
	v_mfma_f32_16x16x32_bf16 v[66:69], v[174:177], v[218:221], v[66:69]
	v_mfma_f32_16x16x32_bf16 v[118:121], v[170:173], v[186:189], v[118:121]
	v_mfma_f32_16x16x32_bf16 v[114:117], v[178:181], v[186:189], v[114:117]
	v_mfma_f32_16x16x32_bf16 v[102:105], v[170:173], v[194:197], v[102:105]
	v_mfma_f32_16x16x32_bf16 v[98:101], v[178:181], v[194:197], v[98:101]
	v_mfma_f32_16x16x32_bf16 v[86:89], v[170:173], v[212:215], v[86:89]
	v_mfma_f32_16x16x32_bf16 v[82:85], v[178:181], v[212:215], v[82:85]
	v_mfma_f32_16x16x32_bf16 v[70:73], v[170:173], v[222:225], v[70:73]
	v_mfma_f32_16x16x32_bf16 v[66:69], v[178:181], v[222:225], v[66:69]
	s_setprio 0
	s_barrier
	s_or_b32 s57, s56, 0x80
	s_mov_b32 m0, s39
	v_add_u32_e32 v134, s57, v137
	ds_read_b128 v[182:185], v147 offset:49152
	ds_read_b128 v[186:189], v147 offset:50176
	ds_read_b128 v[190:193], v147 offset:51200
	ds_read_b128 v[194:197], v147 offset:52224
	ds_read_b128 v[198:201], v147 offset:53248
	ds_read_b128 v[212:215], v147 offset:54272
	ds_read_b128 v[218:221], v147 offset:55296
	ds_read_b128 v[222:225], v147 offset:56320
	global_load_lds_dwordx4 v134, s[6:7]
	v_add_u32_e32 v134, s57, v139
	s_mov_b32 m0, s40
	s_add_i32 s56, s56, 0x80080
	global_load_lds_dwordx4 v134, s[6:7]
	v_add_u32_e32 v134, s56, v137
	s_mov_b32 m0, s43
	s_nop 0
	global_load_lds_dwordx4 v134, s[6:7]
	v_add_u32_e32 v134, s56, v139
	s_mov_b32 m0, s44
	s_nop 0
	global_load_lds_dwordx4 v134, s[6:7]
	v_add_u32_e32 v134, s55, v136
	s_mov_b32 m0, s41
	s_nop 0
	global_load_lds_dwordx4 v134, s[4:5]
	v_add_u32_e32 v134, s55, v138
	s_mov_b32 m0, s42
	s_nop 0
	global_load_lds_dwordx4 v134, s[4:5]
	s_waitcnt vmcnt(8)
	s_waitcnt lgkmcnt(0)
	s_setprio 1
	s_barrier
	v_mfma_f32_16x16x32_bf16 v[62:65], v[150:153], v[182:185], v[62:65]
	v_mfma_f32_16x16x32_bf16 v[58:61], v[158:161], v[182:185], v[58:61]
	v_mfma_f32_16x16x32_bf16 v[46:49], v[150:153], v[190:193], v[46:49]
	v_mfma_f32_16x16x32_bf16 v[42:45], v[158:161], v[190:193], v[42:45]
	v_mfma_f32_16x16x32_bf16 v[30:33], v[150:153], v[198:201], v[30:33]
	v_mfma_f32_16x16x32_bf16 v[26:29], v[158:161], v[198:201], v[26:29]
	v_mfma_f32_16x16x32_bf16 v[14:17], v[150:153], v[218:221], v[14:17]
	v_mfma_f32_16x16x32_bf16 v[10:13], v[158:161], v[218:221], v[10:13]
	v_mfma_f32_16x16x32_bf16 v[62:65], v[154:157], v[186:189], v[62:65]
	v_mfma_f32_16x16x32_bf16 v[58:61], v[162:165], v[186:189], v[58:61]
	v_mfma_f32_16x16x32_bf16 v[46:49], v[154:157], v[194:197], v[46:49]
	v_mfma_f32_16x16x32_bf16 v[42:45], v[162:165], v[194:197], v[42:45]
	v_mfma_f32_16x16x32_bf16 v[30:33], v[154:157], v[212:215], v[30:33]
	v_mfma_f32_16x16x32_bf16 v[26:29], v[162:165], v[212:215], v[26:29]
	v_mfma_f32_16x16x32_bf16 v[14:17], v[154:157], v[222:225], v[14:17]
	v_mfma_f32_16x16x32_bf16 v[10:13], v[162:165], v[222:225], v[10:13]
	s_setprio 0
	s_setprio 1
	v_mfma_f32_16x16x32_bf16 v[54:57], v[166:169], v[182:185], v[54:57]
	v_mfma_f32_16x16x32_bf16 v[50:53], v[174:177], v[182:185], v[50:53]
	v_mfma_f32_16x16x32_bf16 v[38:41], v[166:169], v[190:193], v[38:41]
	v_mfma_f32_16x16x32_bf16 v[34:37], v[174:177], v[190:193], v[34:37]
	v_mfma_f32_16x16x32_bf16 v[22:25], v[166:169], v[198:201], v[22:25]
	v_mfma_f32_16x16x32_bf16 v[18:21], v[174:177], v[198:201], v[18:21]
	v_mfma_f32_16x16x32_bf16 v[6:9], v[166:169], v[218:221], v[6:9]
	v_mfma_f32_16x16x32_bf16 v[2:5], v[174:177], v[218:221], v[2:5]
	v_mfma_f32_16x16x32_bf16 v[54:57], v[170:173], v[186:189], v[54:57]
	v_mfma_f32_16x16x32_bf16 v[50:53], v[178:181], v[186:189], v[50:53]
	v_mfma_f32_16x16x32_bf16 v[38:41], v[170:173], v[194:197], v[38:41]
	v_mfma_f32_16x16x32_bf16 v[34:37], v[178:181], v[194:197], v[34:37]
	v_mfma_f32_16x16x32_bf16 v[22:25], v[170:173], v[212:215], v[22:25]
	v_mfma_f32_16x16x32_bf16 v[18:21], v[178:181], v[212:215], v[18:21]
	v_mfma_f32_16x16x32_bf16 v[6:9], v[170:173], v[222:225], v[6:9]
	v_mfma_f32_16x16x32_bf16 v[2:5], v[178:181], v[222:225], v[2:5]
	s_setprio 0
	s_barrier
	s_add_i32 s54, s54, 2
	s_addk_i32 s52, 0x100
	s_addk_i32 s53, 0x100
	v_add_u32_e32 v132, 0x100, v132
	s_cmp_gt_u32 s54, 29
	v_add_u32_e32 v133, 0x100, v133
.LBB0_115:
	ds_read_b128 v[150:153], v145
	ds_read_b128 v[154:157], v145 offset:1024
	ds_read_b128 v[158:161], v145 offset:2048
	ds_read_b128 v[162:165], v145 offset:3072
	ds_read_b128 v[166:169], v146
	ds_read_b128 v[170:173], v146 offset:1024
	ds_read_b128 v[174:177], v146 offset:2048
	ds_read_b128 v[178:181], v146 offset:3072
	s_cmp_eq_u32 s54, 28
	s_cselect_b32 s57, s50, s53
	s_cselect_b32 s56, s51, s52
	s_or_b32 s55, s57, 0x80
	s_add_i32 m0, s35, 0xc000
	ds_read_b128 v[182:185], v147
	ds_read_b128 v[186:189], v147 offset:1024
	ds_read_b128 v[190:193], v147 offset:2048
	ds_read_b128 v[194:197], v147 offset:3072
	ds_read_b128 v[198:201], v147 offset:4096
	ds_read_b128 v[212:215], v147 offset:5120
	ds_read_b128 v[218:221], v147 offset:6144
	ds_read_b128 v[222:225], v147 offset:7168
	global_load_lds_dwordx4 v133, s[4:5]
	s_add_i32 m0, s35, 0xe000
	s_nop 0
	global_load_lds_dwordx4 v132, s[4:5]
	s_waitcnt vmcnt(8)
	s_waitcnt lgkmcnt(0)
	s_setprio 1
	s_barrier
	v_mfma_f32_16x16x32_bf16 v[126:129], v[150:153], v[182:185], v[126:129]
	v_mfma_f32_16x16x32_bf16 v[122:125], v[158:161], v[182:185], v[122:125]
	v_mfma_f32_16x16x32_bf16 v[110:113], v[150:153], v[190:193], v[110:113]
	v_mfma_f32_16x16x32_bf16 v[106:109], v[158:161], v[190:193], v[106:109]
	v_mfma_f32_16x16x32_bf16 v[94:97], v[150:153], v[198:201], v[94:97]
	v_mfma_f32_16x16x32_bf16 v[90:93], v[158:161], v[198:201], v[90:93]
	v_mfma_f32_16x16x32_bf16 v[78:81], v[150:153], v[218:221], v[78:81]
	v_mfma_f32_16x16x32_bf16 v[74:77], v[158:161], v[218:221], v[74:77]
	v_mfma_f32_16x16x32_bf16 v[126:129], v[154:157], v[186:189], v[126:129]
	v_mfma_f32_16x16x32_bf16 v[122:125], v[162:165], v[186:189], v[122:125]
	v_mfma_f32_16x16x32_bf16 v[110:113], v[154:157], v[194:197], v[110:113]
	v_mfma_f32_16x16x32_bf16 v[106:109], v[162:165], v[194:197], v[106:109]
	v_mfma_f32_16x16x32_bf16 v[94:97], v[154:157], v[212:215], v[94:97]
	v_mfma_f32_16x16x32_bf16 v[90:93], v[162:165], v[212:215], v[90:93]
	v_mfma_f32_16x16x32_bf16 v[78:81], v[154:157], v[222:225], v[78:81]
	v_mfma_f32_16x16x32_bf16 v[74:77], v[162:165], v[222:225], v[74:77]
	s_setprio 0
	s_setprio 1
	v_mfma_f32_16x16x32_bf16 v[118:121], v[166:169], v[182:185], v[118:121]
	v_mfma_f32_16x16x32_bf16 v[114:117], v[174:177], v[182:185], v[114:117]
	v_mfma_f32_16x16x32_bf16 v[102:105], v[166:169], v[190:193], v[102:105]
	v_mfma_f32_16x16x32_bf16 v[98:101], v[174:177], v[190:193], v[98:101]
	v_mfma_f32_16x16x32_bf16 v[86:89], v[166:169], v[198:201], v[86:89]
	v_mfma_f32_16x16x32_bf16 v[82:85], v[174:177], v[198:201], v[82:85]
	v_mfma_f32_16x16x32_bf16 v[70:73], v[166:169], v[218:221], v[70:73]
	v_mfma_f32_16x16x32_bf16 v[66:69], v[174:177], v[218:221], v[66:69]
	v_mfma_f32_16x16x32_bf16 v[118:121], v[170:173], v[186:189], v[118:121]
	v_mfma_f32_16x16x32_bf16 v[114:117], v[178:181], v[186:189], v[114:117]
	v_mfma_f32_16x16x32_bf16 v[102:105], v[170:173], v[194:197], v[102:105]
	v_mfma_f32_16x16x32_bf16 v[98:101], v[178:181], v[194:197], v[98:101]
	v_mfma_f32_16x16x32_bf16 v[86:89], v[170:173], v[212:215], v[86:89]
	v_mfma_f32_16x16x32_bf16 v[82:85], v[178:181], v[212:215], v[82:85]
	v_mfma_f32_16x16x32_bf16 v[70:73], v[170:173], v[222:225], v[70:73]
	v_mfma_f32_16x16x32_bf16 v[66:69], v[178:181], v[222:225], v[66:69]
	s_setprio 0
	s_barrier
	s_mov_b32 m0, s25
	v_add_u32_e32 v134, s56, v137
	ds_read_b128 v[182:185], v147 offset:16384
	ds_read_b128 v[186:189], v147 offset:17408
	ds_read_b128 v[190:193], v147 offset:18432
	ds_read_b128 v[194:197], v147 offset:19456
	ds_read_b128 v[198:201], v147 offset:20480
	ds_read_b128 v[212:215], v147 offset:21504
	ds_read_b128 v[218:221], v147 offset:22528
	ds_read_b128 v[222:225], v147 offset:23552
	global_load_lds_dwordx4 v134, s[6:7]
	v_add_u32_e32 v134, s56, v139
	s_mov_b32 m0, s30
	s_add_i32 s58, s56, 0x80000
	global_load_lds_dwordx4 v134, s[6:7]
	v_add_u32_e32 v134, s58, v137
	s_mov_b32 m0, s31
	s_nop 0
	global_load_lds_dwordx4 v134, s[6:7]
	v_add_u32_e32 v134, s58, v139
	s_mov_b32 m0, s34
	s_nop 0
	global_load_lds_dwordx4 v134, s[6:7]
	v_add_u32_e32 v134, s57, v136
	s_mov_b32 m0, s35
	s_nop 0
	global_load_lds_dwordx4 v134, s[4:5]
	v_add_u32_e32 v134, s57, v138
	s_mov_b32 m0, s36
	s_nop 0
	global_load_lds_dwordx4 v134, s[4:5]
	s_waitcnt vmcnt(8)
	s_waitcnt lgkmcnt(0)
	s_setprio 1
	s_barrier
	v_mfma_f32_16x16x32_bf16 v[62:65], v[150:153], v[182:185], v[62:65]
	v_mfma_f32_16x16x32_bf16 v[58:61], v[158:161], v[182:185], v[58:61]
	v_mfma_f32_16x16x32_bf16 v[46:49], v[150:153], v[190:193], v[46:49]
	v_mfma_f32_16x16x32_bf16 v[42:45], v[158:161], v[190:193], v[42:45]
	v_mfma_f32_16x16x32_bf16 v[30:33], v[150:153], v[198:201], v[30:33]
	v_mfma_f32_16x16x32_bf16 v[26:29], v[158:161], v[198:201], v[26:29]
	v_mfma_f32_16x16x32_bf16 v[14:17], v[150:153], v[218:221], v[14:17]
	v_mfma_f32_16x16x32_bf16 v[10:13], v[158:161], v[218:221], v[10:13]
	v_mfma_f32_16x16x32_bf16 v[62:65], v[154:157], v[186:189], v[62:65]
	v_mfma_f32_16x16x32_bf16 v[58:61], v[162:165], v[186:189], v[58:61]
	v_mfma_f32_16x16x32_bf16 v[46:49], v[154:157], v[194:197], v[46:49]
	v_mfma_f32_16x16x32_bf16 v[42:45], v[162:165], v[194:197], v[42:45]
	v_mfma_f32_16x16x32_bf16 v[30:33], v[154:157], v[212:215], v[30:33]
	v_mfma_f32_16x16x32_bf16 v[26:29], v[162:165], v[212:215], v[26:29]
	v_mfma_f32_16x16x32_bf16 v[14:17], v[154:157], v[222:225], v[14:17]
	v_mfma_f32_16x16x32_bf16 v[10:13], v[162:165], v[222:225], v[10:13]
	s_setprio 0
	s_setprio 1
	v_mfma_f32_16x16x32_bf16 v[54:57], v[166:169], v[182:185], v[54:57]
	v_mfma_f32_16x16x32_bf16 v[50:53], v[174:177], v[182:185], v[50:53]
	v_mfma_f32_16x16x32_bf16 v[38:41], v[166:169], v[190:193], v[38:41]
	v_mfma_f32_16x16x32_bf16 v[34:37], v[174:177], v[190:193], v[34:37]
	v_mfma_f32_16x16x32_bf16 v[22:25], v[166:169], v[198:201], v[22:25]
	v_mfma_f32_16x16x32_bf16 v[18:21], v[174:177], v[198:201], v[18:21]
	v_mfma_f32_16x16x32_bf16 v[6:9], v[166:169], v[218:221], v[6:9]
	v_mfma_f32_16x16x32_bf16 v[2:5], v[174:177], v[218:221], v[2:5]
	v_mfma_f32_16x16x32_bf16 v[54:57], v[170:173], v[186:189], v[54:57]
	v_mfma_f32_16x16x32_bf16 v[50:53], v[178:181], v[186:189], v[50:53]
	v_mfma_f32_16x16x32_bf16 v[38:41], v[170:173], v[194:197], v[38:41]
	v_mfma_f32_16x16x32_bf16 v[34:37], v[178:181], v[194:197], v[34:37]
	v_mfma_f32_16x16x32_bf16 v[22:25], v[170:173], v[212:215], v[22:25]
	v_mfma_f32_16x16x32_bf16 v[18:21], v[178:181], v[212:215], v[18:21]
	v_mfma_f32_16x16x32_bf16 v[6:9], v[170:173], v[222:225], v[6:9]
	v_mfma_f32_16x16x32_bf16 v[2:5], v[178:181], v[222:225], v[2:5]
	s_setprio 0
	s_barrier
	ds_read_b128 v[150:153], v148
	ds_read_b128 v[154:157], v148 offset:1024
	ds_read_b128 v[158:161], v148 offset:2048
	ds_read_b128 v[162:165], v148 offset:3072
	ds_read_b128 v[166:169], v149
	ds_read_b128 v[170:173], v149 offset:1024
	ds_read_b128 v[174:177], v149 offset:2048
	ds_read_b128 v[178:181], v149 offset:3072
	s_add_i32 s57, s57, 0x80000
	s_mov_b32 m0, s37
	v_add_u32_e32 v134, s57, v136
	ds_read_b128 v[182:185], v147 offset:32768
	ds_read_b128 v[186:189], v147 offset:33792
	ds_read_b128 v[190:193], v147 offset:34816
	ds_read_b128 v[194:197], v147 offset:35840
	ds_read_b128 v[198:201], v147 offset:36864
	ds_read_b128 v[212:215], v147 offset:37888
	ds_read_b128 v[218:221], v147 offset:38912
	ds_read_b128 v[222:225], v147 offset:39936
	global_load_lds_dwordx4 v134, s[4:5]
	v_add_u32_e32 v134, s57, v138
	s_mov_b32 m0, s38
	s_nop 0
	global_load_lds_dwordx4 v134, s[4:5]
	s_waitcnt vmcnt(8)
	s_waitcnt lgkmcnt(0)
	s_setprio 1
	s_barrier
	v_mfma_f32_16x16x32_bf16 v[126:129], v[150:153], v[182:185], v[126:129]
	v_mfma_f32_16x16x32_bf16 v[122:125], v[158:161], v[182:185], v[122:125]
	v_mfma_f32_16x16x32_bf16 v[110:113], v[150:153], v[190:193], v[110:113]
	v_mfma_f32_16x16x32_bf16 v[106:109], v[158:161], v[190:193], v[106:109]
	v_mfma_f32_16x16x32_bf16 v[94:97], v[150:153], v[198:201], v[94:97]
	v_mfma_f32_16x16x32_bf16 v[90:93], v[158:161], v[198:201], v[90:93]
	v_mfma_f32_16x16x32_bf16 v[78:81], v[150:153], v[218:221], v[78:81]
	v_mfma_f32_16x16x32_bf16 v[74:77], v[158:161], v[218:221], v[74:77]
	v_mfma_f32_16x16x32_bf16 v[126:129], v[154:157], v[186:189], v[126:129]
	v_mfma_f32_16x16x32_bf16 v[122:125], v[162:165], v[186:189], v[122:125]
	v_mfma_f32_16x16x32_bf16 v[110:113], v[154:157], v[194:197], v[110:113]
	v_mfma_f32_16x16x32_bf16 v[106:109], v[162:165], v[194:197], v[106:109]
	v_mfma_f32_16x16x32_bf16 v[94:97], v[154:157], v[212:215], v[94:97]
	v_mfma_f32_16x16x32_bf16 v[90:93], v[162:165], v[212:215], v[90:93]
	v_mfma_f32_16x16x32_bf16 v[78:81], v[154:157], v[222:225], v[78:81]
	v_mfma_f32_16x16x32_bf16 v[74:77], v[162:165], v[222:225], v[74:77]
	s_setprio 0
	s_setprio 1
	v_mfma_f32_16x16x32_bf16 v[118:121], v[166:169], v[182:185], v[118:121]
	v_mfma_f32_16x16x32_bf16 v[114:117], v[174:177], v[182:185], v[114:117]
	v_mfma_f32_16x16x32_bf16 v[102:105], v[166:169], v[190:193], v[102:105]
	v_mfma_f32_16x16x32_bf16 v[98:101], v[174:177], v[190:193], v[98:101]
	v_mfma_f32_16x16x32_bf16 v[86:89], v[166:169], v[198:201], v[86:89]
	v_mfma_f32_16x16x32_bf16 v[82:85], v[174:177], v[198:201], v[82:85]
	v_mfma_f32_16x16x32_bf16 v[70:73], v[166:169], v[218:221], v[70:73]
	v_mfma_f32_16x16x32_bf16 v[66:69], v[174:177], v[218:221], v[66:69]
	v_mfma_f32_16x16x32_bf16 v[118:121], v[170:173], v[186:189], v[118:121]
	v_mfma_f32_16x16x32_bf16 v[114:117], v[178:181], v[186:189], v[114:117]
	v_mfma_f32_16x16x32_bf16 v[102:105], v[170:173], v[194:197], v[102:105]
	v_mfma_f32_16x16x32_bf16 v[98:101], v[178:181], v[194:197], v[98:101]
	v_mfma_f32_16x16x32_bf16 v[86:89], v[170:173], v[212:215], v[86:89]
	v_mfma_f32_16x16x32_bf16 v[82:85], v[178:181], v[212:215], v[82:85]
	v_mfma_f32_16x16x32_bf16 v[70:73], v[170:173], v[222:225], v[70:73]
	v_mfma_f32_16x16x32_bf16 v[66:69], v[178:181], v[222:225], v[66:69]
	s_setprio 0
	s_barrier
	s_or_b32 s57, s56, 0x80
	s_mov_b32 m0, s39
	v_add_u32_e32 v134, s57, v137
	ds_read_b128 v[182:185], v147 offset:49152
	ds_read_b128 v[186:189], v147 offset:50176
	ds_read_b128 v[190:193], v147 offset:51200
	ds_read_b128 v[194:197], v147 offset:52224
	ds_read_b128 v[198:201], v147 offset:53248
	ds_read_b128 v[212:215], v147 offset:54272
	ds_read_b128 v[218:221], v147 offset:55296
	ds_read_b128 v[222:225], v147 offset:56320
	global_load_lds_dwordx4 v134, s[6:7]
	v_add_u32_e32 v134, s57, v139
	s_mov_b32 m0, s40
	s_add_i32 s56, s56, 0x80080
	global_load_lds_dwordx4 v134, s[6:7]
	v_add_u32_e32 v134, s56, v137
	s_mov_b32 m0, s43
	s_nop 0
	global_load_lds_dwordx4 v134, s[6:7]
	v_add_u32_e32 v134, s56, v139
	s_mov_b32 m0, s44
	s_nop 0
	global_load_lds_dwordx4 v134, s[6:7]
	v_add_u32_e32 v134, s55, v136
	s_mov_b32 m0, s41
	s_nop 0
	global_load_lds_dwordx4 v134, s[4:5]
	v_add_u32_e32 v134, s55, v138
	s_mov_b32 m0, s42
	s_nop 0
	global_load_lds_dwordx4 v134, s[4:5]
	s_add_i32 s54, s54, 2
	s_addk_i32 s52, 0x100
	s_addk_i32 s53, 0x100
	v_add_u32_e32 v132, 0x100, v132
	s_cmp_gt_u32 s54, 29
	v_add_u32_e32 v133, 0x100, v133
	s_waitcnt vmcnt(8)
	s_waitcnt lgkmcnt(0)
	s_setprio 1
	s_barrier
	v_mfma_f32_16x16x32_bf16 v[62:65], v[150:153], v[182:185], v[62:65]
	v_mfma_f32_16x16x32_bf16 v[58:61], v[158:161], v[182:185], v[58:61]
	v_mfma_f32_16x16x32_bf16 v[46:49], v[150:153], v[190:193], v[46:49]
	v_mfma_f32_16x16x32_bf16 v[42:45], v[158:161], v[190:193], v[42:45]
	v_mfma_f32_16x16x32_bf16 v[30:33], v[150:153], v[198:201], v[30:33]
	v_mfma_f32_16x16x32_bf16 v[26:29], v[158:161], v[198:201], v[26:29]
	v_mfma_f32_16x16x32_bf16 v[14:17], v[150:153], v[218:221], v[14:17]
	v_mfma_f32_16x16x32_bf16 v[10:13], v[158:161], v[218:221], v[10:13]
	v_mfma_f32_16x16x32_bf16 v[62:65], v[154:157], v[186:189], v[62:65]
	v_mfma_f32_16x16x32_bf16 v[58:61], v[162:165], v[186:189], v[58:61]
	v_mfma_f32_16x16x32_bf16 v[46:49], v[154:157], v[194:197], v[46:49]
	v_mfma_f32_16x16x32_bf16 v[42:45], v[162:165], v[194:197], v[42:45]
	v_mfma_f32_16x16x32_bf16 v[30:33], v[154:157], v[212:215], v[30:33]
	v_mfma_f32_16x16x32_bf16 v[26:29], v[162:165], v[212:215], v[26:29]
	v_mfma_f32_16x16x32_bf16 v[14:17], v[154:157], v[222:225], v[14:17]
	v_mfma_f32_16x16x32_bf16 v[10:13], v[162:165], v[222:225], v[10:13]
	s_setprio 0
	s_setprio 1
	v_mfma_f32_16x16x32_bf16 v[54:57], v[166:169], v[182:185], v[54:57]
	v_mfma_f32_16x16x32_bf16 v[50:53], v[174:177], v[182:185], v[50:53]
	v_mfma_f32_16x16x32_bf16 v[38:41], v[166:169], v[190:193], v[38:41]
	v_mfma_f32_16x16x32_bf16 v[34:37], v[174:177], v[190:193], v[34:37]
	v_mfma_f32_16x16x32_bf16 v[22:25], v[166:169], v[198:201], v[22:25]
	v_mfma_f32_16x16x32_bf16 v[18:21], v[174:177], v[198:201], v[18:21]
	v_mfma_f32_16x16x32_bf16 v[6:9], v[166:169], v[218:221], v[6:9]
	v_mfma_f32_16x16x32_bf16 v[2:5], v[174:177], v[218:221], v[2:5]
	v_mfma_f32_16x16x32_bf16 v[54:57], v[170:173], v[186:189], v[54:57]
	v_mfma_f32_16x16x32_bf16 v[50:53], v[178:181], v[186:189], v[50:53]
	v_mfma_f32_16x16x32_bf16 v[38:41], v[170:173], v[194:197], v[38:41]
	v_mfma_f32_16x16x32_bf16 v[34:37], v[178:181], v[194:197], v[34:37]
	v_mfma_f32_16x16x32_bf16 v[22:25], v[170:173], v[212:215], v[22:25]
	v_mfma_f32_16x16x32_bf16 v[18:21], v[178:181], v[212:215], v[18:21]
	v_mfma_f32_16x16x32_bf16 v[6:9], v[170:173], v[222:225], v[6:9]
	v_mfma_f32_16x16x32_bf16 v[2:5], v[178:181], v[222:225], v[2:5]
	s_setprio 0
	s_barrier
	s_cbranch_scc0 .LBB0_115
	s_and_b64 vcc, exec, s[16:17]
	s_cbranch_vccz .LBB0_118
	s_barrier

.LBB0_135:
	v_lshrrev_b32_e32 v9, 1, v5
	v_and_b32_e32 v135, 24, v9
	v_and_b32_e32 v136, 15, v5
	v_lshlrev_b32_e32 v9, 1, v135
	v_lshlrev_b32_e32 v5, 2, v5
	s_lshl_b32 s27, s27, 5
	s_lshl_b32 s26, s29, 6
	v_lshl_or_b32 v9, v136, 6, v9
	s_lshl_b32 s29, s29, 13
	v_and_b32_e32 v5, 32, v5
	s_and_b32 s27, s27, 0x60
	v_bitop3_b32 v10, v9, s29, v5 bitop3:0xde
	s_lshl_b32 s29, s27, 7
	v_bitop3_b32 v137, v9, s29, v5 bitop3:0xde
	s_add_i32 s29, s28, 0x18000
	s_or_b32 s31, s12, 0x80
	s_add_i32 s30, s29, s37
	v_add_u32_e32 v5, s31, v131
	s_mov_b32 m0, s30
	s_waitcnt vmcnt(2)
	s_barrier
	global_load_lds_dwordx4 v5, s[6:7]
	v_add_u32_e32 v5, s31, v133
	s_add_i32 s31, s30, 0x2000
	s_mov_b32 m0, s31
	s_or_b32 s35, s21, 0x80
	s_add_i32 s34, s22, 0x8000
	global_load_lds_dwordx4 v5, s[6:7]
	v_add_u32_e32 v5, s35, v130
	s_mov_b32 m0, s34
	s_add_i32 s36, s28, 0x1c000
	global_load_lds_dwordx4 v5, s[4:5]
	v_add_u32_e32 v5, s35, v132
	s_add_i32 s35, s22, 0xa000
	s_mov_b32 m0, s35
	s_or_b32 s38, s12, 0x80080
	s_add_i32 s37, s36, s37
	global_load_lds_dwordx4 v5, s[4:5]
	v_add_u32_e32 v5, s38, v131
	s_mov_b32 m0, s37
	s_add_i32 s39, s21, 0x80080
	global_load_lds_dwordx4 v5, s[6:7]
	v_add_u32_e32 v5, s38, v133
	s_add_i32 s38, s37, 0x2000
	s_mov_b32 m0, s38
	v_lshlrev_b32_e32 v7, 12, v7
	global_load_lds_dwordx4 v5, s[6:7]
	v_lshlrev_b32_e32 v5, 15, v6
	v_and_b32_e32 v5, 0xffff0000, v5
	v_and_b32_e32 v6, 1, v6
	v_add3_u32 v5, s39, v5, v7
	v_lshlrev_b32_e32 v6, 6, v6
	v_lshlrev_b32_e32 v7, 1, v8
	v_add3_u32 v138, v5, v6, v7
	v_lshlrev_b32_e32 v5, 15, v2
	v_and_b32_e32 v5, 0xffff0000, v5
	v_lshlrev_b32_e32 v3, 12, v3
	v_and_b32_e32 v2, 1, v2
	s_waitcnt vmcnt(6)
	v_add3_u32 v3, s39, v5, v3
	v_lshlrev_b32_e32 v2, 6, v2
	v_lshlrev_b32_e32 v4, 1, v4
	v_add3_u32 v139, v3, v2, v4
	v_or_b32_e32 v134, s26, v136
	s_mov_b32 s39, -2
	s_mov_b32 s40, 0
	v_add_u32_e32 v140, s28, v10
	s_barrier
	v_add_u32_e32 v141, s13, v137
	ds_read_b128 v[142:145], v141
	ds_read_b128 v[146:149], v141 offset:1024
	ds_read_b128 v[150:153], v141 offset:2048
	ds_read_b128 v[154:157], v141 offset:3072
	v_add_u32_e32 v141, s16, v137
	ds_read_b128 v[158:161], v141
	ds_read_b128 v[162:165], v141 offset:1024
	ds_read_b128 v[166:169], v141 offset:2048
	ds_read_b128 v[170:173], v141 offset:3072
	s_add_i32 s41, s40, 0x100
	s_cmp_lg_u32 s39, 28
	s_cselect_b32 s43, s41, 0
	s_add_i32 s44, s43, s21
	s_or_b32 s42, s44, 0x80
	s_add_i32 s43, s43, s12
	v_add_u32_e32 v141, s40, v139
	s_add_i32 m0, s22, 0xc000
	ds_read_b128 v[174:177], v140
	ds_read_b128 v[178:181], v140 offset:1024
	ds_read_b128 v[182:185], v140 offset:2048
	ds_read_b128 v[186:189], v140 offset:3072
	ds_read_b128 v[190:193], v140 offset:4096
	ds_read_b128 v[194:197], v140 offset:5120
	ds_read_b128 v[198:201], v140 offset:6144
	ds_read_b128 v[212:215], v140 offset:7168
	global_load_lds_dwordx4 v141, s[4:5]
	v_add_u32_e32 v141, s40, v138
	s_add_i32 m0, s22, 0xe000
	s_nop 0
	global_load_lds_dwordx4 v141, s[4:5]
	s_waitcnt vmcnt(8)
	s_waitcnt lgkmcnt(0)
	s_setprio 1
	s_barrier
	v_mfma_f32_16x16x32_bf16 v[126:129], v[142:145], v[174:177], 0
	v_mfma_f32_16x16x32_bf16 v[122:125], v[150:153], v[174:177], 0
	v_mfma_f32_16x16x32_bf16 v[110:113], v[142:145], v[182:185], 0
	v_mfma_f32_16x16x32_bf16 v[106:109], v[150:153], v[182:185], 0
	v_mfma_f32_16x16x32_bf16 v[94:97], v[142:145], v[190:193], 0
	v_mfma_f32_16x16x32_bf16 v[90:93], v[150:153], v[190:193], 0
	v_mfma_f32_16x16x32_bf16 v[78:81], v[142:145], v[198:201], 0
	v_mfma_f32_16x16x32_bf16 v[74:77], v[150:153], v[198:201], 0
	v_mfma_f32_16x16x32_bf16 v[126:129], v[146:149], v[178:181], v[126:129]
	v_mfma_f32_16x16x32_bf16 v[122:125], v[154:157], v[178:181], v[122:125]
	v_mfma_f32_16x16x32_bf16 v[110:113], v[146:149], v[186:189], v[110:113]
	v_mfma_f32_16x16x32_bf16 v[106:109], v[154:157], v[186:189], v[106:109]
	v_mfma_f32_16x16x32_bf16 v[94:97], v[146:149], v[194:197], v[94:97]
	v_mfma_f32_16x16x32_bf16 v[90:93], v[154:157], v[194:197], v[90:93]
	v_mfma_f32_16x16x32_bf16 v[78:81], v[146:149], v[212:215], v[78:81]
	v_mfma_f32_16x16x32_bf16 v[74:77], v[154:157], v[212:215], v[74:77]
	s_setprio 0
	s_setprio 1
	v_mfma_f32_16x16x32_bf16 v[118:121], v[158:161], v[174:177], 0
	v_mfma_f32_16x16x32_bf16 v[114:117], v[166:169], v[174:177], 0
	v_mfma_f32_16x16x32_bf16 v[102:105], v[158:161], v[182:185], 0
	v_mfma_f32_16x16x32_bf16 v[98:101], v[166:169], v[182:185], 0
	v_mfma_f32_16x16x32_bf16 v[86:89], v[158:161], v[190:193], 0
	v_mfma_f32_16x16x32_bf16 v[82:85], v[166:169], v[190:193], 0
	v_mfma_f32_16x16x32_bf16 v[70:73], v[158:161], v[198:201], 0
	v_mfma_f32_16x16x32_bf16 v[66:69], v[166:169], v[198:201], 0
	v_mfma_f32_16x16x32_bf16 v[118:121], v[162:165], v[178:181], v[118:121]
	v_mfma_f32_16x16x32_bf16 v[114:117], v[170:173], v[178:181], v[114:117]
	v_mfma_f32_16x16x32_bf16 v[102:105], v[162:165], v[186:189], v[102:105]
	v_mfma_f32_16x16x32_bf16 v[98:101], v[170:173], v[186:189], v[98:101]
	v_mfma_f32_16x16x32_bf16 v[86:89], v[162:165], v[194:197], v[86:89]
	v_mfma_f32_16x16x32_bf16 v[82:85], v[170:173], v[194:197], v[82:85]
	v_mfma_f32_16x16x32_bf16 v[70:73], v[162:165], v[212:215], v[70:73]
	v_mfma_f32_16x16x32_bf16 v[66:69], v[170:173], v[212:215], v[66:69]
	s_setprio 0
	s_barrier
	s_mov_b32 m0, s14
	v_add_u32_e32 v141, s43, v131
	ds_read_b128 v[174:177], v140 offset:16384
	ds_read_b128 v[178:181], v140 offset:17408
	ds_read_b128 v[182:185], v140 offset:18432
	ds_read_b128 v[186:189], v140 offset:19456
	ds_read_b128 v[190:193], v140 offset:20480
	ds_read_b128 v[194:197], v140 offset:21504
	ds_read_b128 v[198:201], v140 offset:22528
	ds_read_b128 v[212:215], v140 offset:23552
	global_load_lds_dwordx4 v141, s[6:7]
	v_add_u32_e32 v141, s43, v133
	s_mov_b32 m0, s15
	s_add_i32 s40, s43, 0x80000
	global_load_lds_dwordx4 v141, s[6:7]
	v_add_u32_e32 v141, s40, v131
	s_mov_b32 m0, s17
	s_nop 0
	global_load_lds_dwordx4 v141, s[6:7]
	v_add_u32_e32 v141, s40, v133
	s_mov_b32 m0, s20
	s_nop 0
	global_load_lds_dwordx4 v141, s[6:7]
	v_add_u32_e32 v141, s44, v130
	s_mov_b32 m0, s22
	s_nop 0
	global_load_lds_dwordx4 v141, s[4:5]
	v_add_u32_e32 v141, s44, v132
	s_mov_b32 m0, s23
	s_nop 0
	global_load_lds_dwordx4 v141, s[4:5]
	s_waitcnt vmcnt(8)
	s_waitcnt lgkmcnt(0)
	s_setprio 1
	s_barrier
	v_mfma_f32_16x16x32_bf16 v[62:65], v[142:145], v[174:177], 0
	v_mfma_f32_16x16x32_bf16 v[58:61], v[150:153], v[174:177], 0
	v_mfma_f32_16x16x32_bf16 v[46:49], v[142:145], v[182:185], 0
	v_mfma_f32_16x16x32_bf16 v[42:45], v[150:153], v[182:185], 0
	v_mfma_f32_16x16x32_bf16 v[30:33], v[142:145], v[190:193], 0
	v_mfma_f32_16x16x32_bf16 v[26:29], v[150:153], v[190:193], 0
	v_mfma_f32_16x16x32_bf16 v[14:17], v[142:145], v[198:201], 0
	v_mfma_f32_16x16x32_bf16 v[10:13], v[150:153], v[198:201], 0
	v_mfma_f32_16x16x32_bf16 v[62:65], v[146:149], v[178:181], v[62:65]
	v_mfma_f32_16x16x32_bf16 v[58:61], v[154:157], v[178:181], v[58:61]
	v_mfma_f32_16x16x32_bf16 v[46:49], v[146:149], v[186:189], v[46:49]
	v_mfma_f32_16x16x32_bf16 v[42:45], v[154:157], v[186:189], v[42:45]
	v_mfma_f32_16x16x32_bf16 v[30:33], v[146:149], v[194:197], v[30:33]
	v_mfma_f32_16x16x32_bf16 v[26:29], v[154:157], v[194:197], v[26:29]
	v_mfma_f32_16x16x32_bf16 v[14:17], v[146:149], v[212:215], v[14:17]
	v_mfma_f32_16x16x32_bf16 v[10:13], v[154:157], v[212:215], v[10:13]
	s_setprio 0
	s_setprio 1
	v_mfma_f32_16x16x32_bf16 v[54:57], v[158:161], v[174:177], 0
	v_mfma_f32_16x16x32_bf16 v[50:53], v[166:169], v[174:177], 0
	v_mfma_f32_16x16x32_bf16 v[38:41], v[158:161], v[182:185], 0
	v_mfma_f32_16x16x32_bf16 v[34:37], v[166:169], v[182:185], 0
	v_mfma_f32_16x16x32_bf16 v[22:25], v[158:161], v[190:193], 0
	v_mfma_f32_16x16x32_bf16 v[18:21], v[166:169], v[190:193], 0
	v_mfma_f32_16x16x32_bf16 v[6:9], v[158:161], v[198:201], 0
	v_mfma_f32_16x16x32_bf16 v[2:5], v[166:169], v[198:201], 0
	v_mfma_f32_16x16x32_bf16 v[54:57], v[162:165], v[178:181], v[54:57]
	v_mfma_f32_16x16x32_bf16 v[50:53], v[170:173], v[178:181], v[50:53]
	v_mfma_f32_16x16x32_bf16 v[38:41], v[162:165], v[186:189], v[38:41]
	v_mfma_f32_16x16x32_bf16 v[34:37], v[170:173], v[186:189], v[34:37]
	v_mfma_f32_16x16x32_bf16 v[22:25], v[162:165], v[194:197], v[22:25]
	v_mfma_f32_16x16x32_bf16 v[18:21], v[170:173], v[194:197], v[18:21]
	v_mfma_f32_16x16x32_bf16 v[6:9], v[162:165], v[212:215], v[6:9]
	v_mfma_f32_16x16x32_bf16 v[2:5], v[170:173], v[212:215], v[2:5]
	s_setprio 0
	s_barrier
	v_add_u32_e32 v141, s29, v137
	ds_read_b128 v[142:145], v141
	ds_read_b128 v[146:149], v141 offset:1024
	ds_read_b128 v[150:153], v141 offset:2048
	ds_read_b128 v[154:157], v141 offset:3072
	v_add_u32_e32 v141, s36, v137
	ds_read_b128 v[158:161], v141
	ds_read_b128 v[162:165], v141 offset:1024
	ds_read_b128 v[166:169], v141 offset:2048
	ds_read_b128 v[170:173], v141 offset:3072
	s_add_i32 s44, s44, 0x80000
	s_mov_b32 m0, s24
	v_add_u32_e32 v141, s44, v130
	ds_read_b128 v[174:177], v140 offset:32768
	ds_read_b128 v[178:181], v140 offset:33792
	ds_read_b128 v[182:185], v140 offset:34816
	ds_read_b128 v[186:189], v140 offset:35840
	ds_read_b128 v[190:193], v140 offset:36864
	ds_read_b128 v[194:197], v140 offset:37888
	ds_read_b128 v[198:201], v140 offset:38912
	ds_read_b128 v[212:215], v140 offset:39936
	global_load_lds_dwordx4 v141, s[4:5]
	v_add_u32_e32 v141, s44, v132
	s_mov_b32 m0, s25
	s_nop 0
	global_load_lds_dwordx4 v141, s[4:5]
	s_waitcnt vmcnt(8)
	s_waitcnt lgkmcnt(0)
	s_setprio 1
	s_barrier
	v_mfma_f32_16x16x32_bf16 v[126:129], v[142:145], v[174:177], v[126:129]
	v_mfma_f32_16x16x32_bf16 v[122:125], v[150:153], v[174:177], v[122:125]
	v_mfma_f32_16x16x32_bf16 v[110:113], v[142:145], v[182:185], v[110:113]
	v_mfma_f32_16x16x32_bf16 v[106:109], v[150:153], v[182:185], v[106:109]
	v_mfma_f32_16x16x32_bf16 v[94:97], v[142:145], v[190:193], v[94:97]
	v_mfma_f32_16x16x32_bf16 v[90:93], v[150:153], v[190:193], v[90:93]
	v_mfma_f32_16x16x32_bf16 v[78:81], v[142:145], v[198:201], v[78:81]
	v_mfma_f32_16x16x32_bf16 v[74:77], v[150:153], v[198:201], v[74:77]
	v_mfma_f32_16x16x32_bf16 v[126:129], v[146:149], v[178:181], v[126:129]
	v_mfma_f32_16x16x32_bf16 v[122:125], v[154:157], v[178:181], v[122:125]
	v_mfma_f32_16x16x32_bf16 v[110:113], v[146:149], v[186:189], v[110:113]
	v_mfma_f32_16x16x32_bf16 v[106:109], v[154:157], v[186:189], v[106:109]
	v_mfma_f32_16x16x32_bf16 v[94:97], v[146:149], v[194:197], v[94:97]
	v_mfma_f32_16x16x32_bf16 v[90:93], v[154:157], v[194:197], v[90:93]
	v_mfma_f32_16x16x32_bf16 v[78:81], v[146:149], v[212:215], v[78:81]
	v_mfma_f32_16x16x32_bf16 v[74:77], v[154:157], v[212:215], v[74:77]
	s_setprio 0
	s_setprio 1
	v_mfma_f32_16x16x32_bf16 v[118:121], v[158:161], v[174:177], v[118:121]
	v_mfma_f32_16x16x32_bf16 v[114:117], v[166:169], v[174:177], v[114:117]
	v_mfma_f32_16x16x32_bf16 v[102:105], v[158:161], v[182:185], v[102:105]
	v_mfma_f32_16x16x32_bf16 v[98:101], v[166:169], v[182:185], v[98:101]
	v_mfma_f32_16x16x32_bf16 v[86:89], v[158:161], v[190:193], v[86:89]
	v_mfma_f32_16x16x32_bf16 v[82:85], v[166:169], v[190:193], v[82:85]
	v_mfma_f32_16x16x32_bf16 v[70:73], v[158:161], v[198:201], v[70:73]
	v_mfma_f32_16x16x32_bf16 v[66:69], v[166:169], v[198:201], v[66:69]
	v_mfma_f32_16x16x32_bf16 v[118:121], v[162:165], v[178:181], v[118:121]
	v_mfma_f32_16x16x32_bf16 v[114:117], v[170:173], v[178:181], v[114:117]
	v_mfma_f32_16x16x32_bf16 v[102:105], v[162:165], v[186:189], v[102:105]
	v_mfma_f32_16x16x32_bf16 v[98:101], v[170:173], v[186:189], v[98:101]
	v_mfma_f32_16x16x32_bf16 v[86:89], v[162:165], v[194:197], v[86:89]
	v_mfma_f32_16x16x32_bf16 v[82:85], v[170:173], v[194:197], v[82:85]
	v_mfma_f32_16x16x32_bf16 v[70:73], v[162:165], v[212:215], v[70:73]
	v_mfma_f32_16x16x32_bf16 v[66:69], v[170:173], v[212:215], v[66:69]
	s_setprio 0
	s_barrier
	s_or_b32 s40, s43, 0x80
	s_mov_b32 m0, s30
	v_add_u32_e32 v141, s40, v131
	ds_read_b128 v[174:177], v140 offset:49152
	ds_read_b128 v[178:181], v140 offset:50176
	ds_read_b128 v[182:185], v140 offset:51200
	ds_read_b128 v[186:189], v140 offset:52224
	ds_read_b128 v[190:193], v140 offset:53248
	ds_read_b128 v[194:197], v140 offset:54272
	ds_read_b128 v[198:201], v140 offset:55296
	ds_read_b128 v[212:215], v140 offset:56320
	global_load_lds_dwordx4 v141, s[6:7]
	v_add_u32_e32 v141, s40, v133
	s_mov_b32 m0, s31
	s_add_i32 s43, s43, 0x80080
	global_load_lds_dwordx4 v141, s[6:7]
	v_add_u32_e32 v141, s43, v131
	s_mov_b32 m0, s37
	s_nop 0
	global_load_lds_dwordx4 v141, s[6:7]
	v_add_u32_e32 v141, s43, v133
	s_mov_b32 m0, s38
	s_nop 0
	global_load_lds_dwordx4 v141, s[6:7]
	v_add_u32_e32 v141, s42, v130
	s_mov_b32 m0, s34
	s_nop 0
	global_load_lds_dwordx4 v141, s[4:5]
	v_add_u32_e32 v141, s42, v132
	s_mov_b32 m0, s35
	s_nop 0
	global_load_lds_dwordx4 v141, s[4:5]
	s_waitcnt vmcnt(8)
	s_waitcnt lgkmcnt(0)
	s_setprio 1
	s_barrier
	v_mfma_f32_16x16x32_bf16 v[62:65], v[142:145], v[174:177], v[62:65]
	v_mfma_f32_16x16x32_bf16 v[58:61], v[150:153], v[174:177], v[58:61]
	v_mfma_f32_16x16x32_bf16 v[46:49], v[142:145], v[182:185], v[46:49]
	v_mfma_f32_16x16x32_bf16 v[42:45], v[150:153], v[182:185], v[42:45]
	v_mfma_f32_16x16x32_bf16 v[30:33], v[142:145], v[190:193], v[30:33]
	v_mfma_f32_16x16x32_bf16 v[26:29], v[150:153], v[190:193], v[26:29]
	v_mfma_f32_16x16x32_bf16 v[14:17], v[142:145], v[198:201], v[14:17]
	v_mfma_f32_16x16x32_bf16 v[10:13], v[150:153], v[198:201], v[10:13]
	v_mfma_f32_16x16x32_bf16 v[62:65], v[146:149], v[178:181], v[62:65]
	v_mfma_f32_16x16x32_bf16 v[58:61], v[154:157], v[178:181], v[58:61]
	v_mfma_f32_16x16x32_bf16 v[46:49], v[146:149], v[186:189], v[46:49]
	v_mfma_f32_16x16x32_bf16 v[42:45], v[154:157], v[186:189], v[42:45]
	v_mfma_f32_16x16x32_bf16 v[30:33], v[146:149], v[194:197], v[30:33]
	v_mfma_f32_16x16x32_bf16 v[26:29], v[154:157], v[194:197], v[26:29]
	v_mfma_f32_16x16x32_bf16 v[14:17], v[146:149], v[212:215], v[14:17]
	v_mfma_f32_16x16x32_bf16 v[10:13], v[154:157], v[212:215], v[10:13]
	s_setprio 0
	s_setprio 1
	v_mfma_f32_16x16x32_bf16 v[54:57], v[158:161], v[174:177], v[54:57]
	v_mfma_f32_16x16x32_bf16 v[50:53], v[166:169], v[174:177], v[50:53]
	v_mfma_f32_16x16x32_bf16 v[38:41], v[158:161], v[182:185], v[38:41]
	v_mfma_f32_16x16x32_bf16 v[34:37], v[166:169], v[182:185], v[34:37]
	v_mfma_f32_16x16x32_bf16 v[22:25], v[158:161], v[190:193], v[22:25]
	v_mfma_f32_16x16x32_bf16 v[18:21], v[166:169], v[190:193], v[18:21]
	v_mfma_f32_16x16x32_bf16 v[6:9], v[158:161], v[198:201], v[6:9]
	v_mfma_f32_16x16x32_bf16 v[2:5], v[166:169], v[198:201], v[2:5]
	v_mfma_f32_16x16x32_bf16 v[54:57], v[162:165], v[178:181], v[54:57]
	v_mfma_f32_16x16x32_bf16 v[50:53], v[170:173], v[178:181], v[50:53]
	v_mfma_f32_16x16x32_bf16 v[38:41], v[162:165], v[186:189], v[38:41]
	v_mfma_f32_16x16x32_bf16 v[34:37], v[170:173], v[186:189], v[34:37]
	v_mfma_f32_16x16x32_bf16 v[22:25], v[162:165], v[194:197], v[22:25]
	v_mfma_f32_16x16x32_bf16 v[18:21], v[170:173], v[194:197], v[18:21]
	v_mfma_f32_16x16x32_bf16 v[6:9], v[162:165], v[212:215], v[6:9]
	v_mfma_f32_16x16x32_bf16 v[2:5], v[170:173], v[212:215], v[2:5]
	s_setprio 0
	s_barrier
	s_add_i32 s39, s39, 2
	s_cmp_gt_u32 s39, 29
	s_mov_b32 s40, s41

.LBB0_151:
	v_lshrrev_b32_e32 v9, 1, v5
	v_and_b32_e32 v135, 24, v9
	v_and_b32_e32 v136, 15, v5
	v_lshlrev_b32_e32 v9, 1, v135
	v_lshlrev_b32_e32 v5, 2, v5
	s_lshl_b32 s20, s20, 5
	s_lshl_b32 s19, s21, 6
	v_lshl_or_b32 v9, v136, 6, v9
	s_lshl_b32 s21, s21, 13
	v_and_b32_e32 v5, 32, v5
	s_and_b32 s20, s20, 0x60
	v_bitop3_b32 v10, v9, s21, v5 bitop3:0xde
	s_lshl_b32 s21, s20, 7
	v_bitop3_b32 v137, v9, s21, v5 bitop3:0xde
	s_add_i32 s21, s28, 0x18000
	s_or_b32 s23, s2, 0x80
	s_add_i32 s22, s21, s27
	v_add_u32_e32 v5, s23, v131
	s_mov_b32 m0, s22
	s_waitcnt vmcnt(2)
	s_barrier
	global_load_lds_dwordx4 v5, s[6:7]
	v_add_u32_e32 v5, s23, v133
	s_add_i32 s23, s22, 0x2000
	s_mov_b32 m0, s23
	s_or_b32 s25, s14, 0x80
	s_add_i32 s24, s15, 0x8000
	global_load_lds_dwordx4 v5, s[6:7]
	v_add_u32_e32 v5, s25, v130
	s_mov_b32 m0, s24
	s_add_i32 s26, s28, 0x1c000
	global_load_lds_dwordx4 v5, s[4:5]
	v_add_u32_e32 v5, s25, v132
	s_add_i32 s25, s15, 0xa000
	s_mov_b32 m0, s25
	s_or_b32 s29, s2, 0x80080
	s_add_i32 s27, s26, s27
	global_load_lds_dwordx4 v5, s[4:5]
	v_add_u32_e32 v5, s29, v131
	s_mov_b32 m0, s27
	s_add_i32 s30, s14, 0x80080
	global_load_lds_dwordx4 v5, s[6:7]
	v_add_u32_e32 v5, s29, v133
	s_add_i32 s29, s27, 0x2000
	s_mov_b32 m0, s29
	v_lshlrev_b32_e32 v7, 12, v7
	global_load_lds_dwordx4 v5, s[6:7]
	v_lshlrev_b32_e32 v5, 15, v6
	v_and_b32_e32 v5, 0xffff0000, v5
	v_and_b32_e32 v6, 1, v6
	v_add3_u32 v5, s30, v5, v7
	v_lshlrev_b32_e32 v6, 6, v6
	v_lshlrev_b32_e32 v7, 1, v8
	v_add3_u32 v138, v5, v6, v7
	v_lshlrev_b32_e32 v5, 15, v2
	v_and_b32_e32 v5, 0xffff0000, v5
	v_lshlrev_b32_e32 v3, 12, v3
	v_and_b32_e32 v2, 1, v2
	s_waitcnt vmcnt(6)
	v_add3_u32 v3, s30, v5, v3
	v_lshlrev_b32_e32 v2, 6, v2
	v_lshlrev_b32_e32 v4, 1, v4
	v_add3_u32 v139, v3, v2, v4
	v_or_b32_e32 v134, s19, v136
	s_mov_b32 s30, -2
	s_mov_b32 s31, 0
	v_add_u32_e32 v140, s28, v10
	s_barrier
	v_add_u32_e32 v141, s3, v137
	ds_read_b128 v[142:145], v141
	ds_read_b128 v[146:149], v141 offset:1024
	ds_read_b128 v[150:153], v141 offset:2048
	ds_read_b128 v[154:157], v141 offset:3072
	v_add_u32_e32 v141, s11, v137
	ds_read_b128 v[158:161], v141
	ds_read_b128 v[162:165], v141 offset:1024
	ds_read_b128 v[166:169], v141 offset:2048
	ds_read_b128 v[170:173], v141 offset:3072
	s_add_i32 s34, s31, 0x100
	s_cmp_lg_u32 s30, 28
	s_cselect_b32 s36, s34, 0
	s_add_i32 s37, s36, s14
	s_or_b32 s35, s37, 0x80
	s_add_i32 s36, s36, s2
	v_add_u32_e32 v141, s31, v139
	s_add_i32 m0, s15, 0xc000
	ds_read_b128 v[174:177], v140
	ds_read_b128 v[178:181], v140 offset:1024
	ds_read_b128 v[182:185], v140 offset:2048
	ds_read_b128 v[186:189], v140 offset:3072
	ds_read_b128 v[190:193], v140 offset:4096
	ds_read_b128 v[194:197], v140 offset:5120
	ds_read_b128 v[198:201], v140 offset:6144
	ds_read_b128 v[212:215], v140 offset:7168
	global_load_lds_dwordx4 v141, s[4:5]
	v_add_u32_e32 v141, s31, v138
	s_add_i32 m0, s15, 0xe000
	s_nop 0
	global_load_lds_dwordx4 v141, s[4:5]
	s_waitcnt vmcnt(8)
	s_waitcnt lgkmcnt(0)
	s_setprio 1
	s_barrier
	v_mfma_f32_16x16x32_bf16 v[126:129], v[142:145], v[174:177], 0
	v_mfma_f32_16x16x32_bf16 v[122:125], v[150:153], v[174:177], 0
	v_mfma_f32_16x16x32_bf16 v[110:113], v[142:145], v[182:185], 0
	v_mfma_f32_16x16x32_bf16 v[106:109], v[150:153], v[182:185], 0
	v_mfma_f32_16x16x32_bf16 v[94:97], v[142:145], v[190:193], 0
	v_mfma_f32_16x16x32_bf16 v[90:93], v[150:153], v[190:193], 0
	v_mfma_f32_16x16x32_bf16 v[78:81], v[142:145], v[198:201], 0
	v_mfma_f32_16x16x32_bf16 v[74:77], v[150:153], v[198:201], 0
	v_mfma_f32_16x16x32_bf16 v[126:129], v[146:149], v[178:181], v[126:129]
	v_mfma_f32_16x16x32_bf16 v[122:125], v[154:157], v[178:181], v[122:125]
	v_mfma_f32_16x16x32_bf16 v[110:113], v[146:149], v[186:189], v[110:113]
	v_mfma_f32_16x16x32_bf16 v[106:109], v[154:157], v[186:189], v[106:109]
	v_mfma_f32_16x16x32_bf16 v[94:97], v[146:149], v[194:197], v[94:97]
	v_mfma_f32_16x16x32_bf16 v[90:93], v[154:157], v[194:197], v[90:93]
	v_mfma_f32_16x16x32_bf16 v[78:81], v[146:149], v[212:215], v[78:81]
	v_mfma_f32_16x16x32_bf16 v[74:77], v[154:157], v[212:215], v[74:77]
	s_setprio 0
	s_setprio 1
	v_mfma_f32_16x16x32_bf16 v[118:121], v[158:161], v[174:177], 0
	v_mfma_f32_16x16x32_bf16 v[114:117], v[166:169], v[174:177], 0
	v_mfma_f32_16x16x32_bf16 v[102:105], v[158:161], v[182:185], 0
	v_mfma_f32_16x16x32_bf16 v[98:101], v[166:169], v[182:185], 0
	v_mfma_f32_16x16x32_bf16 v[86:89], v[158:161], v[190:193], 0
	v_mfma_f32_16x16x32_bf16 v[82:85], v[166:169], v[190:193], 0
	v_mfma_f32_16x16x32_bf16 v[70:73], v[158:161], v[198:201], 0
	v_mfma_f32_16x16x32_bf16 v[66:69], v[166:169], v[198:201], 0
	v_mfma_f32_16x16x32_bf16 v[118:121], v[162:165], v[178:181], v[118:121]
	v_mfma_f32_16x16x32_bf16 v[114:117], v[170:173], v[178:181], v[114:117]
	v_mfma_f32_16x16x32_bf16 v[102:105], v[162:165], v[186:189], v[102:105]
	v_mfma_f32_16x16x32_bf16 v[98:101], v[170:173], v[186:189], v[98:101]
	v_mfma_f32_16x16x32_bf16 v[86:89], v[162:165], v[194:197], v[86:89]
	v_mfma_f32_16x16x32_bf16 v[82:85], v[170:173], v[194:197], v[82:85]
	v_mfma_f32_16x16x32_bf16 v[70:73], v[162:165], v[212:215], v[70:73]
	v_mfma_f32_16x16x32_bf16 v[66:69], v[170:173], v[212:215], v[66:69]
	s_setprio 0
	s_barrier
	s_mov_b32 m0, s9
	v_add_u32_e32 v141, s36, v131
	ds_read_b128 v[174:177], v140 offset:16384
	ds_read_b128 v[178:181], v140 offset:17408
	ds_read_b128 v[182:185], v140 offset:18432
	ds_read_b128 v[186:189], v140 offset:19456
	ds_read_b128 v[190:193], v140 offset:20480
	ds_read_b128 v[194:197], v140 offset:21504
	ds_read_b128 v[198:201], v140 offset:22528
	ds_read_b128 v[212:215], v140 offset:23552
	global_load_lds_dwordx4 v141, s[6:7]
	v_add_u32_e32 v141, s36, v133
	s_mov_b32 m0, s10
	s_add_i32 s31, s36, 0x80000
	global_load_lds_dwordx4 v141, s[6:7]
	v_add_u32_e32 v141, s31, v131
	s_mov_b32 m0, s12
	s_nop 0
	global_load_lds_dwordx4 v141, s[6:7]
	v_add_u32_e32 v141, s31, v133
	s_mov_b32 m0, s13
	s_nop 0
	global_load_lds_dwordx4 v141, s[6:7]
	v_add_u32_e32 v141, s37, v130
	s_mov_b32 m0, s15
	s_nop 0
	global_load_lds_dwordx4 v141, s[4:5]
	v_add_u32_e32 v141, s37, v132
	s_mov_b32 m0, s16
	s_nop 0
	global_load_lds_dwordx4 v141, s[4:5]
	s_waitcnt vmcnt(8)
	s_waitcnt lgkmcnt(0)
	s_setprio 1
	s_barrier
	v_mfma_f32_16x16x32_bf16 v[62:65], v[142:145], v[174:177], 0
	v_mfma_f32_16x16x32_bf16 v[58:61], v[150:153], v[174:177], 0
	v_mfma_f32_16x16x32_bf16 v[46:49], v[142:145], v[182:185], 0
	v_mfma_f32_16x16x32_bf16 v[42:45], v[150:153], v[182:185], 0
	v_mfma_f32_16x16x32_bf16 v[30:33], v[142:145], v[190:193], 0
	v_mfma_f32_16x16x32_bf16 v[26:29], v[150:153], v[190:193], 0
	v_mfma_f32_16x16x32_bf16 v[14:17], v[142:145], v[198:201], 0
	v_mfma_f32_16x16x32_bf16 v[10:13], v[150:153], v[198:201], 0
	v_mfma_f32_16x16x32_bf16 v[62:65], v[146:149], v[178:181], v[62:65]
	v_mfma_f32_16x16x32_bf16 v[58:61], v[154:157], v[178:181], v[58:61]
	v_mfma_f32_16x16x32_bf16 v[46:49], v[146:149], v[186:189], v[46:49]
	v_mfma_f32_16x16x32_bf16 v[42:45], v[154:157], v[186:189], v[42:45]
	v_mfma_f32_16x16x32_bf16 v[30:33], v[146:149], v[194:197], v[30:33]
	v_mfma_f32_16x16x32_bf16 v[26:29], v[154:157], v[194:197], v[26:29]
	v_mfma_f32_16x16x32_bf16 v[14:17], v[146:149], v[212:215], v[14:17]
	v_mfma_f32_16x16x32_bf16 v[10:13], v[154:157], v[212:215], v[10:13]
	s_setprio 0
	s_setprio 1
	v_mfma_f32_16x16x32_bf16 v[54:57], v[158:161], v[174:177], 0
	v_mfma_f32_16x16x32_bf16 v[50:53], v[166:169], v[174:177], 0
	v_mfma_f32_16x16x32_bf16 v[38:41], v[158:161], v[182:185], 0
	v_mfma_f32_16x16x32_bf16 v[34:37], v[166:169], v[182:185], 0
	v_mfma_f32_16x16x32_bf16 v[22:25], v[158:161], v[190:193], 0
	v_mfma_f32_16x16x32_bf16 v[18:21], v[166:169], v[190:193], 0
	v_mfma_f32_16x16x32_bf16 v[6:9], v[158:161], v[198:201], 0
	v_mfma_f32_16x16x32_bf16 v[2:5], v[166:169], v[198:201], 0
	v_mfma_f32_16x16x32_bf16 v[54:57], v[162:165], v[178:181], v[54:57]
	v_mfma_f32_16x16x32_bf16 v[50:53], v[170:173], v[178:181], v[50:53]
	v_mfma_f32_16x16x32_bf16 v[38:41], v[162:165], v[186:189], v[38:41]
	v_mfma_f32_16x16x32_bf16 v[34:37], v[170:173], v[186:189], v[34:37]
	v_mfma_f32_16x16x32_bf16 v[22:25], v[162:165], v[194:197], v[22:25]
	v_mfma_f32_16x16x32_bf16 v[18:21], v[170:173], v[194:197], v[18:21]
	v_mfma_f32_16x16x32_bf16 v[6:9], v[162:165], v[212:215], v[6:9]
	v_mfma_f32_16x16x32_bf16 v[2:5], v[170:173], v[212:215], v[2:5]
	s_setprio 0
	s_barrier
	v_add_u32_e32 v141, s21, v137
	ds_read_b128 v[142:145], v141
	ds_read_b128 v[146:149], v141 offset:1024
	ds_read_b128 v[150:153], v141 offset:2048
	ds_read_b128 v[154:157], v141 offset:3072
	v_add_u32_e32 v141, s26, v137
	ds_read_b128 v[158:161], v141
	ds_read_b128 v[162:165], v141 offset:1024
	ds_read_b128 v[166:169], v141 offset:2048
	ds_read_b128 v[170:173], v141 offset:3072
	s_add_i32 s37, s37, 0x80000
	s_mov_b32 m0, s17
	v_add_u32_e32 v141, s37, v130
	ds_read_b128 v[174:177], v140 offset:32768
	ds_read_b128 v[178:181], v140 offset:33792
	ds_read_b128 v[182:185], v140 offset:34816
	ds_read_b128 v[186:189], v140 offset:35840
	ds_read_b128 v[190:193], v140 offset:36864
	ds_read_b128 v[194:197], v140 offset:37888
	ds_read_b128 v[198:201], v140 offset:38912
	ds_read_b128 v[212:215], v140 offset:39936
	global_load_lds_dwordx4 v141, s[4:5]
	v_add_u32_e32 v141, s37, v132
	s_mov_b32 m0, s18
	s_nop 0
	global_load_lds_dwordx4 v141, s[4:5]
	s_waitcnt vmcnt(8)
	s_waitcnt lgkmcnt(0)
	s_setprio 1
	s_barrier
	v_mfma_f32_16x16x32_bf16 v[126:129], v[142:145], v[174:177], v[126:129]
	v_mfma_f32_16x16x32_bf16 v[122:125], v[150:153], v[174:177], v[122:125]
	v_mfma_f32_16x16x32_bf16 v[110:113], v[142:145], v[182:185], v[110:113]
	v_mfma_f32_16x16x32_bf16 v[106:109], v[150:153], v[182:185], v[106:109]
	v_mfma_f32_16x16x32_bf16 v[94:97], v[142:145], v[190:193], v[94:97]
	v_mfma_f32_16x16x32_bf16 v[90:93], v[150:153], v[190:193], v[90:93]
	v_mfma_f32_16x16x32_bf16 v[78:81], v[142:145], v[198:201], v[78:81]
	v_mfma_f32_16x16x32_bf16 v[74:77], v[150:153], v[198:201], v[74:77]
	v_mfma_f32_16x16x32_bf16 v[126:129], v[146:149], v[178:181], v[126:129]
	v_mfma_f32_16x16x32_bf16 v[122:125], v[154:157], v[178:181], v[122:125]
	v_mfma_f32_16x16x32_bf16 v[110:113], v[146:149], v[186:189], v[110:113]
	v_mfma_f32_16x16x32_bf16 v[106:109], v[154:157], v[186:189], v[106:109]
	v_mfma_f32_16x16x32_bf16 v[94:97], v[146:149], v[194:197], v[94:97]
	v_mfma_f32_16x16x32_bf16 v[90:93], v[154:157], v[194:197], v[90:93]
	v_mfma_f32_16x16x32_bf16 v[78:81], v[146:149], v[212:215], v[78:81]
	v_mfma_f32_16x16x32_bf16 v[74:77], v[154:157], v[212:215], v[74:77]
	s_setprio 0
	s_setprio 1
	v_mfma_f32_16x16x32_bf16 v[118:121], v[158:161], v[174:177], v[118:121]
	v_mfma_f32_16x16x32_bf16 v[114:117], v[166:169], v[174:177], v[114:117]
	v_mfma_f32_16x16x32_bf16 v[102:105], v[158:161], v[182:185], v[102:105]
	v_mfma_f32_16x16x32_bf16 v[98:101], v[166:169], v[182:185], v[98:101]
	v_mfma_f32_16x16x32_bf16 v[86:89], v[158:161], v[190:193], v[86:89]
	v_mfma_f32_16x16x32_bf16 v[82:85], v[166:169], v[190:193], v[82:85]
	v_mfma_f32_16x16x32_bf16 v[70:73], v[158:161], v[198:201], v[70:73]
	v_mfma_f32_16x16x32_bf16 v[66:69], v[166:169], v[198:201], v[66:69]
	v_mfma_f32_16x16x32_bf16 v[118:121], v[162:165], v[178:181], v[118:121]
	v_mfma_f32_16x16x32_bf16 v[114:117], v[170:173], v[178:181], v[114:117]
	v_mfma_f32_16x16x32_bf16 v[102:105], v[162:165], v[186:189], v[102:105]
	v_mfma_f32_16x16x32_bf16 v[98:101], v[170:173], v[186:189], v[98:101]
	v_mfma_f32_16x16x32_bf16 v[86:89], v[162:165], v[194:197], v[86:89]
	v_mfma_f32_16x16x32_bf16 v[82:85], v[170:173], v[194:197], v[82:85]
	v_mfma_f32_16x16x32_bf16 v[70:73], v[162:165], v[212:215], v[70:73]
	v_mfma_f32_16x16x32_bf16 v[66:69], v[170:173], v[212:215], v[66:69]
	s_setprio 0
	s_barrier
	s_or_b32 s31, s36, 0x80
	s_mov_b32 m0, s22
	v_add_u32_e32 v141, s31, v131
	ds_read_b128 v[174:177], v140 offset:49152
	ds_read_b128 v[178:181], v140 offset:50176
	ds_read_b128 v[182:185], v140 offset:51200
	ds_read_b128 v[186:189], v140 offset:52224
	ds_read_b128 v[190:193], v140 offset:53248
	ds_read_b128 v[194:197], v140 offset:54272
	ds_read_b128 v[198:201], v140 offset:55296
	ds_read_b128 v[212:215], v140 offset:56320
	global_load_lds_dwordx4 v141, s[6:7]
	v_add_u32_e32 v141, s31, v133
	s_mov_b32 m0, s23
	s_add_i32 s36, s36, 0x80080
	global_load_lds_dwordx4 v141, s[6:7]
	v_add_u32_e32 v141, s36, v131
	s_mov_b32 m0, s27
	s_nop 0
	global_load_lds_dwordx4 v141, s[6:7]
	v_add_u32_e32 v141, s36, v133
	s_mov_b32 m0, s29
	s_nop 0
	global_load_lds_dwordx4 v141, s[6:7]
	v_add_u32_e32 v141, s35, v130
	s_mov_b32 m0, s24
	s_nop 0
	global_load_lds_dwordx4 v141, s[4:5]
	v_add_u32_e32 v141, s35, v132
	s_mov_b32 m0, s25
	s_nop 0
	global_load_lds_dwordx4 v141, s[4:5]
	s_waitcnt vmcnt(8)
	s_waitcnt lgkmcnt(0)
	s_setprio 1
	s_barrier
	v_mfma_f32_16x16x32_bf16 v[62:65], v[142:145], v[174:177], v[62:65]
	v_mfma_f32_16x16x32_bf16 v[58:61], v[150:153], v[174:177], v[58:61]
	v_mfma_f32_16x16x32_bf16 v[46:49], v[142:145], v[182:185], v[46:49]
	v_mfma_f32_16x16x32_bf16 v[42:45], v[150:153], v[182:185], v[42:45]
	v_mfma_f32_16x16x32_bf16 v[30:33], v[142:145], v[190:193], v[30:33]
	v_mfma_f32_16x16x32_bf16 v[26:29], v[150:153], v[190:193], v[26:29]
	v_mfma_f32_16x16x32_bf16 v[14:17], v[142:145], v[198:201], v[14:17]
	v_mfma_f32_16x16x32_bf16 v[10:13], v[150:153], v[198:201], v[10:13]
	v_mfma_f32_16x16x32_bf16 v[62:65], v[146:149], v[178:181], v[62:65]
	v_mfma_f32_16x16x32_bf16 v[58:61], v[154:157], v[178:181], v[58:61]
	v_mfma_f32_16x16x32_bf16 v[46:49], v[146:149], v[186:189], v[46:49]
	v_mfma_f32_16x16x32_bf16 v[42:45], v[154:157], v[186:189], v[42:45]
	v_mfma_f32_16x16x32_bf16 v[30:33], v[146:149], v[194:197], v[30:33]
	v_mfma_f32_16x16x32_bf16 v[26:29], v[154:157], v[194:197], v[26:29]
	v_mfma_f32_16x16x32_bf16 v[14:17], v[146:149], v[212:215], v[14:17]
	v_mfma_f32_16x16x32_bf16 v[10:13], v[154:157], v[212:215], v[10:13]
	s_setprio 0
	s_setprio 1
	v_mfma_f32_16x16x32_bf16 v[54:57], v[158:161], v[174:177], v[54:57]
	v_mfma_f32_16x16x32_bf16 v[50:53], v[166:169], v[174:177], v[50:53]
	v_mfma_f32_16x16x32_bf16 v[38:41], v[158:161], v[182:185], v[38:41]
	v_mfma_f32_16x16x32_bf16 v[34:37], v[166:169], v[182:185], v[34:37]
	v_mfma_f32_16x16x32_bf16 v[22:25], v[158:161], v[190:193], v[22:25]
	v_mfma_f32_16x16x32_bf16 v[18:21], v[166:169], v[190:193], v[18:21]
	v_mfma_f32_16x16x32_bf16 v[6:9], v[158:161], v[198:201], v[6:9]
	v_mfma_f32_16x16x32_bf16 v[2:5], v[166:169], v[198:201], v[2:5]
	v_mfma_f32_16x16x32_bf16 v[54:57], v[162:165], v[178:181], v[54:57]
	v_mfma_f32_16x16x32_bf16 v[50:53], v[170:173], v[178:181], v[50:53]
	v_mfma_f32_16x16x32_bf16 v[38:41], v[162:165], v[186:189], v[38:41]
	v_mfma_f32_16x16x32_bf16 v[34:37], v[170:173], v[186:189], v[34:37]
	v_mfma_f32_16x16x32_bf16 v[22:25], v[162:165], v[194:197], v[22:25]
	v_mfma_f32_16x16x32_bf16 v[18:21], v[170:173], v[194:197], v[18:21]
	v_mfma_f32_16x16x32_bf16 v[6:9], v[162:165], v[212:215], v[6:9]
	v_mfma_f32_16x16x32_bf16 v[2:5], v[170:173], v[212:215], v[2:5]
	s_setprio 0
	s_barrier
	s_add_i32 s30, s30, 2
	s_cmp_gt_u32 s30, 29
	s_mov_b32 s31, s34

.LBB0_186:
	s_or_b64 exec, exec, s[0:1]
	v_readlane_b32 s0, v253, 2
	v_readlane_b32 s14, v253, 0
	v_readlane_b32 s15, v253, 1
	s_mov_b32 s12, s65
	v_readlane_b32 s1, v253, 3
	v_mov_b32_e32 v3, v0
	s_waitcnt lgkmcnt(0)
	s_barrier
	s_cmpk_gt_i32 s14, 0x5ff
	v_readfirstlane_b32 s10, v3
	s_cbranch_scc1 .LBB0_202
	v_bfe_i32 v4, v3, 27, 1
	v_lshlrev_b32_e32 v6, 4, v3
	v_lshrrev_b32_e32 v4, 22, v4
	v_add_u32_e32 v4, v6, v4
	v_and_b32_e32 v4, 0xfffffc00, v4
	v_sub_u32_e32 v4, v6, v4
	v_ashrrev_i32_e32 v2, 31, v3
	v_lshrrev_b32_e32 v5, 4, v4
	v_lshrrev_b32_e32 v2, 26, v2
	v_bitop3_b32 v5, v5, v4, 32 bitop3:0x6c
	v_ashrrev_i32_e32 v4, 31, v4
	v_add_u32_e32 v2, v3, v2
	v_lshrrev_b32_e32 v4, 26, v4
	v_ashrrev_i32_e32 v2, 6, v2
	v_add_u32_e32 v4, v5, v4
	v_lshlrev_b32_e32 v7, 3, v2
	v_ashrrev_i32_e32 v4, 6, v4
	v_and_b32_e32 v7, -16, v7
	v_mul_i32_i24_e32 v9, 64, v4
	v_add_u32_e32 v7, v4, v7
	v_sub_u32_e32 v5, v5, v9
	v_lshlrev_b32_e32 v8, 5, v2
	v_ashrrev_i16_sdwa v5, v1, sext(v5) dst_sel:DWORD dst_unused:UNUSED_PAD src0_sel:DWORD src1_sel:BYTE_0
	v_lshlrev_b32_e32 v9, 1, v7
	v_lshrrev_b32_e32 v10, 2, v7
	v_and_b32_e32 v11, 3, v4
	s_mov_b32 s6, 0x7fffe0
	v_and_b32_e32 v8, 32, v8
	v_bfe_i32 v5, v5, 0, 16
	v_and_b32_e32 v9, 24, v9
	v_and_b32_e32 v10, 4, v10
	v_and_or_b32 v11, v7, s6, v11
	s_movk_i32 s7, 0x1600
	v_add_u32_e32 v8, v8, v5
	v_or3_b32 v9, v11, v10, v9
	v_mul_lo_u32 v7, v7, s7
	v_add_lshl_u32 v132, v8, v7, 1
	v_mul_u32_u24_e32 v7, 0x1600, v9
	v_add_lshl_u32 v133, v7, v8, 1
	v_add_u32_e32 v7, 0x2000, v6
	v_ashrrev_i32_e32 v6, 31, v7
	v_lshrrev_b32_e32 v6, 22, v6
	v_add_u32_e32 v6, v7, v6
	v_ashrrev_i32_e32 v6, 10, v6
	s_load_dwordx2 s[4:5], s[0:1], 0x98
	v_mul_i32_i24_e32 v8, 0x400, v6
	v_sub_u32_e32 v7, v7, v8
	v_lshrrev_b32_e32 v8, 4, v7
	v_bitop3_b32 v8, v8, v7, 32 bitop3:0x6c
	v_lshlrev_b32_e32 v7, 3, v6
	v_and_b32_e32 v9, -16, v7
	v_ashrrev_i32_e32 v7, 31, v8
	s_waitcnt lgkmcnt(0)
	s_add_u32 s0, s4, 0x18100000
	v_lshrrev_b32_e32 v7, 26, v7
	s_addc_u32 s1, s5, 0
	v_add_u32_e32 v10, v8, v7
	s_add_u32 s2, s4, 0x5900000
	v_ashrrev_i32_e32 v7, 6, v10
	v_and_b32_e32 v10, 0xc0, v10
	s_addc_u32 s3, s5, 0
	v_add_u32_e32 v9, v7, v9
	v_sub_u32_e32 v8, v8, v10
	v_and_b32_e32 v13, 3, v7
	s_ashr_i32 s16, s14, 31
	v_lshlrev_b32_e32 v11, 5, v6
	v_ashrrev_i16_sdwa v8, v1, sext(v8) dst_sel:DWORD dst_unused:UNUSED_PAD src0_sel:DWORD src1_sel:BYTE_0
	v_and_or_b32 v13, v9, s6, v13
	s_lshr_b32 s6, s16, 29
	v_and_b32_e32 v11, 32, v11
	v_bfe_i32 v8, v8, 0, 16
	s_add_i32 s6, s14, s6
	s_ashr_i32 s11, s10, 6
	v_add_u32_e32 v10, v11, v8
	v_lshlrev_b32_e32 v11, 1, v9
	v_lshrrev_b32_e32 v12, 2, v9
	v_mul_lo_u32 v9, v9, s7
	s_ashr_i32 s7, s6, 3
	s_and_b32 s6, s6, -8
	s_ashr_i32 s13, s10, 8
	s_lshl_b32 s35, s11, 10
	s_sub_i32 s6, s14, s6
	s_cmp_lt_i32 s6, 0
	s_movk_i32 s8, 0xc1
	s_cselect_b32 s8, s8, 0xc0
	s_mul_i32 s6, s6, s8
	s_add_i32 s6, s6, s7
	s_ashr_i32 s7, s6, 31
	s_lshr_b32 s7, s7, 28
	s_add_i32 s7, s6, s7
	s_ashr_i32 s8, s7, 4
	s_and_b32 s7, s7, 0xfff0
	s_sub_i32 s6, s6, s7
	s_bfe_u32 s7, s6, 0x10007
	s_add_i32 s7, s6, s7
	s_bfe_i32 s9, s7, 0x80000
	v_and_b32_e32 v11, 24, v11
	v_and_b32_e32 v12, 4, v12
	s_sext_i32_i16 s9, s9
	v_or3_b32 v11, v13, v12, v11
	s_and_b32 s7, s7, 0xfe
	s_ashr_i32 s41, s9, 1
	s_add_i32 s17, s12, 0x10000
	v_add_lshl_u32 v134, v10, v9, 1
	v_mul_u32_u24_e32 v9, 0x1600, v11
	s_sub_i32 s6, s6, s7
	s_mul_i32 s46, s41, 0x2c0000
	s_add_i32 s18, s17, s35
	v_add_lshl_u32 v135, v9, v10, 1
	s_lshl_b32 s8, s8, 1
	s_sext_i32_i8 s6, s6
	v_add_u32_e32 v9, s46, v133
	s_mov_b32 m0, s18
	s_add_i32 s19, s18, 0x2000
	s_add_i32 s20, s12, 0x14000
	s_add_i32 s42, s8, s6
	s_sub_i32 s42, 0xbf, s42
	global_load_lds_dwordx4 v9, s[2:3]
	v_add_u32_e32 v9, s46, v135
	s_mov_b32 m0, s19
	s_add_i32 s6, s46, 0x160000
	s_add_i32 s21, s20, s35
	global_load_lds_dwordx4 v9, s[2:3]
	v_add_u32_e32 v9, s6, v133
	s_mov_b32 m0, s21
	s_add_i32 s22, s21, 0x2000
	global_load_lds_dwordx4 v9, s[2:3]
	v_add_u32_e32 v9, s6, v135
	s_mov_b32 m0, s22
	s_mul_i32 s45, s42, 0x2c0000
	s_add_i32 s23, s12, s35
	global_load_lds_dwordx4 v9, s[2:3]
	v_add_u32_e32 v9, s45, v132
	s_mov_b32 m0, s23
	s_add_i32 s24, s23, 0x2000
	global_load_lds_dwordx4 v9, s[0:1]
	v_add_u32_e32 v9, s45, v134
	s_mov_b32 m0, s24
	s_add_i32 s6, s45, 0x160000
	s_add_i32 s25, s23, 0x4000
	global_load_lds_dwordx4 v9, s[0:1]
	v_add_u32_e32 v9, s6, v132
	s_mov_b32 m0, s25
	s_add_i32 s26, s23, 0x6000
	global_load_lds_dwordx4 v9, s[0:1]
	v_add_u32_e32 v9, s6, v134
	s_mov_b32 m0, s26
	s_cmp_eq_u32 s13, 1
	global_load_lds_dwordx4 v9, s[0:1]
	s_cselect_b64 s[6:7], -1, 0
	s_cmp_lg_u32 s13, 1
	s_cbranch_scc1 .LBB0_189
	s_barrier

.LBB0_192:
	s_add_i32 s38, s38, 1
	s_mul_i32 s4, s38, s37
	s_mul_hi_u32 s5, s38, s15
	s_add_i32 s5, s5, s4
	s_mul_i32 s4, s38, s15
	s_add_u32 s12, s4, s14
	s_addc_u32 s13, s5, s16
	v_cmp_gt_i64_e32 vcc, s[12:13], v[208:209]
	v_cmp_lt_i64_e64 s[4:5], s[12:13], v[210:211]
	s_cbranch_vccnz .LBB0_194
	s_ashr_i32 s13, s12, 31
	s_lshr_b32 s13, s13, 29
	s_add_i32 s13, s12, s13
	s_ashr_i32 s39, s13, 3
	s_and_b32 s13, s13, -8
	s_sub_i32 s12, s12, s13
	s_cmp_lt_i32 s12, 0
	s_movk_i32 s13, 0xc1
	s_cselect_b32 s13, s13, 0xc0
	s_mul_i32 s12, s12, s13
	s_add_i32 s12, s12, s39
	s_ashr_i32 s13, s12, 31
	s_lshr_b32 s13, s13, 28
	s_add_i32 s13, s12, s13
	s_ashr_i32 s39, s13, 4
	s_lshl_b32 s40, s39, 1
	s_sub_i32 s39, 0xc0, s40
	s_min_i32 s43, s39, 2
	s_abs_i32 s39, s43
	v_cvt_f32_u32_e32 v2, s39
	s_sub_i32 s47, 0, s39
	s_and_b32 s13, s13, -16
	s_sub_i32 s12, s12, s13
	v_rcp_iflag_f32_e32 v2, v2
	s_abs_i32 s13, s12
	s_xor_b32 s44, s12, s43
	s_ashr_i32 s44, s44, 31
	v_mul_f32_e32 v2, 0x4f7ffffe, v2
	v_cvt_u32_f32_e32 v2, v2
	s_nop 0
	v_readfirstlane_b32 s48, v2
	s_mul_i32 s47, s47, s48
	s_mul_hi_u32 s47, s48, s47
	s_add_i32 s48, s48, s47
	s_mul_hi_u32 s47, s13, s48
	s_mul_i32 s48, s47, s39
	s_sub_i32 s13, s13, s48
	s_add_i32 s49, s47, 1
	s_sub_i32 s48, s13, s39
	s_cmp_ge_u32 s13, s39
	s_cselect_b32 s47, s49, s47
	s_cselect_b32 s13, s48, s13
	s_add_i32 s48, s47, 1
	s_cmp_ge_u32 s13, s39
	s_cselect_b32 s13, s48, s47
	s_xor_b32 s13, s13, s44
	s_sub_i32 s39, s13, s44
	s_mul_i32 s13, s39, s43
	s_sub_i32 s12, s12, s13
	s_add_i32 s40, s40, s12
	s_sub_i32 s40, 0xbf, s40
.LBB0_194:
	s_mul_i32 s12, s40, 0x2c0000
	s_and_b64 s[48:49], s[4:5], exec
	s_mul_i32 s13, s39, 0x2c0000
	s_cselect_b32 s43, s12, s45
	s_cselect_b32 s44, s13, s46
	s_add_i32 s45, s45, 0x160080
	s_addk_i32 s46, 0x100
	s_mov_b32 s47, -2
	v_add_u32_e32 v130, s17, v137
	ds_read_b128 v[142:145], v130
	ds_read_b128 v[146:149], v130 offset:1024
	ds_read_b128 v[150:153], v130 offset:2048
	ds_read_b128 v[154:157], v130 offset:3072
	v_add_u32_e32 v130, s20, v137
	ds_read_b128 v[158:161], v130
	ds_read_b128 v[162:165], v130 offset:1024
	ds_read_b128 v[166:169], v130 offset:2048
	ds_read_b128 v[170:173], v130 offset:3072
	s_add_i32 s48, s45, 0xffea0080
	s_cmpk_eq_i32 s47, 0x54
	s_cselect_b32 s50, s43, s48
	s_cselect_b32 s49, s44, s46
	s_or_b32 s48, s50, 0x80
	v_add_u32_e32 v130, s45, v140
	s_add_i32 m0, s23, 0xc000
	ds_read_b128 v[174:177], v141
	ds_read_b128 v[178:181], v141 offset:1024
	ds_read_b128 v[182:185], v141 offset:2048
	ds_read_b128 v[186:189], v141 offset:3072
	ds_read_b128 v[190:193], v141 offset:4096
	ds_read_b128 v[194:197], v141 offset:5120
	ds_read_b128 v[198:201], v141 offset:6144
	ds_read_b128 v[212:215], v141 offset:7168
	global_load_lds_dwordx4 v130, s[0:1]
	v_add_u32_e32 v130, s45, v139
	s_add_i32 m0, s23, 0xe000
	s_nop 0
	global_load_lds_dwordx4 v130, s[0:1]
	s_waitcnt vmcnt(8)
	s_waitcnt lgkmcnt(0)
	s_setprio 1
	s_barrier
	v_mfma_f32_16x16x32_bf16 v[126:129], v[142:145], v[174:177], 0
	v_mfma_f32_16x16x32_bf16 v[122:125], v[150:153], v[174:177], 0
	v_mfma_f32_16x16x32_bf16 v[118:121], v[142:145], v[182:185], 0
	v_mfma_f32_16x16x32_bf16 v[110:113], v[150:153], v[182:185], 0
	v_mfma_f32_16x16x32_bf16 v[102:105], v[142:145], v[190:193], 0
	v_mfma_f32_16x16x32_bf16 v[94:97], v[150:153], v[190:193], 0
	v_mfma_f32_16x16x32_bf16 v[86:89], v[142:145], v[198:201], 0
	v_mfma_f32_16x16x32_bf16 v[78:81], v[150:153], v[198:201], 0
	v_mfma_f32_16x16x32_bf16 v[126:129], v[146:149], v[178:181], v[126:129]
	v_mfma_f32_16x16x32_bf16 v[122:125], v[154:157], v[178:181], v[122:125]
	v_mfma_f32_16x16x32_bf16 v[118:121], v[146:149], v[186:189], v[118:121]
	v_mfma_f32_16x16x32_bf16 v[110:113], v[154:157], v[186:189], v[110:113]
	v_mfma_f32_16x16x32_bf16 v[102:105], v[146:149], v[194:197], v[102:105]
	v_mfma_f32_16x16x32_bf16 v[94:97], v[154:157], v[194:197], v[94:97]
	v_mfma_f32_16x16x32_bf16 v[86:89], v[146:149], v[212:215], v[86:89]
	v_mfma_f32_16x16x32_bf16 v[78:81], v[154:157], v[212:215], v[78:81]
	s_setprio 0
	s_setprio 1
	v_mfma_f32_16x16x32_bf16 v[114:117], v[158:161], v[174:177], 0
	v_mfma_f32_16x16x32_bf16 v[106:109], v[166:169], v[174:177], 0
	v_mfma_f32_16x16x32_bf16 v[98:101], v[158:161], v[182:185], 0
	v_mfma_f32_16x16x32_bf16 v[90:93], v[166:169], v[182:185], 0
	v_mfma_f32_16x16x32_bf16 v[82:85], v[158:161], v[190:193], 0
	v_mfma_f32_16x16x32_bf16 v[74:77], v[166:169], v[190:193], 0
	v_mfma_f32_16x16x32_bf16 v[70:73], v[158:161], v[198:201], 0
	v_mfma_f32_16x16x32_bf16 v[66:69], v[166:169], v[198:201], 0
	v_mfma_f32_16x16x32_bf16 v[114:117], v[162:165], v[178:181], v[114:117]
	v_mfma_f32_16x16x32_bf16 v[106:109], v[170:173], v[178:181], v[106:109]
	v_mfma_f32_16x16x32_bf16 v[98:101], v[162:165], v[186:189], v[98:101]
	v_mfma_f32_16x16x32_bf16 v[90:93], v[170:173], v[186:189], v[90:93]
	v_mfma_f32_16x16x32_bf16 v[82:85], v[162:165], v[194:197], v[82:85]
	v_mfma_f32_16x16x32_bf16 v[74:77], v[170:173], v[194:197], v[74:77]
	v_mfma_f32_16x16x32_bf16 v[70:73], v[162:165], v[212:215], v[70:73]
	v_mfma_f32_16x16x32_bf16 v[66:69], v[170:173], v[212:215], v[66:69]
	s_setprio 0
	s_barrier
	s_mov_b32 m0, s18
	v_add_u32_e32 v130, s49, v133
	ds_read_b128 v[174:177], v141 offset:16384
	ds_read_b128 v[178:181], v141 offset:17408
	ds_read_b128 v[182:185], v141 offset:18432
	ds_read_b128 v[186:189], v141 offset:19456
	ds_read_b128 v[190:193], v141 offset:20480
	ds_read_b128 v[194:197], v141 offset:21504
	ds_read_b128 v[198:201], v141 offset:22528
	ds_read_b128 v[212:215], v141 offset:23552
	global_load_lds_dwordx4 v130, s[2:3]
	v_add_u32_e32 v130, s49, v135
	s_mov_b32 m0, s19
	s_add_i32 s51, s49, 0x160000
	global_load_lds_dwordx4 v130, s[2:3]
	v_add_u32_e32 v130, s51, v133
	s_mov_b32 m0, s21
	s_nop 0
	global_load_lds_dwordx4 v130, s[2:3]
	v_add_u32_e32 v130, s51, v135
	s_mov_b32 m0, s22
	s_nop 0
	global_load_lds_dwordx4 v130, s[2:3]
	v_add_u32_e32 v130, s50, v132
	s_mov_b32 m0, s23
	s_nop 0
	global_load_lds_dwordx4 v130, s[0:1]
	v_add_u32_e32 v130, s50, v134
	s_mov_b32 m0, s24
	s_nop 0
	global_load_lds_dwordx4 v130, s[0:1]
	s_waitcnt vmcnt(8)
	s_waitcnt lgkmcnt(0)
	s_setprio 1
	s_barrier
	v_mfma_f32_16x16x32_bf16 v[62:65], v[142:145], v[174:177], 0
	v_mfma_f32_16x16x32_bf16 v[58:61], v[150:153], v[174:177], 0
	v_mfma_f32_16x16x32_bf16 v[54:57], v[142:145], v[182:185], 0
	v_mfma_f32_16x16x32_bf16 v[46:49], v[150:153], v[182:185], 0
	v_mfma_f32_16x16x32_bf16 v[38:41], v[142:145], v[190:193], 0
	v_mfma_f32_16x16x32_bf16 v[30:33], v[150:153], v[190:193], 0
	v_mfma_f32_16x16x32_bf16 v[22:25], v[142:145], v[198:201], 0
	v_mfma_f32_16x16x32_bf16 v[14:17], v[150:153], v[198:201], 0
	v_mfma_f32_16x16x32_bf16 v[62:65], v[146:149], v[178:181], v[62:65]
	v_mfma_f32_16x16x32_bf16 v[58:61], v[154:157], v[178:181], v[58:61]
	v_mfma_f32_16x16x32_bf16 v[54:57], v[146:149], v[186:189], v[54:57]
	v_mfma_f32_16x16x32_bf16 v[46:49], v[154:157], v[186:189], v[46:49]
	v_mfma_f32_16x16x32_bf16 v[38:41], v[146:149], v[194:197], v[38:41]
	v_mfma_f32_16x16x32_bf16 v[30:33], v[154:157], v[194:197], v[30:33]
	v_mfma_f32_16x16x32_bf16 v[22:25], v[146:149], v[212:215], v[22:25]
	v_mfma_f32_16x16x32_bf16 v[14:17], v[154:157], v[212:215], v[14:17]
	s_setprio 0
	s_setprio 1
	v_mfma_f32_16x16x32_bf16 v[50:53], v[158:161], v[174:177], 0
	v_mfma_f32_16x16x32_bf16 v[42:45], v[166:169], v[174:177], 0
	v_mfma_f32_16x16x32_bf16 v[34:37], v[158:161], v[182:185], 0
	v_mfma_f32_16x16x32_bf16 v[26:29], v[166:169], v[182:185], 0
	v_mfma_f32_16x16x32_bf16 v[18:21], v[158:161], v[190:193], 0
	v_mfma_f32_16x16x32_bf16 v[10:13], v[166:169], v[190:193], 0
	v_mfma_f32_16x16x32_bf16 v[6:9], v[158:161], v[198:201], 0
	v_mfma_f32_16x16x32_bf16 v[2:5], v[166:169], v[198:201], 0
	v_mfma_f32_16x16x32_bf16 v[50:53], v[162:165], v[178:181], v[50:53]
	v_mfma_f32_16x16x32_bf16 v[42:45], v[170:173], v[178:181], v[42:45]
	v_mfma_f32_16x16x32_bf16 v[34:37], v[162:165], v[186:189], v[34:37]
	v_mfma_f32_16x16x32_bf16 v[26:29], v[170:173], v[186:189], v[26:29]
	v_mfma_f32_16x16x32_bf16 v[18:21], v[162:165], v[194:197], v[18:21]
	v_mfma_f32_16x16x32_bf16 v[10:13], v[170:173], v[194:197], v[10:13]
	v_mfma_f32_16x16x32_bf16 v[6:9], v[162:165], v[212:215], v[6:9]
	v_mfma_f32_16x16x32_bf16 v[2:5], v[170:173], v[212:215], v[2:5]
	s_setprio 0
	s_barrier
	v_add_u32_e32 v130, s27, v137
	ds_read_b128 v[142:145], v130
	ds_read_b128 v[146:149], v130 offset:1024
	ds_read_b128 v[150:153], v130 offset:2048
	ds_read_b128 v[154:157], v130 offset:3072
	v_add_u32_e32 v130, s34, v137
	ds_read_b128 v[158:161], v130
	ds_read_b128 v[162:165], v130 offset:1024
	ds_read_b128 v[166:169], v130 offset:2048
	ds_read_b128 v[170:173], v130 offset:3072
	s_add_i32 s50, s50, 0x160000
	s_mov_b32 m0, s25
	v_add_u32_e32 v130, s50, v132
	ds_read_b128 v[174:177], v141 offset:32768
	ds_read_b128 v[178:181], v141 offset:33792
	ds_read_b128 v[182:185], v141 offset:34816
	ds_read_b128 v[186:189], v141 offset:35840
	ds_read_b128 v[190:193], v141 offset:36864
	ds_read_b128 v[194:197], v141 offset:37888
	ds_read_b128 v[198:201], v141 offset:38912
	ds_read_b128 v[212:215], v141 offset:39936
	global_load_lds_dwordx4 v130, s[0:1]
	v_add_u32_e32 v130, s50, v134
	s_mov_b32 m0, s26
	s_nop 0
	global_load_lds_dwordx4 v130, s[0:1]
	s_waitcnt vmcnt(8)
	s_waitcnt lgkmcnt(0)
	s_setprio 1
	s_barrier
	v_mfma_f32_16x16x32_bf16 v[126:129], v[142:145], v[174:177], v[126:129]
	v_mfma_f32_16x16x32_bf16 v[122:125], v[150:153], v[174:177], v[122:125]
	v_mfma_f32_16x16x32_bf16 v[118:121], v[142:145], v[182:185], v[118:121]
	v_mfma_f32_16x16x32_bf16 v[110:113], v[150:153], v[182:185], v[110:113]
	v_mfma_f32_16x16x32_bf16 v[102:105], v[142:145], v[190:193], v[102:105]
	v_mfma_f32_16x16x32_bf16 v[94:97], v[150:153], v[190:193], v[94:97]
	v_mfma_f32_16x16x32_bf16 v[86:89], v[142:145], v[198:201], v[86:89]
	v_mfma_f32_16x16x32_bf16 v[78:81], v[150:153], v[198:201], v[78:81]
	v_mfma_f32_16x16x32_bf16 v[126:129], v[146:149], v[178:181], v[126:129]
	v_mfma_f32_16x16x32_bf16 v[122:125], v[154:157], v[178:181], v[122:125]
	v_mfma_f32_16x16x32_bf16 v[118:121], v[146:149], v[186:189], v[118:121]
	v_mfma_f32_16x16x32_bf16 v[110:113], v[154:157], v[186:189], v[110:113]
	v_mfma_f32_16x16x32_bf16 v[102:105], v[146:149], v[194:197], v[102:105]
	v_mfma_f32_16x16x32_bf16 v[94:97], v[154:157], v[194:197], v[94:97]
	v_mfma_f32_16x16x32_bf16 v[86:89], v[146:149], v[212:215], v[86:89]
	v_mfma_f32_16x16x32_bf16 v[78:81], v[154:157], v[212:215], v[78:81]
	s_setprio 0
	s_setprio 1
	v_mfma_f32_16x16x32_bf16 v[114:117], v[158:161], v[174:177], v[114:117]
	v_mfma_f32_16x16x32_bf16 v[106:109], v[166:169], v[174:177], v[106:109]
	v_mfma_f32_16x16x32_bf16 v[98:101], v[158:161], v[182:185], v[98:101]
	v_mfma_f32_16x16x32_bf16 v[90:93], v[166:169], v[182:185], v[90:93]
	v_mfma_f32_16x16x32_bf16 v[82:85], v[158:161], v[190:193], v[82:85]
	v_mfma_f32_16x16x32_bf16 v[74:77], v[166:169], v[190:193], v[74:77]
	v_mfma_f32_16x16x32_bf16 v[70:73], v[158:161], v[198:201], v[70:73]
	v_mfma_f32_16x16x32_bf16 v[66:69], v[166:169], v[198:201], v[66:69]
	v_mfma_f32_16x16x32_bf16 v[114:117], v[162:165], v[178:181], v[114:117]
	v_mfma_f32_16x16x32_bf16 v[106:109], v[170:173], v[178:181], v[106:109]
	v_mfma_f32_16x16x32_bf16 v[98:101], v[162:165], v[186:189], v[98:101]
	v_mfma_f32_16x16x32_bf16 v[90:93], v[170:173], v[186:189], v[90:93]
	v_mfma_f32_16x16x32_bf16 v[82:85], v[162:165], v[194:197], v[82:85]
	v_mfma_f32_16x16x32_bf16 v[74:77], v[170:173], v[194:197], v[74:77]
	v_mfma_f32_16x16x32_bf16 v[70:73], v[162:165], v[212:215], v[70:73]
	v_mfma_f32_16x16x32_bf16 v[66:69], v[170:173], v[212:215], v[66:69]
	s_setprio 0
	s_barrier
	s_or_b32 s50, s49, 0x80
	s_mov_b32 m0, s28
	v_add_u32_e32 v130, s50, v133
	ds_read_b128 v[174:177], v141 offset:49152
	ds_read_b128 v[178:181], v141 offset:50176
	ds_read_b128 v[182:185], v141 offset:51200
	ds_read_b128 v[186:189], v141 offset:52224
	ds_read_b128 v[190:193], v141 offset:53248
	ds_read_b128 v[194:197], v141 offset:54272
	ds_read_b128 v[198:201], v141 offset:55296
	ds_read_b128 v[212:215], v141 offset:56320
	global_load_lds_dwordx4 v130, s[2:3]
	v_add_u32_e32 v130, s50, v135
	s_mov_b32 m0, s29
	s_add_i32 s49, s49, 0x160080
	global_load_lds_dwordx4 v130, s[2:3]
	v_add_u32_e32 v130, s49, v133
	s_mov_b32 m0, s35
	s_nop 0
	global_load_lds_dwordx4 v130, s[2:3]
	v_add_u32_e32 v130, s49, v135
	s_mov_b32 m0, s36
	s_nop 0
	global_load_lds_dwordx4 v130, s[2:3]
	v_add_u32_e32 v130, s48, v132
	s_mov_b32 m0, s30
	s_nop 0
	global_load_lds_dwordx4 v130, s[0:1]
	v_add_u32_e32 v130, s48, v134
	s_mov_b32 m0, s31
	s_nop 0
	global_load_lds_dwordx4 v130, s[0:1]
	s_waitcnt vmcnt(8)
	s_waitcnt lgkmcnt(0)
	s_setprio 1
	s_barrier
	v_mfma_f32_16x16x32_bf16 v[62:65], v[142:145], v[174:177], v[62:65]
	v_mfma_f32_16x16x32_bf16 v[58:61], v[150:153], v[174:177], v[58:61]
	v_mfma_f32_16x16x32_bf16 v[54:57], v[142:145], v[182:185], v[54:57]
	v_mfma_f32_16x16x32_bf16 v[46:49], v[150:153], v[182:185], v[46:49]
	v_mfma_f32_16x16x32_bf16 v[38:41], v[142:145], v[190:193], v[38:41]
	v_mfma_f32_16x16x32_bf16 v[30:33], v[150:153], v[190:193], v[30:33]
	v_mfma_f32_16x16x32_bf16 v[22:25], v[142:145], v[198:201], v[22:25]
	v_mfma_f32_16x16x32_bf16 v[14:17], v[150:153], v[198:201], v[14:17]
	v_mfma_f32_16x16x32_bf16 v[62:65], v[146:149], v[178:181], v[62:65]
	v_mfma_f32_16x16x32_bf16 v[58:61], v[154:157], v[178:181], v[58:61]
	v_mfma_f32_16x16x32_bf16 v[54:57], v[146:149], v[186:189], v[54:57]
	v_mfma_f32_16x16x32_bf16 v[46:49], v[154:157], v[186:189], v[46:49]
	v_mfma_f32_16x16x32_bf16 v[38:41], v[146:149], v[194:197], v[38:41]
	v_mfma_f32_16x16x32_bf16 v[30:33], v[154:157], v[194:197], v[30:33]
	v_mfma_f32_16x16x32_bf16 v[22:25], v[146:149], v[212:215], v[22:25]
	v_mfma_f32_16x16x32_bf16 v[14:17], v[154:157], v[212:215], v[14:17]
	s_setprio 0
	s_setprio 1
	v_mfma_f32_16x16x32_bf16 v[50:53], v[158:161], v[174:177], v[50:53]
	v_mfma_f32_16x16x32_bf16 v[42:45], v[166:169], v[174:177], v[42:45]
	v_mfma_f32_16x16x32_bf16 v[34:37], v[158:161], v[182:185], v[34:37]
	v_mfma_f32_16x16x32_bf16 v[26:29], v[166:169], v[182:185], v[26:29]
	v_mfma_f32_16x16x32_bf16 v[18:21], v[158:161], v[190:193], v[18:21]
	v_mfma_f32_16x16x32_bf16 v[10:13], v[166:169], v[190:193], v[10:13]
	v_mfma_f32_16x16x32_bf16 v[6:9], v[158:161], v[198:201], v[6:9]
	v_mfma_f32_16x16x32_bf16 v[2:5], v[166:169], v[198:201], v[2:5]
	v_mfma_f32_16x16x32_bf16 v[50:53], v[162:165], v[178:181], v[50:53]
	v_mfma_f32_16x16x32_bf16 v[42:45], v[170:173], v[178:181], v[42:45]
	v_mfma_f32_16x16x32_bf16 v[34:37], v[162:165], v[186:189], v[34:37]
	v_mfma_f32_16x16x32_bf16 v[26:29], v[170:173], v[186:189], v[26:29]
	v_mfma_f32_16x16x32_bf16 v[18:21], v[162:165], v[194:197], v[18:21]
	v_mfma_f32_16x16x32_bf16 v[10:13], v[170:173], v[194:197], v[10:13]
	v_mfma_f32_16x16x32_bf16 v[6:9], v[162:165], v[212:215], v[6:9]
	v_mfma_f32_16x16x32_bf16 v[2:5], v[170:173], v[212:215], v[2:5]
	s_setprio 0
	s_barrier
	s_add_i32 s47, s47, 2
	s_addk_i32 s45, 0x100
	s_addk_i32 s46, 0x100
	s_cmpk_gt_u32 s47, 0x55
.LBB0_195:
	v_add_u32_e32 v130, s17, v137
	ds_read_b128 v[142:145], v130
	ds_read_b128 v[146:149], v130 offset:1024
	ds_read_b128 v[150:153], v130 offset:2048
	ds_read_b128 v[154:157], v130 offset:3072
	v_add_u32_e32 v130, s20, v137
	ds_read_b128 v[158:161], v130
	ds_read_b128 v[162:165], v130 offset:1024
	ds_read_b128 v[166:169], v130 offset:2048
	ds_read_b128 v[170:173], v130 offset:3072
	s_add_i32 s48, s45, 0xffea0080
	s_cmpk_eq_i32 s47, 0x54
	s_cselect_b32 s50, s43, s48
	s_cselect_b32 s49, s44, s46
	s_or_b32 s48, s50, 0x80
	v_add_u32_e32 v130, s45, v140
	s_add_i32 m0, s23, 0xc000
	ds_read_b128 v[174:177], v141
	ds_read_b128 v[178:181], v141 offset:1024
	ds_read_b128 v[182:185], v141 offset:2048
	ds_read_b128 v[186:189], v141 offset:3072
	ds_read_b128 v[190:193], v141 offset:4096
	ds_read_b128 v[194:197], v141 offset:5120
	ds_read_b128 v[198:201], v141 offset:6144
	ds_read_b128 v[212:215], v141 offset:7168
	global_load_lds_dwordx4 v130, s[0:1]
	v_add_u32_e32 v130, s45, v139
	s_add_i32 m0, s23, 0xe000
	s_nop 0
	global_load_lds_dwordx4 v130, s[0:1]
	s_waitcnt vmcnt(8)
	s_waitcnt lgkmcnt(0)
	s_setprio 1
	s_barrier
	v_mfma_f32_16x16x32_bf16 v[126:129], v[142:145], v[174:177], v[126:129]
	v_mfma_f32_16x16x32_bf16 v[122:125], v[150:153], v[174:177], v[122:125]
	v_mfma_f32_16x16x32_bf16 v[118:121], v[142:145], v[182:185], v[118:121]
	v_mfma_f32_16x16x32_bf16 v[110:113], v[150:153], v[182:185], v[110:113]
	v_mfma_f32_16x16x32_bf16 v[102:105], v[142:145], v[190:193], v[102:105]
	v_mfma_f32_16x16x32_bf16 v[94:97], v[150:153], v[190:193], v[94:97]
	v_mfma_f32_16x16x32_bf16 v[86:89], v[142:145], v[198:201], v[86:89]
	v_mfma_f32_16x16x32_bf16 v[78:81], v[150:153], v[198:201], v[78:81]
	v_mfma_f32_16x16x32_bf16 v[126:129], v[146:149], v[178:181], v[126:129]
	v_mfma_f32_16x16x32_bf16 v[122:125], v[154:157], v[178:181], v[122:125]
	v_mfma_f32_16x16x32_bf16 v[118:121], v[146:149], v[186:189], v[118:121]
	v_mfma_f32_16x16x32_bf16 v[110:113], v[154:157], v[186:189], v[110:113]
	v_mfma_f32_16x16x32_bf16 v[102:105], v[146:149], v[194:197], v[102:105]
	v_mfma_f32_16x16x32_bf16 v[94:97], v[154:157], v[194:197], v[94:97]
	v_mfma_f32_16x16x32_bf16 v[86:89], v[146:149], v[212:215], v[86:89]
	v_mfma_f32_16x16x32_bf16 v[78:81], v[154:157], v[212:215], v[78:81]
	s_setprio 0
	s_setprio 1
	v_mfma_f32_16x16x32_bf16 v[114:117], v[158:161], v[174:177], v[114:117]
	v_mfma_f32_16x16x32_bf16 v[106:109], v[166:169], v[174:177], v[106:109]
	v_mfma_f32_16x16x32_bf16 v[98:101], v[158:161], v[182:185], v[98:101]
	v_mfma_f32_16x16x32_bf16 v[90:93], v[166:169], v[182:185], v[90:93]
	v_mfma_f32_16x16x32_bf16 v[82:85], v[158:161], v[190:193], v[82:85]
	v_mfma_f32_16x16x32_bf16 v[74:77], v[166:169], v[190:193], v[74:77]
	v_mfma_f32_16x16x32_bf16 v[70:73], v[158:161], v[198:201], v[70:73]
	v_mfma_f32_16x16x32_bf16 v[66:69], v[166:169], v[198:201], v[66:69]
	v_mfma_f32_16x16x32_bf16 v[114:117], v[162:165], v[178:181], v[114:117]
	v_mfma_f32_16x16x32_bf16 v[106:109], v[170:173], v[178:181], v[106:109]
	v_mfma_f32_16x16x32_bf16 v[98:101], v[162:165], v[186:189], v[98:101]
	v_mfma_f32_16x16x32_bf16 v[90:93], v[170:173], v[186:189], v[90:93]
	v_mfma_f32_16x16x32_bf16 v[82:85], v[162:165], v[194:197], v[82:85]
	v_mfma_f32_16x16x32_bf16 v[74:77], v[170:173], v[194:197], v[74:77]
	v_mfma_f32_16x16x32_bf16 v[70:73], v[162:165], v[212:215], v[70:73]
	v_mfma_f32_16x16x32_bf16 v[66:69], v[170:173], v[212:215], v[66:69]
	s_setprio 0
	s_barrier
	s_mov_b32 m0, s18
	v_add_u32_e32 v130, s49, v133
	ds_read_b128 v[174:177], v141 offset:16384
	ds_read_b128 v[178:181], v141 offset:17408
	ds_read_b128 v[182:185], v141 offset:18432
	ds_read_b128 v[186:189], v141 offset:19456
	ds_read_b128 v[190:193], v141 offset:20480
	ds_read_b128 v[194:197], v141 offset:21504
	ds_read_b128 v[198:201], v141 offset:22528
	ds_read_b128 v[212:215], v141 offset:23552
	global_load_lds_dwordx4 v130, s[2:3]
	v_add_u32_e32 v130, s49, v135
	s_mov_b32 m0, s19
	s_add_i32 s51, s49, 0x160000
	global_load_lds_dwordx4 v130, s[2:3]
	v_add_u32_e32 v130, s51, v133
	s_mov_b32 m0, s21
	s_nop 0
	global_load_lds_dwordx4 v130, s[2:3]
	v_add_u32_e32 v130, s51, v135
	s_mov_b32 m0, s22
	s_nop 0
	global_load_lds_dwordx4 v130, s[2:3]
	v_add_u32_e32 v130, s50, v132
	s_mov_b32 m0, s23
	s_nop 0
	global_load_lds_dwordx4 v130, s[0:1]
	v_add_u32_e32 v130, s50, v134
	s_mov_b32 m0, s24
	s_nop 0
	global_load_lds_dwordx4 v130, s[0:1]
	s_waitcnt vmcnt(8)
	s_waitcnt lgkmcnt(0)
	s_setprio 1
	s_barrier
	v_mfma_f32_16x16x32_bf16 v[62:65], v[142:145], v[174:177], v[62:65]
	v_mfma_f32_16x16x32_bf16 v[58:61], v[150:153], v[174:177], v[58:61]
	v_mfma_f32_16x16x32_bf16 v[54:57], v[142:145], v[182:185], v[54:57]
	v_mfma_f32_16x16x32_bf16 v[46:49], v[150:153], v[182:185], v[46:49]
	v_mfma_f32_16x16x32_bf16 v[38:41], v[142:145], v[190:193], v[38:41]
	v_mfma_f32_16x16x32_bf16 v[30:33], v[150:153], v[190:193], v[30:33]
	v_mfma_f32_16x16x32_bf16 v[22:25], v[142:145], v[198:201], v[22:25]
	v_mfma_f32_16x16x32_bf16 v[14:17], v[150:153], v[198:201], v[14:17]
	v_mfma_f32_16x16x32_bf16 v[62:65], v[146:149], v[178:181], v[62:65]
	v_mfma_f32_16x16x32_bf16 v[58:61], v[154:157], v[178:181], v[58:61]
	v_mfma_f32_16x16x32_bf16 v[54:57], v[146:149], v[186:189], v[54:57]
	v_mfma_f32_16x16x32_bf16 v[46:49], v[154:157], v[186:189], v[46:49]
	v_mfma_f32_16x16x32_bf16 v[38:41], v[146:149], v[194:197], v[38:41]
	v_mfma_f32_16x16x32_bf16 v[30:33], v[154:157], v[194:197], v[30:33]
	v_mfma_f32_16x16x32_bf16 v[22:25], v[146:149], v[212:215], v[22:25]
	v_mfma_f32_16x16x32_bf16 v[14:17], v[154:157], v[212:215], v[14:17]
	s_setprio 0
	s_setprio 1
	v_mfma_f32_16x16x32_bf16 v[50:53], v[158:161], v[174:177], v[50:53]
	v_mfma_f32_16x16x32_bf16 v[42:45], v[166:169], v[174:177], v[42:45]
	v_mfma_f32_16x16x32_bf16 v[34:37], v[158:161], v[182:185], v[34:37]
	v_mfma_f32_16x16x32_bf16 v[26:29], v[166:169], v[182:185], v[26:29]
	v_mfma_f32_16x16x32_bf16 v[18:21], v[158:161], v[190:193], v[18:21]
	v_mfma_f32_16x16x32_bf16 v[10:13], v[166:169], v[190:193], v[10:13]
	v_mfma_f32_16x16x32_bf16 v[6:9], v[158:161], v[198:201], v[6:9]
	v_mfma_f32_16x16x32_bf16 v[2:5], v[166:169], v[198:201], v[2:5]
	v_mfma_f32_16x16x32_bf16 v[50:53], v[162:165], v[178:181], v[50:53]
	v_mfma_f32_16x16x32_bf16 v[42:45], v[170:173], v[178:181], v[42:45]
	v_mfma_f32_16x16x32_bf16 v[34:37], v[162:165], v[186:189], v[34:37]
	v_mfma_f32_16x16x32_bf16 v[26:29], v[170:173], v[186:189], v[26:29]
	v_mfma_f32_16x16x32_bf16 v[18:21], v[162:165], v[194:197], v[18:21]
	v_mfma_f32_16x16x32_bf16 v[10:13], v[170:173], v[194:197], v[10:13]
	v_mfma_f32_16x16x32_bf16 v[6:9], v[162:165], v[212:215], v[6:9]
	v_mfma_f32_16x16x32_bf16 v[2:5], v[170:173], v[212:215], v[2:5]
	s_setprio 0
	s_barrier
	v_add_u32_e32 v130, s27, v137
	ds_read_b128 v[142:145], v130
	ds_read_b128 v[146:149], v130 offset:1024
	ds_read_b128 v[150:153], v130 offset:2048
	ds_read_b128 v[154:157], v130 offset:3072
	v_add_u32_e32 v130, s34, v137
	ds_read_b128 v[158:161], v130
	ds_read_b128 v[162:165], v130 offset:1024
	ds_read_b128 v[166:169], v130 offset:2048
	ds_read_b128 v[170:173], v130 offset:3072
	s_add_i32 s50, s50, 0x160000
	s_mov_b32 m0, s25
	v_add_u32_e32 v130, s50, v132
	ds_read_b128 v[174:177], v141 offset:32768
	ds_read_b128 v[178:181], v141 offset:33792
	ds_read_b128 v[182:185], v141 offset:34816
	ds_read_b128 v[186:189], v141 offset:35840
	ds_read_b128 v[190:193], v141 offset:36864
	ds_read_b128 v[194:197], v141 offset:37888
	ds_read_b128 v[198:201], v141 offset:38912
	ds_read_b128 v[212:215], v141 offset:39936
	global_load_lds_dwordx4 v130, s[0:1]
	v_add_u32_e32 v130, s50, v134
	s_mov_b32 m0, s26
	s_nop 0
	global_load_lds_dwordx4 v130, s[0:1]
	s_waitcnt vmcnt(8)
	s_waitcnt lgkmcnt(0)
	s_setprio 1
	s_barrier
	v_mfma_f32_16x16x32_bf16 v[126:129], v[142:145], v[174:177], v[126:129]
	v_mfma_f32_16x16x32_bf16 v[122:125], v[150:153], v[174:177], v[122:125]
	v_mfma_f32_16x16x32_bf16 v[118:121], v[142:145], v[182:185], v[118:121]
	v_mfma_f32_16x16x32_bf16 v[110:113], v[150:153], v[182:185], v[110:113]
	v_mfma_f32_16x16x32_bf16 v[102:105], v[142:145], v[190:193], v[102:105]
	v_mfma_f32_16x16x32_bf16 v[94:97], v[150:153], v[190:193], v[94:97]
	v_mfma_f32_16x16x32_bf16 v[86:89], v[142:145], v[198:201], v[86:89]
	v_mfma_f32_16x16x32_bf16 v[78:81], v[150:153], v[198:201], v[78:81]
	v_mfma_f32_16x16x32_bf16 v[126:129], v[146:149], v[178:181], v[126:129]
	v_mfma_f32_16x16x32_bf16 v[122:125], v[154:157], v[178:181], v[122:125]
	v_mfma_f32_16x16x32_bf16 v[118:121], v[146:149], v[186:189], v[118:121]
	v_mfma_f32_16x16x32_bf16 v[110:113], v[154:157], v[186:189], v[110:113]
	v_mfma_f32_16x16x32_bf16 v[102:105], v[146:149], v[194:197], v[102:105]
	v_mfma_f32_16x16x32_bf16 v[94:97], v[154:157], v[194:197], v[94:97]
	v_mfma_f32_16x16x32_bf16 v[86:89], v[146:149], v[212:215], v[86:89]
	v_mfma_f32_16x16x32_bf16 v[78:81], v[154:157], v[212:215], v[78:81]
	s_setprio 0
	s_setprio 1
	v_mfma_f32_16x16x32_bf16 v[114:117], v[158:161], v[174:177], v[114:117]
	v_mfma_f32_16x16x32_bf16 v[106:109], v[166:169], v[174:177], v[106:109]
	v_mfma_f32_16x16x32_bf16 v[98:101], v[158:161], v[182:185], v[98:101]
	v_mfma_f32_16x16x32_bf16 v[90:93], v[166:169], v[182:185], v[90:93]
	v_mfma_f32_16x16x32_bf16 v[82:85], v[158:161], v[190:193], v[82:85]
	v_mfma_f32_16x16x32_bf16 v[74:77], v[166:169], v[190:193], v[74:77]
	v_mfma_f32_16x16x32_bf16 v[70:73], v[158:161], v[198:201], v[70:73]
	v_mfma_f32_16x16x32_bf16 v[66:69], v[166:169], v[198:201], v[66:69]
	v_mfma_f32_16x16x32_bf16 v[114:117], v[162:165], v[178:181], v[114:117]
	v_mfma_f32_16x16x32_bf16 v[106:109], v[170:173], v[178:181], v[106:109]
	v_mfma_f32_16x16x32_bf16 v[98:101], v[162:165], v[186:189], v[98:101]
	v_mfma_f32_16x16x32_bf16 v[90:93], v[170:173], v[186:189], v[90:93]
	v_mfma_f32_16x16x32_bf16 v[82:85], v[162:165], v[194:197], v[82:85]
	v_mfma_f32_16x16x32_bf16 v[74:77], v[170:173], v[194:197], v[74:77]
	v_mfma_f32_16x16x32_bf16 v[70:73], v[162:165], v[212:215], v[70:73]
	v_mfma_f32_16x16x32_bf16 v[66:69], v[170:173], v[212:215], v[66:69]
	s_setprio 0
	s_barrier
	s_or_b32 s50, s49, 0x80
	s_mov_b32 m0, s28
	v_add_u32_e32 v130, s50, v133
	ds_read_b128 v[174:177], v141 offset:49152
	ds_read_b128 v[178:181], v141 offset:50176
	ds_read_b128 v[182:185], v141 offset:51200
	ds_read_b128 v[186:189], v141 offset:52224
	ds_read_b128 v[190:193], v141 offset:53248
	ds_read_b128 v[194:197], v141 offset:54272
	ds_read_b128 v[198:201], v141 offset:55296
	ds_read_b128 v[212:215], v141 offset:56320
	global_load_lds_dwordx4 v130, s[2:3]
	v_add_u32_e32 v130, s50, v135
	s_mov_b32 m0, s29
	s_add_i32 s49, s49, 0x160080
	global_load_lds_dwordx4 v130, s[2:3]
	v_add_u32_e32 v130, s49, v133
	s_mov_b32 m0, s35
	s_nop 0
	global_load_lds_dwordx4 v130, s[2:3]
	v_add_u32_e32 v130, s49, v135
	s_mov_b32 m0, s36
	s_nop 0
	global_load_lds_dwordx4 v130, s[2:3]
	v_add_u32_e32 v130, s48, v132
	s_mov_b32 m0, s30
	s_nop 0
	global_load_lds_dwordx4 v130, s[0:1]
	v_add_u32_e32 v130, s48, v134
	s_mov_b32 m0, s31
	s_nop 0
	global_load_lds_dwordx4 v130, s[0:1]
	s_add_i32 s47, s47, 2
	s_addk_i32 s45, 0x100
	s_addk_i32 s46, 0x100
	s_cmpk_gt_u32 s47, 0x55
	s_waitcnt vmcnt(8)
	s_waitcnt lgkmcnt(0)
	s_setprio 1
	s_barrier
	v_mfma_f32_16x16x32_bf16 v[62:65], v[142:145], v[174:177], v[62:65]
	v_mfma_f32_16x16x32_bf16 v[58:61], v[150:153], v[174:177], v[58:61]
	v_mfma_f32_16x16x32_bf16 v[54:57], v[142:145], v[182:185], v[54:57]
	v_mfma_f32_16x16x32_bf16 v[46:49], v[150:153], v[182:185], v[46:49]
	v_mfma_f32_16x16x32_bf16 v[38:41], v[142:145], v[190:193], v[38:41]
	v_mfma_f32_16x16x32_bf16 v[30:33], v[150:153], v[190:193], v[30:33]
	v_mfma_f32_16x16x32_bf16 v[22:25], v[142:145], v[198:201], v[22:25]
	v_mfma_f32_16x16x32_bf16 v[14:17], v[150:153], v[198:201], v[14:17]
	v_mfma_f32_16x16x32_bf16 v[62:65], v[146:149], v[178:181], v[62:65]
	v_mfma_f32_16x16x32_bf16 v[58:61], v[154:157], v[178:181], v[58:61]
	v_mfma_f32_16x16x32_bf16 v[54:57], v[146:149], v[186:189], v[54:57]
	v_mfma_f32_16x16x32_bf16 v[46:49], v[154:157], v[186:189], v[46:49]
	v_mfma_f32_16x16x32_bf16 v[38:41], v[146:149], v[194:197], v[38:41]
	v_mfma_f32_16x16x32_bf16 v[30:33], v[154:157], v[194:197], v[30:33]
	v_mfma_f32_16x16x32_bf16 v[22:25], v[146:149], v[212:215], v[22:25]
	v_mfma_f32_16x16x32_bf16 v[14:17], v[154:157], v[212:215], v[14:17]
	s_setprio 0
	s_setprio 1
	v_mfma_f32_16x16x32_bf16 v[50:53], v[158:161], v[174:177], v[50:53]
	v_mfma_f32_16x16x32_bf16 v[42:45], v[166:169], v[174:177], v[42:45]
	v_mfma_f32_16x16x32_bf16 v[34:37], v[158:161], v[182:185], v[34:37]
	v_mfma_f32_16x16x32_bf16 v[26:29], v[166:169], v[182:185], v[26:29]
	v_mfma_f32_16x16x32_bf16 v[18:21], v[158:161], v[190:193], v[18:21]
	v_mfma_f32_16x16x32_bf16 v[10:13], v[166:169], v[190:193], v[10:13]
	v_mfma_f32_16x16x32_bf16 v[6:9], v[158:161], v[198:201], v[6:9]
	v_mfma_f32_16x16x32_bf16 v[2:5], v[166:169], v[198:201], v[2:5]
	v_mfma_f32_16x16x32_bf16 v[50:53], v[162:165], v[178:181], v[50:53]
	v_mfma_f32_16x16x32_bf16 v[42:45], v[170:173], v[178:181], v[42:45]
	v_mfma_f32_16x16x32_bf16 v[34:37], v[162:165], v[186:189], v[34:37]
	v_mfma_f32_16x16x32_bf16 v[26:29], v[170:173], v[186:189], v[26:29]
	v_mfma_f32_16x16x32_bf16 v[18:21], v[162:165], v[194:197], v[18:21]
	v_mfma_f32_16x16x32_bf16 v[10:13], v[170:173], v[194:197], v[10:13]
	v_mfma_f32_16x16x32_bf16 v[6:9], v[162:165], v[212:215], v[6:9]
	v_mfma_f32_16x16x32_bf16 v[2:5], v[170:173], v[212:215], v[2:5]
	s_setprio 0
	s_barrier
	s_cbranch_scc0 .LBB0_195
	s_and_b64 vcc, exec, s[10:11]
	s_cbranch_vccz .LBB0_198
	s_barrier

.LBB0_282:
	s_lshl_b32 s65, s28, 20
	s_and_b64 s[36:37], s[30:31], exec
	s_cselect_b32 s36, s65, s68
	s_lshl_b32 s66, s64, 20
	s_and_b64 s[70:71], s[30:31], exec
	s_cselect_b32 s37, s66, s67
	v_add_u32_e32 v135, s68, v150
	v_add_u32_e32 v136, s68, v151
	s_addk_i32 s67, 0x100
	s_addk_i32 s68, 0x100
	s_mov_b32 s69, -2
	s_waitcnt vmcnt(0)
	v_add_u32_e32 v137, s42, v148
	ds_read_b128 v[138:141], v137
	ds_read_b128 v[154:157], v137 offset:1024
	ds_read_b128 v[158:161], v137 offset:2048
	ds_read_b128 v[162:165], v137 offset:3072
	v_add_u32_e32 v137, s45, v148
	ds_read_b128 v[166:169], v137
	ds_read_b128 v[170:173], v137 offset:1024
	ds_read_b128 v[174:177], v137 offset:2048
	ds_read_b128 v[178:181], v137 offset:3072
	s_cmp_eq_u32 s69, 28
	s_cselect_b32 s72, s36, s68
	s_cselect_b32 s71, s37, s67
	s_or_b32 s70, s72, 0x80
	s_add_i32 m0, s48, 0xc000
	ds_read_b128 v[182:185], v152
	ds_read_b128 v[186:189], v152 offset:1024
	ds_read_b128 v[190:193], v152 offset:2048
	ds_read_b128 v[194:197], v152 offset:3072
	ds_read_b128 v[198:201], v152 offset:4096
	ds_read_b128 v[212:215], v152 offset:5120
	ds_read_b128 v[218:221], v152 offset:6144
	ds_read_b128 v[222:225], v152 offset:7168
	global_load_lds_dwordx4 v136, s[8:9]
	s_add_i32 m0, s48, 0xe000
	s_nop 0
	global_load_lds_dwordx4 v135, s[8:9]
	s_waitcnt vmcnt(8)
	s_waitcnt lgkmcnt(0)
	s_setprio 1
	s_barrier
	v_mfma_f32_16x16x32_bf16 v[126:129], v[138:141], v[182:185], 0
	v_mfma_f32_16x16x32_bf16 v[122:125], v[158:161], v[182:185], 0
	v_mfma_f32_16x16x32_bf16 v[110:113], v[138:141], v[190:193], 0
	v_mfma_f32_16x16x32_bf16 v[106:109], v[158:161], v[190:193], 0
	v_mfma_f32_16x16x32_bf16 v[94:97], v[138:141], v[198:201], 0
	v_mfma_f32_16x16x32_bf16 v[90:93], v[158:161], v[198:201], 0
	v_mfma_f32_16x16x32_bf16 v[78:81], v[138:141], v[218:221], 0
	v_mfma_f32_16x16x32_bf16 v[74:77], v[158:161], v[218:221], 0
	v_mfma_f32_16x16x32_bf16 v[126:129], v[154:157], v[186:189], v[126:129]
	v_mfma_f32_16x16x32_bf16 v[122:125], v[162:165], v[186:189], v[122:125]
	v_mfma_f32_16x16x32_bf16 v[110:113], v[154:157], v[194:197], v[110:113]
	v_mfma_f32_16x16x32_bf16 v[106:109], v[162:165], v[194:197], v[106:109]
	v_mfma_f32_16x16x32_bf16 v[94:97], v[154:157], v[212:215], v[94:97]
	v_mfma_f32_16x16x32_bf16 v[90:93], v[162:165], v[212:215], v[90:93]
	v_mfma_f32_16x16x32_bf16 v[78:81], v[154:157], v[222:225], v[78:81]
	v_mfma_f32_16x16x32_bf16 v[74:77], v[162:165], v[222:225], v[74:77]
	s_setprio 0
	s_setprio 1
	v_mfma_f32_16x16x32_bf16 v[118:121], v[166:169], v[182:185], 0
	v_mfma_f32_16x16x32_bf16 v[114:117], v[174:177], v[182:185], 0
	v_mfma_f32_16x16x32_bf16 v[102:105], v[166:169], v[190:193], 0
	v_mfma_f32_16x16x32_bf16 v[98:101], v[174:177], v[190:193], 0
	v_mfma_f32_16x16x32_bf16 v[86:89], v[166:169], v[198:201], 0
	v_mfma_f32_16x16x32_bf16 v[82:85], v[174:177], v[198:201], 0
	v_mfma_f32_16x16x32_bf16 v[70:73], v[166:169], v[218:221], 0
	v_mfma_f32_16x16x32_bf16 v[66:69], v[174:177], v[218:221], 0
	v_mfma_f32_16x16x32_bf16 v[118:121], v[170:173], v[186:189], v[118:121]
	v_mfma_f32_16x16x32_bf16 v[114:117], v[178:181], v[186:189], v[114:117]
	v_mfma_f32_16x16x32_bf16 v[102:105], v[170:173], v[194:197], v[102:105]
	v_mfma_f32_16x16x32_bf16 v[98:101], v[178:181], v[194:197], v[98:101]
	v_mfma_f32_16x16x32_bf16 v[86:89], v[170:173], v[212:215], v[86:89]
	v_mfma_f32_16x16x32_bf16 v[82:85], v[178:181], v[212:215], v[82:85]
	v_mfma_f32_16x16x32_bf16 v[70:73], v[170:173], v[222:225], v[70:73]
	v_mfma_f32_16x16x32_bf16 v[66:69], v[178:181], v[222:225], v[66:69]
	s_setprio 0
	s_barrier
	s_mov_b32 m0, s43
	v_add_u32_e32 v137, s71, v143
	ds_read_b128 v[182:185], v152 offset:16384
	ds_read_b128 v[186:189], v152 offset:17408
	ds_read_b128 v[190:193], v152 offset:18432
	ds_read_b128 v[194:197], v152 offset:19456
	ds_read_b128 v[198:201], v152 offset:20480
	ds_read_b128 v[212:215], v152 offset:21504
	ds_read_b128 v[218:221], v152 offset:22528
	ds_read_b128 v[222:225], v152 offset:23552
	global_load_lds_dwordx4 v137, s[10:11]
	v_add_u32_e32 v137, s71, v145
	s_mov_b32 m0, s44
	s_add_i32 s73, s71, 0x80000
	global_load_lds_dwordx4 v137, s[10:11]
	v_add_u32_e32 v137, s73, v143
	s_mov_b32 m0, s46
	s_nop 0
	global_load_lds_dwordx4 v137, s[10:11]
	v_add_u32_e32 v137, s73, v145
	s_mov_b32 m0, s47
	s_nop 0
	global_load_lds_dwordx4 v137, s[10:11]
	v_add_u32_e32 v137, s72, v142
	s_mov_b32 m0, s48
	s_nop 0
	global_load_lds_dwordx4 v137, s[8:9]
	v_add_u32_e32 v137, s72, v144
	s_mov_b32 m0, s49
	s_nop 0
	global_load_lds_dwordx4 v137, s[8:9]
	s_waitcnt vmcnt(8)
	s_waitcnt lgkmcnt(0)
	s_setprio 1
	s_barrier
	v_mfma_f32_16x16x32_bf16 v[62:65], v[138:141], v[182:185], 0
	v_mfma_f32_16x16x32_bf16 v[58:61], v[158:161], v[182:185], 0
	v_mfma_f32_16x16x32_bf16 v[46:49], v[138:141], v[190:193], 0
	v_mfma_f32_16x16x32_bf16 v[42:45], v[158:161], v[190:193], 0
	v_mfma_f32_16x16x32_bf16 v[30:33], v[138:141], v[198:201], 0
	v_mfma_f32_16x16x32_bf16 v[26:29], v[158:161], v[198:201], 0
	v_mfma_f32_16x16x32_bf16 v[14:17], v[138:141], v[218:221], 0
	v_mfma_f32_16x16x32_bf16 v[10:13], v[158:161], v[218:221], 0
	v_mfma_f32_16x16x32_bf16 v[62:65], v[154:157], v[186:189], v[62:65]
	v_mfma_f32_16x16x32_bf16 v[58:61], v[162:165], v[186:189], v[58:61]
	v_mfma_f32_16x16x32_bf16 v[46:49], v[154:157], v[194:197], v[46:49]
	v_mfma_f32_16x16x32_bf16 v[42:45], v[162:165], v[194:197], v[42:45]
	v_mfma_f32_16x16x32_bf16 v[30:33], v[154:157], v[212:215], v[30:33]
	v_mfma_f32_16x16x32_bf16 v[26:29], v[162:165], v[212:215], v[26:29]
	v_mfma_f32_16x16x32_bf16 v[14:17], v[154:157], v[222:225], v[14:17]
	v_mfma_f32_16x16x32_bf16 v[10:13], v[162:165], v[222:225], v[10:13]
	s_setprio 0
	s_setprio 1
	v_mfma_f32_16x16x32_bf16 v[54:57], v[166:169], v[182:185], 0
	v_mfma_f32_16x16x32_bf16 v[50:53], v[174:177], v[182:185], 0
	v_mfma_f32_16x16x32_bf16 v[38:41], v[166:169], v[190:193], 0
	v_mfma_f32_16x16x32_bf16 v[34:37], v[174:177], v[190:193], 0
	v_mfma_f32_16x16x32_bf16 v[22:25], v[166:169], v[198:201], 0
	v_mfma_f32_16x16x32_bf16 v[18:21], v[174:177], v[198:201], 0
	v_mfma_f32_16x16x32_bf16 v[6:9], v[166:169], v[218:221], 0
	v_mfma_f32_16x16x32_bf16 v[2:5], v[174:177], v[218:221], 0
	v_mfma_f32_16x16x32_bf16 v[54:57], v[170:173], v[186:189], v[54:57]
	v_mfma_f32_16x16x32_bf16 v[50:53], v[178:181], v[186:189], v[50:53]
	v_mfma_f32_16x16x32_bf16 v[38:41], v[170:173], v[194:197], v[38:41]
	v_mfma_f32_16x16x32_bf16 v[34:37], v[178:181], v[194:197], v[34:37]
	v_mfma_f32_16x16x32_bf16 v[22:25], v[170:173], v[212:215], v[22:25]
	v_mfma_f32_16x16x32_bf16 v[18:21], v[178:181], v[212:215], v[18:21]
	v_mfma_f32_16x16x32_bf16 v[6:9], v[170:173], v[222:225], v[6:9]
	v_mfma_f32_16x16x32_bf16 v[2:5], v[178:181], v[222:225], v[2:5]
	s_setprio 0
	s_barrier
	v_add_u32_e32 v137, s52, v148
	ds_read_b128 v[138:141], v137
	ds_read_b128 v[154:157], v137 offset:1024
	ds_read_b128 v[158:161], v137 offset:2048
	ds_read_b128 v[162:165], v137 offset:3072
	v_add_u32_e32 v137, s57, v148
	ds_read_b128 v[166:169], v137
	ds_read_b128 v[170:173], v137 offset:1024
	ds_read_b128 v[174:177], v137 offset:2048
	ds_read_b128 v[178:181], v137 offset:3072
	s_add_i32 s72, s72, 0x80000
	s_mov_b32 m0, s50
	v_add_u32_e32 v137, s72, v142
	ds_read_b128 v[182:185], v152 offset:32768
	ds_read_b128 v[186:189], v152 offset:33792
	ds_read_b128 v[190:193], v152 offset:34816
	ds_read_b128 v[194:197], v152 offset:35840
	ds_read_b128 v[198:201], v152 offset:36864
	ds_read_b128 v[212:215], v152 offset:37888
	ds_read_b128 v[218:221], v152 offset:38912
	ds_read_b128 v[222:225], v152 offset:39936
	global_load_lds_dwordx4 v137, s[8:9]
	v_add_u32_e32 v137, s72, v144
	s_mov_b32 m0, s51
	s_nop 0
	global_load_lds_dwordx4 v137, s[8:9]
	s_waitcnt vmcnt(8)
	s_waitcnt lgkmcnt(0)
	s_setprio 1
	s_barrier
	v_mfma_f32_16x16x32_bf16 v[126:129], v[138:141], v[182:185], v[126:129]
	v_mfma_f32_16x16x32_bf16 v[122:125], v[158:161], v[182:185], v[122:125]
	v_mfma_f32_16x16x32_bf16 v[110:113], v[138:141], v[190:193], v[110:113]
	v_mfma_f32_16x16x32_bf16 v[106:109], v[158:161], v[190:193], v[106:109]
	v_mfma_f32_16x16x32_bf16 v[94:97], v[138:141], v[198:201], v[94:97]
	v_mfma_f32_16x16x32_bf16 v[90:93], v[158:161], v[198:201], v[90:93]
	v_mfma_f32_16x16x32_bf16 v[78:81], v[138:141], v[218:221], v[78:81]
	v_mfma_f32_16x16x32_bf16 v[74:77], v[158:161], v[218:221], v[74:77]
	v_mfma_f32_16x16x32_bf16 v[126:129], v[154:157], v[186:189], v[126:129]
	v_mfma_f32_16x16x32_bf16 v[122:125], v[162:165], v[186:189], v[122:125]
	v_mfma_f32_16x16x32_bf16 v[110:113], v[154:157], v[194:197], v[110:113]
	v_mfma_f32_16x16x32_bf16 v[106:109], v[162:165], v[194:197], v[106:109]
	v_mfma_f32_16x16x32_bf16 v[94:97], v[154:157], v[212:215], v[94:97]
	v_mfma_f32_16x16x32_bf16 v[90:93], v[162:165], v[212:215], v[90:93]
	v_mfma_f32_16x16x32_bf16 v[78:81], v[154:157], v[222:225], v[78:81]
	v_mfma_f32_16x16x32_bf16 v[74:77], v[162:165], v[222:225], v[74:77]
	s_setprio 0
	s_setprio 1
	v_mfma_f32_16x16x32_bf16 v[118:121], v[166:169], v[182:185], v[118:121]
	v_mfma_f32_16x16x32_bf16 v[114:117], v[174:177], v[182:185], v[114:117]
	v_mfma_f32_16x16x32_bf16 v[102:105], v[166:169], v[190:193], v[102:105]
	v_mfma_f32_16x16x32_bf16 v[98:101], v[174:177], v[190:193], v[98:101]
	v_mfma_f32_16x16x32_bf16 v[86:89], v[166:169], v[198:201], v[86:89]
	v_mfma_f32_16x16x32_bf16 v[82:85], v[174:177], v[198:201], v[82:85]
	v_mfma_f32_16x16x32_bf16 v[70:73], v[166:169], v[218:221], v[70:73]
	v_mfma_f32_16x16x32_bf16 v[66:69], v[174:177], v[218:221], v[66:69]
	v_mfma_f32_16x16x32_bf16 v[118:121], v[170:173], v[186:189], v[118:121]
	v_mfma_f32_16x16x32_bf16 v[114:117], v[178:181], v[186:189], v[114:117]
	v_mfma_f32_16x16x32_bf16 v[102:105], v[170:173], v[194:197], v[102:105]
	v_mfma_f32_16x16x32_bf16 v[98:101], v[178:181], v[194:197], v[98:101]
	v_mfma_f32_16x16x32_bf16 v[86:89], v[170:173], v[212:215], v[86:89]
	v_mfma_f32_16x16x32_bf16 v[82:85], v[178:181], v[212:215], v[82:85]
	v_mfma_f32_16x16x32_bf16 v[70:73], v[170:173], v[222:225], v[70:73]
	v_mfma_f32_16x16x32_bf16 v[66:69], v[178:181], v[222:225], v[66:69]
	s_setprio 0
	s_barrier
	s_or_b32 s72, s71, 0x80
	s_mov_b32 m0, s53
	v_add_u32_e32 v137, s72, v143
	ds_read_b128 v[182:185], v152 offset:49152
	ds_read_b128 v[186:189], v152 offset:50176
	ds_read_b128 v[190:193], v152 offset:51200
	ds_read_b128 v[194:197], v152 offset:52224
	ds_read_b128 v[198:201], v152 offset:53248
	ds_read_b128 v[212:215], v152 offset:54272
	ds_read_b128 v[218:221], v152 offset:55296
	ds_read_b128 v[222:225], v152 offset:56320
	global_load_lds_dwordx4 v137, s[10:11]
	v_add_u32_e32 v137, s72, v145
	s_mov_b32 m0, s54
	s_add_i32 s71, s71, 0x80080
	global_load_lds_dwordx4 v137, s[10:11]
	v_add_u32_e32 v137, s71, v143
	s_mov_b32 m0, s58
	s_nop 0
	global_load_lds_dwordx4 v137, s[10:11]
	v_add_u32_e32 v137, s71, v145
	s_mov_b32 m0, s59
	s_nop 0
	global_load_lds_dwordx4 v137, s[10:11]
	v_add_u32_e32 v137, s70, v142
	s_mov_b32 m0, s55
	s_nop 0
	global_load_lds_dwordx4 v137, s[8:9]
	v_add_u32_e32 v137, s70, v144
	s_mov_b32 m0, s56
	s_nop 0
	global_load_lds_dwordx4 v137, s[8:9]
	s_waitcnt vmcnt(8)
	s_waitcnt lgkmcnt(0)
	s_setprio 1
	s_barrier
	v_mfma_f32_16x16x32_bf16 v[62:65], v[138:141], v[182:185], v[62:65]
	v_mfma_f32_16x16x32_bf16 v[58:61], v[158:161], v[182:185], v[58:61]
	v_mfma_f32_16x16x32_bf16 v[46:49], v[138:141], v[190:193], v[46:49]
	v_mfma_f32_16x16x32_bf16 v[42:45], v[158:161], v[190:193], v[42:45]
	v_mfma_f32_16x16x32_bf16 v[30:33], v[138:141], v[198:201], v[30:33]
	v_mfma_f32_16x16x32_bf16 v[26:29], v[158:161], v[198:201], v[26:29]
	v_mfma_f32_16x16x32_bf16 v[14:17], v[138:141], v[218:221], v[14:17]
	v_mfma_f32_16x16x32_bf16 v[10:13], v[158:161], v[218:221], v[10:13]
	v_mfma_f32_16x16x32_bf16 v[62:65], v[154:157], v[186:189], v[62:65]
	v_mfma_f32_16x16x32_bf16 v[58:61], v[162:165], v[186:189], v[58:61]
	v_mfma_f32_16x16x32_bf16 v[46:49], v[154:157], v[194:197], v[46:49]
	v_mfma_f32_16x16x32_bf16 v[42:45], v[162:165], v[194:197], v[42:45]
	v_mfma_f32_16x16x32_bf16 v[30:33], v[154:157], v[212:215], v[30:33]
	v_mfma_f32_16x16x32_bf16 v[26:29], v[162:165], v[212:215], v[26:29]
	v_mfma_f32_16x16x32_bf16 v[14:17], v[154:157], v[222:225], v[14:17]
	v_mfma_f32_16x16x32_bf16 v[10:13], v[162:165], v[222:225], v[10:13]
	s_setprio 0
	s_setprio 1
	v_mfma_f32_16x16x32_bf16 v[54:57], v[166:169], v[182:185], v[54:57]
	v_mfma_f32_16x16x32_bf16 v[50:53], v[174:177], v[182:185], v[50:53]
	v_mfma_f32_16x16x32_bf16 v[38:41], v[166:169], v[190:193], v[38:41]
	v_mfma_f32_16x16x32_bf16 v[34:37], v[174:177], v[190:193], v[34:37]
	v_mfma_f32_16x16x32_bf16 v[22:25], v[166:169], v[198:201], v[22:25]
	v_mfma_f32_16x16x32_bf16 v[18:21], v[174:177], v[198:201], v[18:21]
	v_mfma_f32_16x16x32_bf16 v[6:9], v[166:169], v[218:221], v[6:9]
	v_mfma_f32_16x16x32_bf16 v[2:5], v[174:177], v[218:221], v[2:5]
	v_mfma_f32_16x16x32_bf16 v[54:57], v[170:173], v[186:189], v[54:57]
	v_mfma_f32_16x16x32_bf16 v[50:53], v[178:181], v[186:189], v[50:53]
	v_mfma_f32_16x16x32_bf16 v[38:41], v[170:173], v[194:197], v[38:41]
	v_mfma_f32_16x16x32_bf16 v[34:37], v[178:181], v[194:197], v[34:37]
	v_mfma_f32_16x16x32_bf16 v[22:25], v[170:173], v[212:215], v[22:25]
	v_mfma_f32_16x16x32_bf16 v[18:21], v[178:181], v[212:215], v[18:21]
	v_mfma_f32_16x16x32_bf16 v[6:9], v[170:173], v[222:225], v[6:9]
	v_mfma_f32_16x16x32_bf16 v[2:5], v[178:181], v[222:225], v[2:5]
	s_setprio 0
	s_barrier
	s_add_i32 s69, s69, 2
	s_addk_i32 s67, 0x100
	s_addk_i32 s68, 0x100
	v_add_u32_e32 v135, 0x100, v135
	s_cmp_gt_u32 s69, 29
	v_add_u32_e32 v136, 0x100, v136
.LBB0_283:
	v_add_u32_e32 v137, s42, v148
	ds_read_b128 v[138:141], v137
	ds_read_b128 v[154:157], v137 offset:1024
	ds_read_b128 v[158:161], v137 offset:2048
	ds_read_b128 v[162:165], v137 offset:3072
	v_add_u32_e32 v137, s45, v148
	ds_read_b128 v[166:169], v137
	ds_read_b128 v[170:173], v137 offset:1024
	ds_read_b128 v[174:177], v137 offset:2048
	ds_read_b128 v[178:181], v137 offset:3072
	s_cmp_eq_u32 s69, 28
	s_cselect_b32 s72, s36, s68
	s_cselect_b32 s71, s37, s67
	s_or_b32 s70, s72, 0x80
	s_add_i32 m0, s48, 0xc000
	ds_read_b128 v[182:185], v152
	ds_read_b128 v[186:189], v152 offset:1024
	ds_read_b128 v[190:193], v152 offset:2048
	ds_read_b128 v[194:197], v152 offset:3072
	ds_read_b128 v[198:201], v152 offset:4096
	ds_read_b128 v[212:215], v152 offset:5120
	ds_read_b128 v[218:221], v152 offset:6144
	ds_read_b128 v[222:225], v152 offset:7168
	global_load_lds_dwordx4 v136, s[8:9]
	s_add_i32 m0, s48, 0xe000
	s_nop 0
	global_load_lds_dwordx4 v135, s[8:9]
	s_waitcnt vmcnt(8)
	s_waitcnt lgkmcnt(0)
	s_setprio 1
	s_barrier
	v_mfma_f32_16x16x32_bf16 v[126:129], v[138:141], v[182:185], v[126:129]
	v_mfma_f32_16x16x32_bf16 v[122:125], v[158:161], v[182:185], v[122:125]
	v_mfma_f32_16x16x32_bf16 v[110:113], v[138:141], v[190:193], v[110:113]
	v_mfma_f32_16x16x32_bf16 v[106:109], v[158:161], v[190:193], v[106:109]
	v_mfma_f32_16x16x32_bf16 v[94:97], v[138:141], v[198:201], v[94:97]
	v_mfma_f32_16x16x32_bf16 v[90:93], v[158:161], v[198:201], v[90:93]
	v_mfma_f32_16x16x32_bf16 v[78:81], v[138:141], v[218:221], v[78:81]
	v_mfma_f32_16x16x32_bf16 v[74:77], v[158:161], v[218:221], v[74:77]
	v_mfma_f32_16x16x32_bf16 v[126:129], v[154:157], v[186:189], v[126:129]
	v_mfma_f32_16x16x32_bf16 v[122:125], v[162:165], v[186:189], v[122:125]
	v_mfma_f32_16x16x32_bf16 v[110:113], v[154:157], v[194:197], v[110:113]
	v_mfma_f32_16x16x32_bf16 v[106:109], v[162:165], v[194:197], v[106:109]
	v_mfma_f32_16x16x32_bf16 v[94:97], v[154:157], v[212:215], v[94:97]
	v_mfma_f32_16x16x32_bf16 v[90:93], v[162:165], v[212:215], v[90:93]
	v_mfma_f32_16x16x32_bf16 v[78:81], v[154:157], v[222:225], v[78:81]
	v_mfma_f32_16x16x32_bf16 v[74:77], v[162:165], v[222:225], v[74:77]
	s_setprio 0
	s_setprio 1
	v_mfma_f32_16x16x32_bf16 v[118:121], v[166:169], v[182:185], v[118:121]
	v_mfma_f32_16x16x32_bf16 v[114:117], v[174:177], v[182:185], v[114:117]
	v_mfma_f32_16x16x32_bf16 v[102:105], v[166:169], v[190:193], v[102:105]
	v_mfma_f32_16x16x32_bf16 v[98:101], v[174:177], v[190:193], v[98:101]
	v_mfma_f32_16x16x32_bf16 v[86:89], v[166:169], v[198:201], v[86:89]
	v_mfma_f32_16x16x32_bf16 v[82:85], v[174:177], v[198:201], v[82:85]
	v_mfma_f32_16x16x32_bf16 v[70:73], v[166:169], v[218:221], v[70:73]
	v_mfma_f32_16x16x32_bf16 v[66:69], v[174:177], v[218:221], v[66:69]
	v_mfma_f32_16x16x32_bf16 v[118:121], v[170:173], v[186:189], v[118:121]
	v_mfma_f32_16x16x32_bf16 v[114:117], v[178:181], v[186:189], v[114:117]
	v_mfma_f32_16x16x32_bf16 v[102:105], v[170:173], v[194:197], v[102:105]
	v_mfma_f32_16x16x32_bf16 v[98:101], v[178:181], v[194:197], v[98:101]
	v_mfma_f32_16x16x32_bf16 v[86:89], v[170:173], v[212:215], v[86:89]
	v_mfma_f32_16x16x32_bf16 v[82:85], v[178:181], v[212:215], v[82:85]
	v_mfma_f32_16x16x32_bf16 v[70:73], v[170:173], v[222:225], v[70:73]
	v_mfma_f32_16x16x32_bf16 v[66:69], v[178:181], v[222:225], v[66:69]
	s_setprio 0
	s_barrier
	s_mov_b32 m0, s43
	v_add_u32_e32 v137, s71, v143
	ds_read_b128 v[182:185], v152 offset:16384
	ds_read_b128 v[186:189], v152 offset:17408
	ds_read_b128 v[190:193], v152 offset:18432
	ds_read_b128 v[194:197], v152 offset:19456
	ds_read_b128 v[198:201], v152 offset:20480
	ds_read_b128 v[212:215], v152 offset:21504
	ds_read_b128 v[218:221], v152 offset:22528
	ds_read_b128 v[222:225], v152 offset:23552
	global_load_lds_dwordx4 v137, s[10:11]
	v_add_u32_e32 v137, s71, v145
	s_mov_b32 m0, s44
	s_add_i32 s73, s71, 0x80000
	global_load_lds_dwordx4 v137, s[10:11]
	v_add_u32_e32 v137, s73, v143
	s_mov_b32 m0, s46
	s_nop 0
	global_load_lds_dwordx4 v137, s[10:11]
	v_add_u32_e32 v137, s73, v145
	s_mov_b32 m0, s47
	s_nop 0
	global_load_lds_dwordx4 v137, s[10:11]
	v_add_u32_e32 v137, s72, v142
	s_mov_b32 m0, s48
	s_nop 0
	global_load_lds_dwordx4 v137, s[8:9]
	v_add_u32_e32 v137, s72, v144
	s_mov_b32 m0, s49
	s_nop 0
	global_load_lds_dwordx4 v137, s[8:9]
	s_waitcnt vmcnt(8)
	s_waitcnt lgkmcnt(0)
	s_setprio 1
	s_barrier
	v_mfma_f32_16x16x32_bf16 v[62:65], v[138:141], v[182:185], v[62:65]
	v_mfma_f32_16x16x32_bf16 v[58:61], v[158:161], v[182:185], v[58:61]
	v_mfma_f32_16x16x32_bf16 v[46:49], v[138:141], v[190:193], v[46:49]
	v_mfma_f32_16x16x32_bf16 v[42:45], v[158:161], v[190:193], v[42:45]
	v_mfma_f32_16x16x32_bf16 v[30:33], v[138:141], v[198:201], v[30:33]
	v_mfma_f32_16x16x32_bf16 v[26:29], v[158:161], v[198:201], v[26:29]
	v_mfma_f32_16x16x32_bf16 v[14:17], v[138:141], v[218:221], v[14:17]
	v_mfma_f32_16x16x32_bf16 v[10:13], v[158:161], v[218:221], v[10:13]
	v_mfma_f32_16x16x32_bf16 v[62:65], v[154:157], v[186:189], v[62:65]
	v_mfma_f32_16x16x32_bf16 v[58:61], v[162:165], v[186:189], v[58:61]
	v_mfma_f32_16x16x32_bf16 v[46:49], v[154:157], v[194:197], v[46:49]
	v_mfma_f32_16x16x32_bf16 v[42:45], v[162:165], v[194:197], v[42:45]
	v_mfma_f32_16x16x32_bf16 v[30:33], v[154:157], v[212:215], v[30:33]
	v_mfma_f32_16x16x32_bf16 v[26:29], v[162:165], v[212:215], v[26:29]
	v_mfma_f32_16x16x32_bf16 v[14:17], v[154:157], v[222:225], v[14:17]
	v_mfma_f32_16x16x32_bf16 v[10:13], v[162:165], v[222:225], v[10:13]
	s_setprio 0
	s_setprio 1
	v_mfma_f32_16x16x32_bf16 v[54:57], v[166:169], v[182:185], v[54:57]
	v_mfma_f32_16x16x32_bf16 v[50:53], v[174:177], v[182:185], v[50:53]
	v_mfma_f32_16x16x32_bf16 v[38:41], v[166:169], v[190:193], v[38:41]
	v_mfma_f32_16x16x32_bf16 v[34:37], v[174:177], v[190:193], v[34:37]
	v_mfma_f32_16x16x32_bf16 v[22:25], v[166:169], v[198:201], v[22:25]
	v_mfma_f32_16x16x32_bf16 v[18:21], v[174:177], v[198:201], v[18:21]
	v_mfma_f32_16x16x32_bf16 v[6:9], v[166:169], v[218:221], v[6:9]
	v_mfma_f32_16x16x32_bf16 v[2:5], v[174:177], v[218:221], v[2:5]
	v_mfma_f32_16x16x32_bf16 v[54:57], v[170:173], v[186:189], v[54:57]
	v_mfma_f32_16x16x32_bf16 v[50:53], v[178:181], v[186:189], v[50:53]
	v_mfma_f32_16x16x32_bf16 v[38:41], v[170:173], v[194:197], v[38:41]
	v_mfma_f32_16x16x32_bf16 v[34:37], v[178:181], v[194:197], v[34:37]
	v_mfma_f32_16x16x32_bf16 v[22:25], v[170:173], v[212:215], v[22:25]
	v_mfma_f32_16x16x32_bf16 v[18:21], v[178:181], v[212:215], v[18:21]
	v_mfma_f32_16x16x32_bf16 v[6:9], v[170:173], v[222:225], v[6:9]
	v_mfma_f32_16x16x32_bf16 v[2:5], v[178:181], v[222:225], v[2:5]
	s_setprio 0
	s_barrier
	v_add_u32_e32 v137, s52, v148
	ds_read_b128 v[138:141], v137
	ds_read_b128 v[154:157], v137 offset:1024
	ds_read_b128 v[158:161], v137 offset:2048
	ds_read_b128 v[162:165], v137 offset:3072
	v_add_u32_e32 v137, s57, v148
	ds_read_b128 v[166:169], v137
	ds_read_b128 v[170:173], v137 offset:1024
	ds_read_b128 v[174:177], v137 offset:2048
	ds_read_b128 v[178:181], v137 offset:3072
	s_add_i32 s72, s72, 0x80000
	s_mov_b32 m0, s50
	v_add_u32_e32 v137, s72, v142
	ds_read_b128 v[182:185], v152 offset:32768
	ds_read_b128 v[186:189], v152 offset:33792
	ds_read_b128 v[190:193], v152 offset:34816
	ds_read_b128 v[194:197], v152 offset:35840
	ds_read_b128 v[198:201], v152 offset:36864
	ds_read_b128 v[212:215], v152 offset:37888
	ds_read_b128 v[218:221], v152 offset:38912
	ds_read_b128 v[222:225], v152 offset:39936
	global_load_lds_dwordx4 v137, s[8:9]
	v_add_u32_e32 v137, s72, v144
	s_mov_b32 m0, s51
	s_nop 0
	global_load_lds_dwordx4 v137, s[8:9]
	s_waitcnt vmcnt(8)
	s_waitcnt lgkmcnt(0)
	s_setprio 1
	s_barrier
	v_mfma_f32_16x16x32_bf16 v[126:129], v[138:141], v[182:185], v[126:129]
	v_mfma_f32_16x16x32_bf16 v[122:125], v[158:161], v[182:185], v[122:125]
	v_mfma_f32_16x16x32_bf16 v[110:113], v[138:141], v[190:193], v[110:113]
	v_mfma_f32_16x16x32_bf16 v[106:109], v[158:161], v[190:193], v[106:109]
	v_mfma_f32_16x16x32_bf16 v[94:97], v[138:141], v[198:201], v[94:97]
	v_mfma_f32_16x16x32_bf16 v[90:93], v[158:161], v[198:201], v[90:93]
	v_mfma_f32_16x16x32_bf16 v[78:81], v[138:141], v[218:221], v[78:81]
	v_mfma_f32_16x16x32_bf16 v[74:77], v[158:161], v[218:221], v[74:77]
	v_mfma_f32_16x16x32_bf16 v[126:129], v[154:157], v[186:189], v[126:129]
	v_mfma_f32_16x16x32_bf16 v[122:125], v[162:165], v[186:189], v[122:125]
	v_mfma_f32_16x16x32_bf16 v[110:113], v[154:157], v[194:197], v[110:113]
	v_mfma_f32_16x16x32_bf16 v[106:109], v[162:165], v[194:197], v[106:109]
	v_mfma_f32_16x16x32_bf16 v[94:97], v[154:157], v[212:215], v[94:97]
	v_mfma_f32_16x16x32_bf16 v[90:93], v[162:165], v[212:215], v[90:93]
	v_mfma_f32_16x16x32_bf16 v[78:81], v[154:157], v[222:225], v[78:81]
	v_mfma_f32_16x16x32_bf16 v[74:77], v[162:165], v[222:225], v[74:77]
	s_setprio 0
	s_setprio 1
	v_mfma_f32_16x16x32_bf16 v[118:121], v[166:169], v[182:185], v[118:121]
	v_mfma_f32_16x16x32_bf16 v[114:117], v[174:177], v[182:185], v[114:117]
	v_mfma_f32_16x16x32_bf16 v[102:105], v[166:169], v[190:193], v[102:105]
	v_mfma_f32_16x16x32_bf16 v[98:101], v[174:177], v[190:193], v[98:101]
	v_mfma_f32_16x16x32_bf16 v[86:89], v[166:169], v[198:201], v[86:89]
	v_mfma_f32_16x16x32_bf16 v[82:85], v[174:177], v[198:201], v[82:85]
	v_mfma_f32_16x16x32_bf16 v[70:73], v[166:169], v[218:221], v[70:73]
	v_mfma_f32_16x16x32_bf16 v[66:69], v[174:177], v[218:221], v[66:69]
	v_mfma_f32_16x16x32_bf16 v[118:121], v[170:173], v[186:189], v[118:121]
	v_mfma_f32_16x16x32_bf16 v[114:117], v[178:181], v[186:189], v[114:117]
	v_mfma_f32_16x16x32_bf16 v[102:105], v[170:173], v[194:197], v[102:105]
	v_mfma_f32_16x16x32_bf16 v[98:101], v[178:181], v[194:197], v[98:101]
	v_mfma_f32_16x16x32_bf16 v[86:89], v[170:173], v[212:215], v[86:89]
	v_mfma_f32_16x16x32_bf16 v[82:85], v[178:181], v[212:215], v[82:85]
	v_mfma_f32_16x16x32_bf16 v[70:73], v[170:173], v[222:225], v[70:73]
	v_mfma_f32_16x16x32_bf16 v[66:69], v[178:181], v[222:225], v[66:69]
	s_setprio 0
	s_barrier
	s_or_b32 s72, s71, 0x80
	s_mov_b32 m0, s53
	v_add_u32_e32 v137, s72, v143
	ds_read_b128 v[182:185], v152 offset:49152
	ds_read_b128 v[186:189], v152 offset:50176
	ds_read_b128 v[190:193], v152 offset:51200
	ds_read_b128 v[194:197], v152 offset:52224
	ds_read_b128 v[198:201], v152 offset:53248
	ds_read_b128 v[212:215], v152 offset:54272
	ds_read_b128 v[218:221], v152 offset:55296
	ds_read_b128 v[222:225], v152 offset:56320
	global_load_lds_dwordx4 v137, s[10:11]
	v_add_u32_e32 v137, s72, v145
	s_mov_b32 m0, s54
	s_add_i32 s71, s71, 0x80080
	global_load_lds_dwordx4 v137, s[10:11]
	v_add_u32_e32 v137, s71, v143
	s_mov_b32 m0, s58
	s_nop 0
	global_load_lds_dwordx4 v137, s[10:11]
	v_add_u32_e32 v137, s71, v145
	s_mov_b32 m0, s59
	s_nop 0
	global_load_lds_dwordx4 v137, s[10:11]
	v_add_u32_e32 v137, s70, v142
	s_mov_b32 m0, s55
	s_nop 0
	global_load_lds_dwordx4 v137, s[8:9]
	v_add_u32_e32 v137, s70, v144
	s_mov_b32 m0, s56
	s_nop 0
	global_load_lds_dwordx4 v137, s[8:9]
	s_add_i32 s69, s69, 2
	s_addk_i32 s67, 0x100
	s_addk_i32 s68, 0x100
	v_add_u32_e32 v135, 0x100, v135
	s_cmp_gt_u32 s69, 29
	v_add_u32_e32 v136, 0x100, v136
	s_waitcnt vmcnt(8)
	s_waitcnt lgkmcnt(0)
	s_setprio 1
	s_barrier
	v_mfma_f32_16x16x32_bf16 v[62:65], v[138:141], v[182:185], v[62:65]
	v_mfma_f32_16x16x32_bf16 v[58:61], v[158:161], v[182:185], v[58:61]
	v_mfma_f32_16x16x32_bf16 v[46:49], v[138:141], v[190:193], v[46:49]
	v_mfma_f32_16x16x32_bf16 v[42:45], v[158:161], v[190:193], v[42:45]
	v_mfma_f32_16x16x32_bf16 v[30:33], v[138:141], v[198:201], v[30:33]
	v_mfma_f32_16x16x32_bf16 v[26:29], v[158:161], v[198:201], v[26:29]
	v_mfma_f32_16x16x32_bf16 v[14:17], v[138:141], v[218:221], v[14:17]
	v_mfma_f32_16x16x32_bf16 v[10:13], v[158:161], v[218:221], v[10:13]
	v_mfma_f32_16x16x32_bf16 v[62:65], v[154:157], v[186:189], v[62:65]
	v_mfma_f32_16x16x32_bf16 v[58:61], v[162:165], v[186:189], v[58:61]
	v_mfma_f32_16x16x32_bf16 v[46:49], v[154:157], v[194:197], v[46:49]
	v_mfma_f32_16x16x32_bf16 v[42:45], v[162:165], v[194:197], v[42:45]
	v_mfma_f32_16x16x32_bf16 v[30:33], v[154:157], v[212:215], v[30:33]
	v_mfma_f32_16x16x32_bf16 v[26:29], v[162:165], v[212:215], v[26:29]
	v_mfma_f32_16x16x32_bf16 v[14:17], v[154:157], v[222:225], v[14:17]
	v_mfma_f32_16x16x32_bf16 v[10:13], v[162:165], v[222:225], v[10:13]
	s_setprio 0
	s_setprio 1
	v_mfma_f32_16x16x32_bf16 v[54:57], v[166:169], v[182:185], v[54:57]
	v_mfma_f32_16x16x32_bf16 v[50:53], v[174:177], v[182:185], v[50:53]
	v_mfma_f32_16x16x32_bf16 v[38:41], v[166:169], v[190:193], v[38:41]
	v_mfma_f32_16x16x32_bf16 v[34:37], v[174:177], v[190:193], v[34:37]
	v_mfma_f32_16x16x32_bf16 v[22:25], v[166:169], v[198:201], v[22:25]
	v_mfma_f32_16x16x32_bf16 v[18:21], v[174:177], v[198:201], v[18:21]
	v_mfma_f32_16x16x32_bf16 v[6:9], v[166:169], v[218:221], v[6:9]
	v_mfma_f32_16x16x32_bf16 v[2:5], v[174:177], v[218:221], v[2:5]
	v_mfma_f32_16x16x32_bf16 v[54:57], v[170:173], v[186:189], v[54:57]
	v_mfma_f32_16x16x32_bf16 v[50:53], v[178:181], v[186:189], v[50:53]
	v_mfma_f32_16x16x32_bf16 v[38:41], v[170:173], v[194:197], v[38:41]
	v_mfma_f32_16x16x32_bf16 v[34:37], v[178:181], v[194:197], v[34:37]
	v_mfma_f32_16x16x32_bf16 v[22:25], v[170:173], v[212:215], v[22:25]
	v_mfma_f32_16x16x32_bf16 v[18:21], v[178:181], v[212:215], v[18:21]
	v_mfma_f32_16x16x32_bf16 v[6:9], v[170:173], v[222:225], v[6:9]
	v_mfma_f32_16x16x32_bf16 v[2:5], v[178:181], v[222:225], v[2:5]
	s_setprio 0
	s_barrier
	s_cbranch_scc0 .LBB0_283
	s_and_b64 vcc, exec, s[20:21]
	s_cbranch_vccz .LBB0_286
	s_barrier

.LBB0_313:
	v_and_b32_e32 v134, 15, v130
	v_and_b32_e32 v8, 48, v130
	v_lshlrev_b32_e32 v9, 2, v130
	s_and_b32 s14, s12, 3
	s_lshl_b32 s26, s13, 13
	v_lshl_or_b32 v8, v134, 6, v8
	v_and_b32_e32 v9, 32, v9
	v_bitop3_b32 v10, v8, s26, v9 bitop3:0xde
	s_lshl_b32 s26, s14, 12
	v_bitop3_b32 v138, v8, s26, v9 bitop3:0xde
	s_add_i32 s26, s40, 0x18000
	s_or_b32 s28, s2, 0x80
	s_add_i32 s27, s26, s34
	v_add_u32_e32 v8, s28, v133
	s_mov_b32 m0, s27
	s_waitcnt vmcnt(2)
	s_barrier
	global_load_lds_dwordx4 v8, s[10:11]
	v_add_u32_e32 v8, s28, v136
	s_add_i32 s28, s27, 0x2000
	s_mov_b32 m0, s28
	s_or_b32 s30, s21, 0x80
	s_add_i32 s29, s22, 0x8000
	global_load_lds_dwordx4 v8, s[10:11]
	v_add_u32_e32 v8, s30, v131
	s_mov_b32 m0, s29
	s_add_i32 s31, s40, 0x1c000
	global_load_lds_dwordx4 v8, s[8:9]
	v_add_u32_e32 v8, s30, v135
	s_add_i32 s30, s22, 0xa000
	s_mov_b32 m0, s30
	s_or_b32 s35, s2, 0x80080
	s_add_i32 s34, s31, s34
	global_load_lds_dwordx4 v8, s[8:9]
	v_add_u32_e32 v8, s35, v133
	s_mov_b32 m0, s34
	s_add_i32 s36, s21, 0x80080
	global_load_lds_dwordx4 v8, s[10:11]
	v_add_u32_e32 v8, s35, v136
	s_add_i32 s35, s34, 0x2000
	s_mov_b32 m0, s35
	v_lshlrev_b32_e32 v6, 12, v6
	global_load_lds_dwordx4 v8, s[10:11]
	v_lshlrev_b32_e32 v8, 15, v5
	v_and_b32_e32 v8, 0xffff0000, v8
	v_and_b32_e32 v5, 1, v5
	v_add3_u32 v6, s36, v8, v6
	v_lshlrev_b32_e32 v5, 6, v5
	v_lshlrev_b32_e32 v7, 1, v7
	v_add3_u32 v139, v6, v5, v7
	v_lshlrev_b32_e32 v5, 15, v2
	v_and_b32_e32 v5, 0xffff0000, v5
	v_lshlrev_b32_e32 v3, 12, v3
	v_and_b32_e32 v2, 1, v2
	s_waitcnt vmcnt(6)
	v_add3_u32 v3, s36, v5, v3
	v_lshlrev_b32_e32 v2, 6, v2
	v_lshlrev_b32_e32 v4, 1, v4
	s_lshl_b32 s12, s13, 6
	v_add3_u32 v140, v3, v2, v4
	v_or_b32_e32 v137, s12, v134
	s_mov_b32 s36, -2
	s_mov_b32 s37, 0
	v_add_u32_e32 v141, s40, v10
	s_barrier
	v_add_u32_e32 v154, s3, v138
	v_add_u32_e32 v170, s18, v138
	ds_read_b128 v[142:145], v154
	ds_read_b128 v[146:149], v154 offset:1024
	ds_read_b128 v[150:153], v154 offset:2048
	ds_read_b128 v[154:157], v154 offset:3072
	ds_read_b128 v[158:161], v170
	ds_read_b128 v[162:165], v170 offset:1024
	ds_read_b128 v[166:169], v170 offset:2048
	ds_read_b128 v[170:173], v170 offset:3072
	s_add_i32 s41, s37, 0x100
	s_cmp_lg_u32 s36, 28
	s_cselect_b32 s43, s41, 0
	s_add_i32 s44, s43, s21
	s_or_b32 s42, s44, 0x80
	s_add_i32 s43, s43, s2
	v_add_u32_e32 v202, s37, v140
	s_add_i32 m0, s22, 0xc000
	ds_read_b128 v[174:177], v141
	ds_read_b128 v[178:181], v141 offset:1024
	ds_read_b128 v[182:185], v141 offset:2048
	ds_read_b128 v[186:189], v141 offset:3072
	ds_read_b128 v[190:193], v141 offset:4096
	ds_read_b128 v[194:197], v141 offset:5120
	ds_read_b128 v[198:201], v141 offset:6144
	ds_read_b128 v[212:215], v141 offset:7168
	global_load_lds_dwordx4 v202, s[8:9]
	v_add_u32_e32 v202, s37, v139
	s_add_i32 m0, s22, 0xe000
	s_nop 0
	global_load_lds_dwordx4 v202, s[8:9]
	s_waitcnt vmcnt(8)
	s_waitcnt lgkmcnt(0)
	s_setprio 1
	s_barrier
	v_mfma_f32_16x16x32_bf16 v[126:129], v[142:145], v[174:177], 0
	v_mfma_f32_16x16x32_bf16 v[122:125], v[150:153], v[174:177], 0
	v_mfma_f32_16x16x32_bf16 v[110:113], v[142:145], v[182:185], 0
	v_mfma_f32_16x16x32_bf16 v[106:109], v[150:153], v[182:185], 0
	v_mfma_f32_16x16x32_bf16 v[94:97], v[142:145], v[190:193], 0
	v_mfma_f32_16x16x32_bf16 v[90:93], v[150:153], v[190:193], 0
	v_mfma_f32_16x16x32_bf16 v[78:81], v[142:145], v[198:201], 0
	v_mfma_f32_16x16x32_bf16 v[74:77], v[150:153], v[198:201], 0
	v_mfma_f32_16x16x32_bf16 v[126:129], v[146:149], v[178:181], v[126:129]
	v_mfma_f32_16x16x32_bf16 v[122:125], v[154:157], v[178:181], v[122:125]
	v_mfma_f32_16x16x32_bf16 v[110:113], v[146:149], v[186:189], v[110:113]
	v_mfma_f32_16x16x32_bf16 v[106:109], v[154:157], v[186:189], v[106:109]
	v_mfma_f32_16x16x32_bf16 v[94:97], v[146:149], v[194:197], v[94:97]
	v_mfma_f32_16x16x32_bf16 v[90:93], v[154:157], v[194:197], v[90:93]
	v_mfma_f32_16x16x32_bf16 v[78:81], v[146:149], v[212:215], v[78:81]
	v_mfma_f32_16x16x32_bf16 v[74:77], v[154:157], v[212:215], v[74:77]
	s_setprio 0
	s_setprio 1
	v_mfma_f32_16x16x32_bf16 v[118:121], v[158:161], v[174:177], 0
	v_mfma_f32_16x16x32_bf16 v[114:117], v[166:169], v[174:177], 0
	v_mfma_f32_16x16x32_bf16 v[102:105], v[158:161], v[182:185], 0
	v_mfma_f32_16x16x32_bf16 v[98:101], v[166:169], v[182:185], 0
	v_mfma_f32_16x16x32_bf16 v[86:89], v[158:161], v[190:193], 0
	v_mfma_f32_16x16x32_bf16 v[82:85], v[166:169], v[190:193], 0
	v_mfma_f32_16x16x32_bf16 v[70:73], v[158:161], v[198:201], 0
	v_mfma_f32_16x16x32_bf16 v[66:69], v[166:169], v[198:201], 0
	v_mfma_f32_16x16x32_bf16 v[118:121], v[162:165], v[178:181], v[118:121]
	v_mfma_f32_16x16x32_bf16 v[114:117], v[170:173], v[178:181], v[114:117]
	v_mfma_f32_16x16x32_bf16 v[102:105], v[162:165], v[186:189], v[102:105]
	v_mfma_f32_16x16x32_bf16 v[98:101], v[170:173], v[186:189], v[98:101]
	v_mfma_f32_16x16x32_bf16 v[86:89], v[162:165], v[194:197], v[86:89]
	v_mfma_f32_16x16x32_bf16 v[82:85], v[170:173], v[194:197], v[82:85]
	v_mfma_f32_16x16x32_bf16 v[70:73], v[162:165], v[212:215], v[70:73]
	v_mfma_f32_16x16x32_bf16 v[66:69], v[170:173], v[212:215], v[66:69]
	s_setprio 0
	s_barrier
	s_mov_b32 m0, s16
	v_add_u32_e32 v202, s43, v133
	ds_read_b128 v[174:177], v141 offset:16384
	ds_read_b128 v[178:181], v141 offset:17408
	ds_read_b128 v[182:185], v141 offset:18432
	ds_read_b128 v[186:189], v141 offset:19456
	ds_read_b128 v[190:193], v141 offset:20480
	ds_read_b128 v[194:197], v141 offset:21504
	ds_read_b128 v[198:201], v141 offset:22528
	ds_read_b128 v[212:215], v141 offset:23552
	global_load_lds_dwordx4 v202, s[10:11]
	v_add_u32_e32 v202, s43, v136
	s_mov_b32 m0, s17
	s_add_i32 s37, s43, 0x80000
	global_load_lds_dwordx4 v202, s[10:11]
	v_add_u32_e32 v202, s37, v133
	s_mov_b32 m0, s19
	s_nop 0
	global_load_lds_dwordx4 v202, s[10:11]
	v_add_u32_e32 v202, s37, v136
	s_mov_b32 m0, s20
	s_nop 0
	global_load_lds_dwordx4 v202, s[10:11]
	v_add_u32_e32 v202, s44, v131
	s_mov_b32 m0, s22
	s_nop 0
	global_load_lds_dwordx4 v202, s[8:9]
	v_add_u32_e32 v202, s44, v135
	s_mov_b32 m0, s23
	s_nop 0
	global_load_lds_dwordx4 v202, s[8:9]
	s_waitcnt vmcnt(8)
	s_waitcnt lgkmcnt(0)
	s_setprio 1
	s_barrier
	v_mfma_f32_16x16x32_bf16 v[62:65], v[142:145], v[174:177], 0
	v_mfma_f32_16x16x32_bf16 v[58:61], v[150:153], v[174:177], 0
	v_mfma_f32_16x16x32_bf16 v[46:49], v[142:145], v[182:185], 0
	v_mfma_f32_16x16x32_bf16 v[42:45], v[150:153], v[182:185], 0
	v_mfma_f32_16x16x32_bf16 v[30:33], v[142:145], v[190:193], 0
	v_mfma_f32_16x16x32_bf16 v[26:29], v[150:153], v[190:193], 0
	v_mfma_f32_16x16x32_bf16 v[14:17], v[142:145], v[198:201], 0
	v_mfma_f32_16x16x32_bf16 v[10:13], v[150:153], v[198:201], 0
	v_mfma_f32_16x16x32_bf16 v[62:65], v[146:149], v[178:181], v[62:65]
	v_mfma_f32_16x16x32_bf16 v[58:61], v[154:157], v[178:181], v[58:61]
	v_mfma_f32_16x16x32_bf16 v[46:49], v[146:149], v[186:189], v[46:49]
	v_mfma_f32_16x16x32_bf16 v[42:45], v[154:157], v[186:189], v[42:45]
	v_mfma_f32_16x16x32_bf16 v[30:33], v[146:149], v[194:197], v[30:33]
	v_mfma_f32_16x16x32_bf16 v[26:29], v[154:157], v[194:197], v[26:29]
	v_mfma_f32_16x16x32_bf16 v[14:17], v[146:149], v[212:215], v[14:17]
	v_mfma_f32_16x16x32_bf16 v[10:13], v[154:157], v[212:215], v[10:13]
	s_setprio 0
	s_setprio 1
	v_mfma_f32_16x16x32_bf16 v[54:57], v[158:161], v[174:177], 0
	v_mfma_f32_16x16x32_bf16 v[50:53], v[166:169], v[174:177], 0
	v_mfma_f32_16x16x32_bf16 v[38:41], v[158:161], v[182:185], 0
	v_mfma_f32_16x16x32_bf16 v[34:37], v[166:169], v[182:185], 0
	v_mfma_f32_16x16x32_bf16 v[22:25], v[158:161], v[190:193], 0
	v_mfma_f32_16x16x32_bf16 v[18:21], v[166:169], v[190:193], 0
	v_mfma_f32_16x16x32_bf16 v[6:9], v[158:161], v[198:201], 0
	v_mfma_f32_16x16x32_bf16 v[2:5], v[166:169], v[198:201], 0
	v_mfma_f32_16x16x32_bf16 v[54:57], v[162:165], v[178:181], v[54:57]
	v_mfma_f32_16x16x32_bf16 v[50:53], v[170:173], v[178:181], v[50:53]
	v_mfma_f32_16x16x32_bf16 v[38:41], v[162:165], v[186:189], v[38:41]
	v_mfma_f32_16x16x32_bf16 v[34:37], v[170:173], v[186:189], v[34:37]
	v_mfma_f32_16x16x32_bf16 v[22:25], v[162:165], v[194:197], v[22:25]
	v_mfma_f32_16x16x32_bf16 v[18:21], v[170:173], v[194:197], v[18:21]
	v_mfma_f32_16x16x32_bf16 v[6:9], v[162:165], v[212:215], v[6:9]
	v_mfma_f32_16x16x32_bf16 v[2:5], v[170:173], v[212:215], v[2:5]
	s_setprio 0
	s_barrier
	v_add_u32_e32 v154, s26, v138
	v_add_u32_e32 v170, s31, v138
	ds_read_b128 v[142:145], v154
	ds_read_b128 v[146:149], v154 offset:1024
	ds_read_b128 v[150:153], v154 offset:2048
	ds_read_b128 v[154:157], v154 offset:3072
	ds_read_b128 v[158:161], v170
	ds_read_b128 v[162:165], v170 offset:1024
	ds_read_b128 v[166:169], v170 offset:2048
	ds_read_b128 v[170:173], v170 offset:3072
	s_add_i32 s44, s44, 0x80000
	s_mov_b32 m0, s24
	v_add_u32_e32 v202, s44, v131
	ds_read_b128 v[174:177], v141 offset:32768
	ds_read_b128 v[178:181], v141 offset:33792
	ds_read_b128 v[182:185], v141 offset:34816
	ds_read_b128 v[186:189], v141 offset:35840
	ds_read_b128 v[190:193], v141 offset:36864
	ds_read_b128 v[194:197], v141 offset:37888
	ds_read_b128 v[198:201], v141 offset:38912
	ds_read_b128 v[212:215], v141 offset:39936
	global_load_lds_dwordx4 v202, s[8:9]
	v_add_u32_e32 v202, s44, v135
	s_mov_b32 m0, s25
	s_nop 0
	global_load_lds_dwordx4 v202, s[8:9]
	s_waitcnt vmcnt(8)
	s_waitcnt lgkmcnt(0)
	s_setprio 1
	s_barrier
	v_mfma_f32_16x16x32_bf16 v[126:129], v[142:145], v[174:177], v[126:129]
	v_mfma_f32_16x16x32_bf16 v[122:125], v[150:153], v[174:177], v[122:125]
	v_mfma_f32_16x16x32_bf16 v[110:113], v[142:145], v[182:185], v[110:113]
	v_mfma_f32_16x16x32_bf16 v[106:109], v[150:153], v[182:185], v[106:109]
	v_mfma_f32_16x16x32_bf16 v[94:97], v[142:145], v[190:193], v[94:97]
	v_mfma_f32_16x16x32_bf16 v[90:93], v[150:153], v[190:193], v[90:93]
	v_mfma_f32_16x16x32_bf16 v[78:81], v[142:145], v[198:201], v[78:81]
	v_mfma_f32_16x16x32_bf16 v[74:77], v[150:153], v[198:201], v[74:77]
	v_mfma_f32_16x16x32_bf16 v[126:129], v[146:149], v[178:181], v[126:129]
	v_mfma_f32_16x16x32_bf16 v[122:125], v[154:157], v[178:181], v[122:125]
	v_mfma_f32_16x16x32_bf16 v[110:113], v[146:149], v[186:189], v[110:113]
	v_mfma_f32_16x16x32_bf16 v[106:109], v[154:157], v[186:189], v[106:109]
	v_mfma_f32_16x16x32_bf16 v[94:97], v[146:149], v[194:197], v[94:97]
	v_mfma_f32_16x16x32_bf16 v[90:93], v[154:157], v[194:197], v[90:93]
	v_mfma_f32_16x16x32_bf16 v[78:81], v[146:149], v[212:215], v[78:81]
	v_mfma_f32_16x16x32_bf16 v[74:77], v[154:157], v[212:215], v[74:77]
	s_setprio 0
	s_setprio 1
	v_mfma_f32_16x16x32_bf16 v[118:121], v[158:161], v[174:177], v[118:121]
	v_mfma_f32_16x16x32_bf16 v[114:117], v[166:169], v[174:177], v[114:117]
	v_mfma_f32_16x16x32_bf16 v[102:105], v[158:161], v[182:185], v[102:105]
	v_mfma_f32_16x16x32_bf16 v[98:101], v[166:169], v[182:185], v[98:101]
	v_mfma_f32_16x16x32_bf16 v[86:89], v[158:161], v[190:193], v[86:89]
	v_mfma_f32_16x16x32_bf16 v[82:85], v[166:169], v[190:193], v[82:85]
	v_mfma_f32_16x16x32_bf16 v[70:73], v[158:161], v[198:201], v[70:73]
	v_mfma_f32_16x16x32_bf16 v[66:69], v[166:169], v[198:201], v[66:69]
	v_mfma_f32_16x16x32_bf16 v[118:121], v[162:165], v[178:181], v[118:121]
	v_mfma_f32_16x16x32_bf16 v[114:117], v[170:173], v[178:181], v[114:117]
	v_mfma_f32_16x16x32_bf16 v[102:105], v[162:165], v[186:189], v[102:105]
	v_mfma_f32_16x16x32_bf16 v[98:101], v[170:173], v[186:189], v[98:101]
	v_mfma_f32_16x16x32_bf16 v[86:89], v[162:165], v[194:197], v[86:89]
	v_mfma_f32_16x16x32_bf16 v[82:85], v[170:173], v[194:197], v[82:85]
	v_mfma_f32_16x16x32_bf16 v[70:73], v[162:165], v[212:215], v[70:73]
	v_mfma_f32_16x16x32_bf16 v[66:69], v[170:173], v[212:215], v[66:69]
	s_setprio 0
	s_barrier
	s_or_b32 s37, s43, 0x80
	s_mov_b32 m0, s27
	v_add_u32_e32 v202, s37, v133
	ds_read_b128 v[174:177], v141 offset:49152
	ds_read_b128 v[178:181], v141 offset:50176
	ds_read_b128 v[182:185], v141 offset:51200
	ds_read_b128 v[186:189], v141 offset:52224
	ds_read_b128 v[190:193], v141 offset:53248
	ds_read_b128 v[194:197], v141 offset:54272
	ds_read_b128 v[198:201], v141 offset:55296
	ds_read_b128 v[212:215], v141 offset:56320
	global_load_lds_dwordx4 v202, s[10:11]
	v_add_u32_e32 v202, s37, v136
	s_mov_b32 m0, s28
	s_add_i32 s43, s43, 0x80080
	global_load_lds_dwordx4 v202, s[10:11]
	v_add_u32_e32 v202, s43, v133
	s_mov_b32 m0, s34
	s_nop 0
	global_load_lds_dwordx4 v202, s[10:11]
	v_add_u32_e32 v202, s43, v136
	s_mov_b32 m0, s35
	s_nop 0
	global_load_lds_dwordx4 v202, s[10:11]
	v_add_u32_e32 v202, s42, v131
	s_mov_b32 m0, s29
	s_nop 0
	global_load_lds_dwordx4 v202, s[8:9]
	v_add_u32_e32 v202, s42, v135
	s_mov_b32 m0, s30
	s_nop 0
	global_load_lds_dwordx4 v202, s[8:9]
	s_waitcnt vmcnt(8)
	s_waitcnt lgkmcnt(0)
	s_setprio 1
	s_barrier
	v_mfma_f32_16x16x32_bf16 v[62:65], v[142:145], v[174:177], v[62:65]
	v_mfma_f32_16x16x32_bf16 v[58:61], v[150:153], v[174:177], v[58:61]
	v_mfma_f32_16x16x32_bf16 v[46:49], v[142:145], v[182:185], v[46:49]
	v_mfma_f32_16x16x32_bf16 v[42:45], v[150:153], v[182:185], v[42:45]
	v_mfma_f32_16x16x32_bf16 v[30:33], v[142:145], v[190:193], v[30:33]
	v_mfma_f32_16x16x32_bf16 v[26:29], v[150:153], v[190:193], v[26:29]
	v_mfma_f32_16x16x32_bf16 v[14:17], v[142:145], v[198:201], v[14:17]
	v_mfma_f32_16x16x32_bf16 v[10:13], v[150:153], v[198:201], v[10:13]
	v_mfma_f32_16x16x32_bf16 v[62:65], v[146:149], v[178:181], v[62:65]
	v_mfma_f32_16x16x32_bf16 v[58:61], v[154:157], v[178:181], v[58:61]
	v_mfma_f32_16x16x32_bf16 v[46:49], v[146:149], v[186:189], v[46:49]
	v_mfma_f32_16x16x32_bf16 v[42:45], v[154:157], v[186:189], v[42:45]
	v_mfma_f32_16x16x32_bf16 v[30:33], v[146:149], v[194:197], v[30:33]
	v_mfma_f32_16x16x32_bf16 v[26:29], v[154:157], v[194:197], v[26:29]
	v_mfma_f32_16x16x32_bf16 v[14:17], v[146:149], v[212:215], v[14:17]
	v_mfma_f32_16x16x32_bf16 v[10:13], v[154:157], v[212:215], v[10:13]
	s_setprio 0
	s_setprio 1
	v_mfma_f32_16x16x32_bf16 v[54:57], v[158:161], v[174:177], v[54:57]
	v_mfma_f32_16x16x32_bf16 v[50:53], v[166:169], v[174:177], v[50:53]
	v_mfma_f32_16x16x32_bf16 v[38:41], v[158:161], v[182:185], v[38:41]
	v_mfma_f32_16x16x32_bf16 v[34:37], v[166:169], v[182:185], v[34:37]
	v_mfma_f32_16x16x32_bf16 v[22:25], v[158:161], v[190:193], v[22:25]
	v_mfma_f32_16x16x32_bf16 v[18:21], v[166:169], v[190:193], v[18:21]
	v_mfma_f32_16x16x32_bf16 v[6:9], v[158:161], v[198:201], v[6:9]
	v_mfma_f32_16x16x32_bf16 v[2:5], v[166:169], v[198:201], v[2:5]
	v_mfma_f32_16x16x32_bf16 v[54:57], v[162:165], v[178:181], v[54:57]
	v_mfma_f32_16x16x32_bf16 v[50:53], v[170:173], v[178:181], v[50:53]
	v_mfma_f32_16x16x32_bf16 v[38:41], v[162:165], v[186:189], v[38:41]
	v_mfma_f32_16x16x32_bf16 v[34:37], v[170:173], v[186:189], v[34:37]
	v_mfma_f32_16x16x32_bf16 v[22:25], v[162:165], v[194:197], v[22:25]
	v_mfma_f32_16x16x32_bf16 v[18:21], v[170:173], v[194:197], v[18:21]
	v_mfma_f32_16x16x32_bf16 v[6:9], v[162:165], v[212:215], v[6:9]
	v_mfma_f32_16x16x32_bf16 v[2:5], v[170:173], v[212:215], v[2:5]
	s_setprio 0
	s_barrier
	s_add_i32 s36, s36, 2
	s_cmp_gt_u32 s36, 29
	s_mov_b32 s37, s41

.LBB0_615:
	s_lshl_b32 s12, s40, 20
	s_and_b64 s[48:49], s[4:5], exec
	s_cselect_b32 s43, s12, s46
	s_lshl_b32 s13, s39, 20
	s_and_b64 s[48:49], s[4:5], exec
	s_cselect_b32 s44, s13, s45
	v_add_u32_e32 v130, s46, v139
	v_add_u32_e32 v131, s46, v140
	s_addk_i32 s45, 0x100
	s_addk_i32 s46, 0x100
	s_mov_b32 s47, -2
	v_add_u32_e32 v154, s17, v137
	v_add_u32_e32 v170, s20, v137
	ds_read_b128 v[142:145], v154
	ds_read_b128 v[146:149], v154 offset:1024
	ds_read_b128 v[150:153], v154 offset:2048
	ds_read_b128 v[154:157], v154 offset:3072
	ds_read_b128 v[158:161], v170
	ds_read_b128 v[162:165], v170 offset:1024
	ds_read_b128 v[166:169], v170 offset:2048
	ds_read_b128 v[170:173], v170 offset:3072
	s_cmp_eq_u32 s47, 28
	s_cselect_b32 s50, s43, s46
	s_cselect_b32 s49, s44, s45
	s_or_b32 s48, s50, 0x80
	s_add_i32 m0, s23, 0xc000
	ds_read_b128 v[174:177], v141
	ds_read_b128 v[178:181], v141 offset:1024
	ds_read_b128 v[182:185], v141 offset:2048
	ds_read_b128 v[186:189], v141 offset:3072
	ds_read_b128 v[190:193], v141 offset:4096
	ds_read_b128 v[194:197], v141 offset:5120
	ds_read_b128 v[198:201], v141 offset:6144
	ds_read_b128 v[204:207], v141 offset:7168
	global_load_lds_dwordx4 v131, s[0:1]
	s_add_i32 m0, s23, 0xe000
	s_nop 0
	global_load_lds_dwordx4 v130, s[0:1]
	s_waitcnt vmcnt(8)
	s_waitcnt lgkmcnt(0)
	s_setprio 1
	s_barrier
	v_mfma_f32_16x16x32_bf16 v[126:129], v[142:145], v[174:177], 0
	v_mfma_f32_16x16x32_bf16 v[122:125], v[150:153], v[174:177], 0
	v_mfma_f32_16x16x32_bf16 v[118:121], v[142:145], v[182:185], 0
	v_mfma_f32_16x16x32_bf16 v[110:113], v[150:153], v[182:185], 0
	v_mfma_f32_16x16x32_bf16 v[102:105], v[142:145], v[190:193], 0
	v_mfma_f32_16x16x32_bf16 v[94:97], v[150:153], v[190:193], 0
	v_mfma_f32_16x16x32_bf16 v[86:89], v[142:145], v[198:201], 0
	v_mfma_f32_16x16x32_bf16 v[78:81], v[150:153], v[198:201], 0
	v_mfma_f32_16x16x32_bf16 v[126:129], v[146:149], v[178:181], v[126:129]
	v_mfma_f32_16x16x32_bf16 v[122:125], v[154:157], v[178:181], v[122:125]
	v_mfma_f32_16x16x32_bf16 v[118:121], v[146:149], v[186:189], v[118:121]
	v_mfma_f32_16x16x32_bf16 v[110:113], v[154:157], v[186:189], v[110:113]
	v_mfma_f32_16x16x32_bf16 v[102:105], v[146:149], v[194:197], v[102:105]
	v_mfma_f32_16x16x32_bf16 v[94:97], v[154:157], v[194:197], v[94:97]
	v_mfma_f32_16x16x32_bf16 v[86:89], v[146:149], v[204:207], v[86:89]
	v_mfma_f32_16x16x32_bf16 v[78:81], v[154:157], v[204:207], v[78:81]
	s_setprio 0
	s_setprio 1
	v_mfma_f32_16x16x32_bf16 v[114:117], v[158:161], v[174:177], 0
	v_mfma_f32_16x16x32_bf16 v[106:109], v[166:169], v[174:177], 0
	v_mfma_f32_16x16x32_bf16 v[98:101], v[158:161], v[182:185], 0
	v_mfma_f32_16x16x32_bf16 v[90:93], v[166:169], v[182:185], 0
	v_mfma_f32_16x16x32_bf16 v[82:85], v[158:161], v[190:193], 0
	v_mfma_f32_16x16x32_bf16 v[74:77], v[166:169], v[190:193], 0
	v_mfma_f32_16x16x32_bf16 v[70:73], v[158:161], v[198:201], 0
	v_mfma_f32_16x16x32_bf16 v[66:69], v[166:169], v[198:201], 0
	v_mfma_f32_16x16x32_bf16 v[114:117], v[162:165], v[178:181], v[114:117]
	v_mfma_f32_16x16x32_bf16 v[106:109], v[170:173], v[178:181], v[106:109]
	v_mfma_f32_16x16x32_bf16 v[98:101], v[162:165], v[186:189], v[98:101]
	v_mfma_f32_16x16x32_bf16 v[90:93], v[170:173], v[186:189], v[90:93]
	v_mfma_f32_16x16x32_bf16 v[82:85], v[162:165], v[194:197], v[82:85]
	v_mfma_f32_16x16x32_bf16 v[74:77], v[170:173], v[194:197], v[74:77]
	v_mfma_f32_16x16x32_bf16 v[70:73], v[162:165], v[204:207], v[70:73]
	v_mfma_f32_16x16x32_bf16 v[66:69], v[170:173], v[204:207], v[66:69]
	s_setprio 0
	s_barrier
	s_mov_b32 m0, s18
	v_add_u32_e32 v202, s49, v133
	ds_read_b128 v[174:177], v141 offset:16384
	ds_read_b128 v[178:181], v141 offset:17408
	ds_read_b128 v[182:185], v141 offset:18432
	ds_read_b128 v[186:189], v141 offset:19456
	ds_read_b128 v[190:193], v141 offset:20480
	ds_read_b128 v[194:197], v141 offset:21504
	ds_read_b128 v[198:201], v141 offset:22528
	ds_read_b128 v[204:207], v141 offset:23552
	global_load_lds_dwordx4 v202, s[2:3]
	v_add_u32_e32 v202, s49, v135
	s_mov_b32 m0, s19
	s_add_i32 s51, s49, 0x80000
	global_load_lds_dwordx4 v202, s[2:3]
	v_add_u32_e32 v202, s51, v133
	s_mov_b32 m0, s21
	s_nop 0
	global_load_lds_dwordx4 v202, s[2:3]
	v_add_u32_e32 v202, s51, v135
	s_mov_b32 m0, s22
	s_nop 0
	global_load_lds_dwordx4 v202, s[2:3]
	v_add_u32_e32 v202, s50, v132
	s_mov_b32 m0, s23
	s_nop 0
	global_load_lds_dwordx4 v202, s[0:1]
	v_add_u32_e32 v202, s50, v134
	s_mov_b32 m0, s24
	s_nop 0
	global_load_lds_dwordx4 v202, s[0:1]
	s_waitcnt vmcnt(8)
	s_waitcnt lgkmcnt(0)
	s_setprio 1
	s_barrier
	v_mfma_f32_16x16x32_bf16 v[62:65], v[142:145], v[174:177], 0
	v_mfma_f32_16x16x32_bf16 v[58:61], v[150:153], v[174:177], 0
	v_mfma_f32_16x16x32_bf16 v[54:57], v[142:145], v[182:185], 0
	v_mfma_f32_16x16x32_bf16 v[46:49], v[150:153], v[182:185], 0
	v_mfma_f32_16x16x32_bf16 v[38:41], v[142:145], v[190:193], 0
	v_mfma_f32_16x16x32_bf16 v[30:33], v[150:153], v[190:193], 0
	v_mfma_f32_16x16x32_bf16 v[22:25], v[142:145], v[198:201], 0
	v_mfma_f32_16x16x32_bf16 v[14:17], v[150:153], v[198:201], 0
	v_mfma_f32_16x16x32_bf16 v[62:65], v[146:149], v[178:181], v[62:65]
	v_mfma_f32_16x16x32_bf16 v[58:61], v[154:157], v[178:181], v[58:61]
	v_mfma_f32_16x16x32_bf16 v[54:57], v[146:149], v[186:189], v[54:57]
	v_mfma_f32_16x16x32_bf16 v[46:49], v[154:157], v[186:189], v[46:49]
	v_mfma_f32_16x16x32_bf16 v[38:41], v[146:149], v[194:197], v[38:41]
	v_mfma_f32_16x16x32_bf16 v[30:33], v[154:157], v[194:197], v[30:33]
	v_mfma_f32_16x16x32_bf16 v[22:25], v[146:149], v[204:207], v[22:25]
	v_mfma_f32_16x16x32_bf16 v[14:17], v[154:157], v[204:207], v[14:17]
	s_setprio 0
	s_setprio 1
	v_mfma_f32_16x16x32_bf16 v[50:53], v[158:161], v[174:177], 0
	v_mfma_f32_16x16x32_bf16 v[42:45], v[166:169], v[174:177], 0
	v_mfma_f32_16x16x32_bf16 v[34:37], v[158:161], v[182:185], 0
	v_mfma_f32_16x16x32_bf16 v[26:29], v[166:169], v[182:185], 0
	v_mfma_f32_16x16x32_bf16 v[18:21], v[158:161], v[190:193], 0
	v_mfma_f32_16x16x32_bf16 v[10:13], v[166:169], v[190:193], 0
	v_mfma_f32_16x16x32_bf16 v[6:9], v[158:161], v[198:201], 0
	v_mfma_f32_16x16x32_bf16 v[2:5], v[166:169], v[198:201], 0
	v_mfma_f32_16x16x32_bf16 v[50:53], v[162:165], v[178:181], v[50:53]
	v_mfma_f32_16x16x32_bf16 v[42:45], v[170:173], v[178:181], v[42:45]
	v_mfma_f32_16x16x32_bf16 v[34:37], v[162:165], v[186:189], v[34:37]
	v_mfma_f32_16x16x32_bf16 v[26:29], v[170:173], v[186:189], v[26:29]
	v_mfma_f32_16x16x32_bf16 v[18:21], v[162:165], v[194:197], v[18:21]
	v_mfma_f32_16x16x32_bf16 v[10:13], v[170:173], v[194:197], v[10:13]
	v_mfma_f32_16x16x32_bf16 v[6:9], v[162:165], v[204:207], v[6:9]
	v_mfma_f32_16x16x32_bf16 v[2:5], v[170:173], v[204:207], v[2:5]
	s_setprio 0
	s_barrier
	v_add_u32_e32 v154, s27, v137
	v_add_u32_e32 v170, s34, v137
	ds_read_b128 v[142:145], v154
	ds_read_b128 v[146:149], v154 offset:1024
	ds_read_b128 v[150:153], v154 offset:2048
	ds_read_b128 v[154:157], v154 offset:3072
	ds_read_b128 v[158:161], v170
	ds_read_b128 v[162:165], v170 offset:1024
	ds_read_b128 v[166:169], v170 offset:2048
	ds_read_b128 v[170:173], v170 offset:3072
	s_add_i32 s50, s50, 0x80000
	s_mov_b32 m0, s25
	v_add_u32_e32 v202, s50, v132
	ds_read_b128 v[174:177], v141 offset:32768
	ds_read_b128 v[178:181], v141 offset:33792
	ds_read_b128 v[182:185], v141 offset:34816
	ds_read_b128 v[186:189], v141 offset:35840
	ds_read_b128 v[190:193], v141 offset:36864
	ds_read_b128 v[194:197], v141 offset:37888
	ds_read_b128 v[198:201], v141 offset:38912
	ds_read_b128 v[204:207], v141 offset:39936
	global_load_lds_dwordx4 v202, s[0:1]
	v_add_u32_e32 v202, s50, v134
	s_mov_b32 m0, s26
	s_nop 0
	global_load_lds_dwordx4 v202, s[0:1]
	s_waitcnt vmcnt(8)
	s_waitcnt lgkmcnt(0)
	s_setprio 1
	s_barrier
	v_mfma_f32_16x16x32_bf16 v[126:129], v[142:145], v[174:177], v[126:129]
	v_mfma_f32_16x16x32_bf16 v[122:125], v[150:153], v[174:177], v[122:125]
	v_mfma_f32_16x16x32_bf16 v[118:121], v[142:145], v[182:185], v[118:121]
	v_mfma_f32_16x16x32_bf16 v[110:113], v[150:153], v[182:185], v[110:113]
	v_mfma_f32_16x16x32_bf16 v[102:105], v[142:145], v[190:193], v[102:105]
	v_mfma_f32_16x16x32_bf16 v[94:97], v[150:153], v[190:193], v[94:97]
	v_mfma_f32_16x16x32_bf16 v[86:89], v[142:145], v[198:201], v[86:89]
	v_mfma_f32_16x16x32_bf16 v[78:81], v[150:153], v[198:201], v[78:81]
	v_mfma_f32_16x16x32_bf16 v[126:129], v[146:149], v[178:181], v[126:129]
	v_mfma_f32_16x16x32_bf16 v[122:125], v[154:157], v[178:181], v[122:125]
	v_mfma_f32_16x16x32_bf16 v[118:121], v[146:149], v[186:189], v[118:121]
	v_mfma_f32_16x16x32_bf16 v[110:113], v[154:157], v[186:189], v[110:113]
	v_mfma_f32_16x16x32_bf16 v[102:105], v[146:149], v[194:197], v[102:105]
	v_mfma_f32_16x16x32_bf16 v[94:97], v[154:157], v[194:197], v[94:97]
	v_mfma_f32_16x16x32_bf16 v[86:89], v[146:149], v[204:207], v[86:89]
	v_mfma_f32_16x16x32_bf16 v[78:81], v[154:157], v[204:207], v[78:81]
	s_setprio 0
	s_setprio 1
	v_mfma_f32_16x16x32_bf16 v[114:117], v[158:161], v[174:177], v[114:117]
	v_mfma_f32_16x16x32_bf16 v[106:109], v[166:169], v[174:177], v[106:109]
	v_mfma_f32_16x16x32_bf16 v[98:101], v[158:161], v[182:185], v[98:101]
	v_mfma_f32_16x16x32_bf16 v[90:93], v[166:169], v[182:185], v[90:93]
	v_mfma_f32_16x16x32_bf16 v[82:85], v[158:161], v[190:193], v[82:85]
	v_mfma_f32_16x16x32_bf16 v[74:77], v[166:169], v[190:193], v[74:77]
	v_mfma_f32_16x16x32_bf16 v[70:73], v[158:161], v[198:201], v[70:73]
	v_mfma_f32_16x16x32_bf16 v[66:69], v[166:169], v[198:201], v[66:69]
	v_mfma_f32_16x16x32_bf16 v[114:117], v[162:165], v[178:181], v[114:117]
	v_mfma_f32_16x16x32_bf16 v[106:109], v[170:173], v[178:181], v[106:109]
	v_mfma_f32_16x16x32_bf16 v[98:101], v[162:165], v[186:189], v[98:101]
	v_mfma_f32_16x16x32_bf16 v[90:93], v[170:173], v[186:189], v[90:93]
	v_mfma_f32_16x16x32_bf16 v[82:85], v[162:165], v[194:197], v[82:85]
	v_mfma_f32_16x16x32_bf16 v[74:77], v[170:173], v[194:197], v[74:77]
	v_mfma_f32_16x16x32_bf16 v[70:73], v[162:165], v[204:207], v[70:73]
	v_mfma_f32_16x16x32_bf16 v[66:69], v[170:173], v[204:207], v[66:69]
	s_setprio 0
	s_barrier
	s_or_b32 s50, s49, 0x80
	s_mov_b32 m0, s28
	v_add_u32_e32 v202, s50, v133
	ds_read_b128 v[174:177], v141 offset:49152
	ds_read_b128 v[178:181], v141 offset:50176
	ds_read_b128 v[182:185], v141 offset:51200
	ds_read_b128 v[186:189], v141 offset:52224
	ds_read_b128 v[190:193], v141 offset:53248
	ds_read_b128 v[194:197], v141 offset:54272
	ds_read_b128 v[198:201], v141 offset:55296
	ds_read_b128 v[204:207], v141 offset:56320
	global_load_lds_dwordx4 v202, s[2:3]
	v_add_u32_e32 v202, s50, v135
	s_mov_b32 m0, s29
	s_add_i32 s49, s49, 0x80080
	global_load_lds_dwordx4 v202, s[2:3]
	v_add_u32_e32 v202, s49, v133
	s_mov_b32 m0, s35
	s_nop 0
	global_load_lds_dwordx4 v202, s[2:3]
	v_add_u32_e32 v202, s49, v135
	s_mov_b32 m0, s36
	s_nop 0
	global_load_lds_dwordx4 v202, s[2:3]
	v_add_u32_e32 v202, s48, v132
	s_mov_b32 m0, s30
	s_nop 0
	global_load_lds_dwordx4 v202, s[0:1]
	v_add_u32_e32 v202, s48, v134
	s_mov_b32 m0, s31
	s_nop 0
	global_load_lds_dwordx4 v202, s[0:1]
	s_waitcnt vmcnt(8)
	s_waitcnt lgkmcnt(0)
	s_setprio 1
	s_barrier
	v_mfma_f32_16x16x32_bf16 v[62:65], v[142:145], v[174:177], v[62:65]
	v_mfma_f32_16x16x32_bf16 v[58:61], v[150:153], v[174:177], v[58:61]
	v_mfma_f32_16x16x32_bf16 v[54:57], v[142:145], v[182:185], v[54:57]
	v_mfma_f32_16x16x32_bf16 v[46:49], v[150:153], v[182:185], v[46:49]
	v_mfma_f32_16x16x32_bf16 v[38:41], v[142:145], v[190:193], v[38:41]
	v_mfma_f32_16x16x32_bf16 v[30:33], v[150:153], v[190:193], v[30:33]
	v_mfma_f32_16x16x32_bf16 v[22:25], v[142:145], v[198:201], v[22:25]
	v_mfma_f32_16x16x32_bf16 v[14:17], v[150:153], v[198:201], v[14:17]
	v_mfma_f32_16x16x32_bf16 v[62:65], v[146:149], v[178:181], v[62:65]
	v_mfma_f32_16x16x32_bf16 v[58:61], v[154:157], v[178:181], v[58:61]
	v_mfma_f32_16x16x32_bf16 v[54:57], v[146:149], v[186:189], v[54:57]
	v_mfma_f32_16x16x32_bf16 v[46:49], v[154:157], v[186:189], v[46:49]
	v_mfma_f32_16x16x32_bf16 v[38:41], v[146:149], v[194:197], v[38:41]
	v_mfma_f32_16x16x32_bf16 v[30:33], v[154:157], v[194:197], v[30:33]
	v_mfma_f32_16x16x32_bf16 v[22:25], v[146:149], v[204:207], v[22:25]
	v_mfma_f32_16x16x32_bf16 v[14:17], v[154:157], v[204:207], v[14:17]
	s_setprio 0
	s_setprio 1
	v_mfma_f32_16x16x32_bf16 v[50:53], v[158:161], v[174:177], v[50:53]
	v_mfma_f32_16x16x32_bf16 v[42:45], v[166:169], v[174:177], v[42:45]
	v_mfma_f32_16x16x32_bf16 v[34:37], v[158:161], v[182:185], v[34:37]
	v_mfma_f32_16x16x32_bf16 v[26:29], v[166:169], v[182:185], v[26:29]
	v_mfma_f32_16x16x32_bf16 v[18:21], v[158:161], v[190:193], v[18:21]
	v_mfma_f32_16x16x32_bf16 v[10:13], v[166:169], v[190:193], v[10:13]
	v_mfma_f32_16x16x32_bf16 v[6:9], v[158:161], v[198:201], v[6:9]
	v_mfma_f32_16x16x32_bf16 v[2:5], v[166:169], v[198:201], v[2:5]
	v_mfma_f32_16x16x32_bf16 v[50:53], v[162:165], v[178:181], v[50:53]
	v_mfma_f32_16x16x32_bf16 v[42:45], v[170:173], v[178:181], v[42:45]
	v_mfma_f32_16x16x32_bf16 v[34:37], v[162:165], v[186:189], v[34:37]
	v_mfma_f32_16x16x32_bf16 v[26:29], v[170:173], v[186:189], v[26:29]
	v_mfma_f32_16x16x32_bf16 v[18:21], v[162:165], v[194:197], v[18:21]
	v_mfma_f32_16x16x32_bf16 v[10:13], v[170:173], v[194:197], v[10:13]
	v_mfma_f32_16x16x32_bf16 v[6:9], v[162:165], v[204:207], v[6:9]
	v_mfma_f32_16x16x32_bf16 v[2:5], v[170:173], v[204:207], v[2:5]
	s_setprio 0
	s_barrier
	s_add_i32 s47, s47, 2
	s_addk_i32 s45, 0x100
	s_addk_i32 s46, 0x100
	v_add_u32_e32 v130, 0x100, v130
	s_cmp_gt_u32 s47, 29
	v_add_u32_e32 v131, 0x100, v131
.LBB0_616:
	v_add_u32_e32 v154, s17, v137
	v_add_u32_e32 v170, s20, v137
	ds_read_b128 v[142:145], v154
	ds_read_b128 v[146:149], v154 offset:1024
	ds_read_b128 v[150:153], v154 offset:2048
	ds_read_b128 v[154:157], v154 offset:3072
	ds_read_b128 v[158:161], v170
	ds_read_b128 v[162:165], v170 offset:1024
	ds_read_b128 v[166:169], v170 offset:2048
	ds_read_b128 v[170:173], v170 offset:3072
	s_cmp_eq_u32 s47, 28
	s_cselect_b32 s50, s43, s46
	s_cselect_b32 s49, s44, s45
	s_or_b32 s48, s50, 0x80
	s_add_i32 m0, s23, 0xc000
	ds_read_b128 v[174:177], v141
	ds_read_b128 v[178:181], v141 offset:1024
	ds_read_b128 v[182:185], v141 offset:2048
	ds_read_b128 v[186:189], v141 offset:3072
	ds_read_b128 v[190:193], v141 offset:4096
	ds_read_b128 v[194:197], v141 offset:5120
	ds_read_b128 v[198:201], v141 offset:6144
	ds_read_b128 v[204:207], v141 offset:7168
	global_load_lds_dwordx4 v131, s[0:1]
	s_add_i32 m0, s23, 0xe000
	s_nop 0
	global_load_lds_dwordx4 v130, s[0:1]
	s_waitcnt vmcnt(8)
	s_waitcnt lgkmcnt(0)
	s_setprio 1
	s_barrier
	v_mfma_f32_16x16x32_bf16 v[126:129], v[142:145], v[174:177], v[126:129]
	v_mfma_f32_16x16x32_bf16 v[122:125], v[150:153], v[174:177], v[122:125]
	v_mfma_f32_16x16x32_bf16 v[118:121], v[142:145], v[182:185], v[118:121]
	v_mfma_f32_16x16x32_bf16 v[110:113], v[150:153], v[182:185], v[110:113]
	v_mfma_f32_16x16x32_bf16 v[102:105], v[142:145], v[190:193], v[102:105]
	v_mfma_f32_16x16x32_bf16 v[94:97], v[150:153], v[190:193], v[94:97]
	v_mfma_f32_16x16x32_bf16 v[86:89], v[142:145], v[198:201], v[86:89]
	v_mfma_f32_16x16x32_bf16 v[78:81], v[150:153], v[198:201], v[78:81]
	v_mfma_f32_16x16x32_bf16 v[126:129], v[146:149], v[178:181], v[126:129]
	v_mfma_f32_16x16x32_bf16 v[122:125], v[154:157], v[178:181], v[122:125]
	v_mfma_f32_16x16x32_bf16 v[118:121], v[146:149], v[186:189], v[118:121]
	v_mfma_f32_16x16x32_bf16 v[110:113], v[154:157], v[186:189], v[110:113]
	v_mfma_f32_16x16x32_bf16 v[102:105], v[146:149], v[194:197], v[102:105]
	v_mfma_f32_16x16x32_bf16 v[94:97], v[154:157], v[194:197], v[94:97]
	v_mfma_f32_16x16x32_bf16 v[86:89], v[146:149], v[204:207], v[86:89]
	v_mfma_f32_16x16x32_bf16 v[78:81], v[154:157], v[204:207], v[78:81]
	s_setprio 0
	s_setprio 1
	v_mfma_f32_16x16x32_bf16 v[114:117], v[158:161], v[174:177], v[114:117]
	v_mfma_f32_16x16x32_bf16 v[106:109], v[166:169], v[174:177], v[106:109]
	v_mfma_f32_16x16x32_bf16 v[98:101], v[158:161], v[182:185], v[98:101]
	v_mfma_f32_16x16x32_bf16 v[90:93], v[166:169], v[182:185], v[90:93]
	v_mfma_f32_16x16x32_bf16 v[82:85], v[158:161], v[190:193], v[82:85]
	v_mfma_f32_16x16x32_bf16 v[74:77], v[166:169], v[190:193], v[74:77]
	v_mfma_f32_16x16x32_bf16 v[70:73], v[158:161], v[198:201], v[70:73]
	v_mfma_f32_16x16x32_bf16 v[66:69], v[166:169], v[198:201], v[66:69]
	v_mfma_f32_16x16x32_bf16 v[114:117], v[162:165], v[178:181], v[114:117]
	v_mfma_f32_16x16x32_bf16 v[106:109], v[170:173], v[178:181], v[106:109]
	v_mfma_f32_16x16x32_bf16 v[98:101], v[162:165], v[186:189], v[98:101]
	v_mfma_f32_16x16x32_bf16 v[90:93], v[170:173], v[186:189], v[90:93]
	v_mfma_f32_16x16x32_bf16 v[82:85], v[162:165], v[194:197], v[82:85]
	v_mfma_f32_16x16x32_bf16 v[74:77], v[170:173], v[194:197], v[74:77]
	v_mfma_f32_16x16x32_bf16 v[70:73], v[162:165], v[204:207], v[70:73]
	v_mfma_f32_16x16x32_bf16 v[66:69], v[170:173], v[204:207], v[66:69]
	s_setprio 0
	s_barrier
	s_mov_b32 m0, s18
	v_add_u32_e32 v202, s49, v133
	ds_read_b128 v[174:177], v141 offset:16384
	ds_read_b128 v[178:181], v141 offset:17408
	ds_read_b128 v[182:185], v141 offset:18432
	ds_read_b128 v[186:189], v141 offset:19456
	ds_read_b128 v[190:193], v141 offset:20480
	ds_read_b128 v[194:197], v141 offset:21504
	ds_read_b128 v[198:201], v141 offset:22528
	ds_read_b128 v[204:207], v141 offset:23552
	global_load_lds_dwordx4 v202, s[2:3]
	v_add_u32_e32 v202, s49, v135
	s_mov_b32 m0, s19
	s_add_i32 s51, s49, 0x80000
	global_load_lds_dwordx4 v202, s[2:3]
	v_add_u32_e32 v202, s51, v133
	s_mov_b32 m0, s21
	s_nop 0
	global_load_lds_dwordx4 v202, s[2:3]
	v_add_u32_e32 v202, s51, v135
	s_mov_b32 m0, s22
	s_nop 0
	global_load_lds_dwordx4 v202, s[2:3]
	v_add_u32_e32 v202, s50, v132
	s_mov_b32 m0, s23
	s_nop 0
	global_load_lds_dwordx4 v202, s[0:1]
	v_add_u32_e32 v202, s50, v134
	s_mov_b32 m0, s24
	s_nop 0
	global_load_lds_dwordx4 v202, s[0:1]
	s_waitcnt vmcnt(8)
	s_waitcnt lgkmcnt(0)
	s_setprio 1
	s_barrier
	v_mfma_f32_16x16x32_bf16 v[62:65], v[142:145], v[174:177], v[62:65]
	v_mfma_f32_16x16x32_bf16 v[58:61], v[150:153], v[174:177], v[58:61]
	v_mfma_f32_16x16x32_bf16 v[54:57], v[142:145], v[182:185], v[54:57]
	v_mfma_f32_16x16x32_bf16 v[46:49], v[150:153], v[182:185], v[46:49]
	v_mfma_f32_16x16x32_bf16 v[38:41], v[142:145], v[190:193], v[38:41]
	v_mfma_f32_16x16x32_bf16 v[30:33], v[150:153], v[190:193], v[30:33]
	v_mfma_f32_16x16x32_bf16 v[22:25], v[142:145], v[198:201], v[22:25]
	v_mfma_f32_16x16x32_bf16 v[14:17], v[150:153], v[198:201], v[14:17]
	v_mfma_f32_16x16x32_bf16 v[62:65], v[146:149], v[178:181], v[62:65]
	v_mfma_f32_16x16x32_bf16 v[58:61], v[154:157], v[178:181], v[58:61]
	v_mfma_f32_16x16x32_bf16 v[54:57], v[146:149], v[186:189], v[54:57]
	v_mfma_f32_16x16x32_bf16 v[46:49], v[154:157], v[186:189], v[46:49]
	v_mfma_f32_16x16x32_bf16 v[38:41], v[146:149], v[194:197], v[38:41]
	v_mfma_f32_16x16x32_bf16 v[30:33], v[154:157], v[194:197], v[30:33]
	v_mfma_f32_16x16x32_bf16 v[22:25], v[146:149], v[204:207], v[22:25]
	v_mfma_f32_16x16x32_bf16 v[14:17], v[154:157], v[204:207], v[14:17]
	s_setprio 0
	s_setprio 1
	v_mfma_f32_16x16x32_bf16 v[50:53], v[158:161], v[174:177], v[50:53]
	v_mfma_f32_16x16x32_bf16 v[42:45], v[166:169], v[174:177], v[42:45]
	v_mfma_f32_16x16x32_bf16 v[34:37], v[158:161], v[182:185], v[34:37]
	v_mfma_f32_16x16x32_bf16 v[26:29], v[166:169], v[182:185], v[26:29]
	v_mfma_f32_16x16x32_bf16 v[18:21], v[158:161], v[190:193], v[18:21]
	v_mfma_f32_16x16x32_bf16 v[10:13], v[166:169], v[190:193], v[10:13]
	v_mfma_f32_16x16x32_bf16 v[6:9], v[158:161], v[198:201], v[6:9]
	v_mfma_f32_16x16x32_bf16 v[2:5], v[166:169], v[198:201], v[2:5]
	v_mfma_f32_16x16x32_bf16 v[50:53], v[162:165], v[178:181], v[50:53]
	v_mfma_f32_16x16x32_bf16 v[42:45], v[170:173], v[178:181], v[42:45]
	v_mfma_f32_16x16x32_bf16 v[34:37], v[162:165], v[186:189], v[34:37]
	v_mfma_f32_16x16x32_bf16 v[26:29], v[170:173], v[186:189], v[26:29]
	v_mfma_f32_16x16x32_bf16 v[18:21], v[162:165], v[194:197], v[18:21]
	v_mfma_f32_16x16x32_bf16 v[10:13], v[170:173], v[194:197], v[10:13]
	v_mfma_f32_16x16x32_bf16 v[6:9], v[162:165], v[204:207], v[6:9]
	v_mfma_f32_16x16x32_bf16 v[2:5], v[170:173], v[204:207], v[2:5]
	s_setprio 0
	s_barrier
	v_add_u32_e32 v154, s27, v137
	v_add_u32_e32 v170, s34, v137
	ds_read_b128 v[142:145], v154
	ds_read_b128 v[146:149], v154 offset:1024
	ds_read_b128 v[150:153], v154 offset:2048
	ds_read_b128 v[154:157], v154 offset:3072
	ds_read_b128 v[158:161], v170
	ds_read_b128 v[162:165], v170 offset:1024
	ds_read_b128 v[166:169], v170 offset:2048
	ds_read_b128 v[170:173], v170 offset:3072
	s_add_i32 s50, s50, 0x80000
	s_mov_b32 m0, s25
	v_add_u32_e32 v202, s50, v132
	ds_read_b128 v[174:177], v141 offset:32768
	ds_read_b128 v[178:181], v141 offset:33792
	ds_read_b128 v[182:185], v141 offset:34816
	ds_read_b128 v[186:189], v141 offset:35840
	ds_read_b128 v[190:193], v141 offset:36864
	ds_read_b128 v[194:197], v141 offset:37888
	ds_read_b128 v[198:201], v141 offset:38912
	ds_read_b128 v[204:207], v141 offset:39936
	global_load_lds_dwordx4 v202, s[0:1]
	v_add_u32_e32 v202, s50, v134
	s_mov_b32 m0, s26
	s_nop 0
	global_load_lds_dwordx4 v202, s[0:1]
	s_waitcnt vmcnt(8)
	s_waitcnt lgkmcnt(0)
	s_setprio 1
	s_barrier
	v_mfma_f32_16x16x32_bf16 v[126:129], v[142:145], v[174:177], v[126:129]
	v_mfma_f32_16x16x32_bf16 v[122:125], v[150:153], v[174:177], v[122:125]
	v_mfma_f32_16x16x32_bf16 v[118:121], v[142:145], v[182:185], v[118:121]
	v_mfma_f32_16x16x32_bf16 v[110:113], v[150:153], v[182:185], v[110:113]
	v_mfma_f32_16x16x32_bf16 v[102:105], v[142:145], v[190:193], v[102:105]
	v_mfma_f32_16x16x32_bf16 v[94:97], v[150:153], v[190:193], v[94:97]
	v_mfma_f32_16x16x32_bf16 v[86:89], v[142:145], v[198:201], v[86:89]
	v_mfma_f32_16x16x32_bf16 v[78:81], v[150:153], v[198:201], v[78:81]
	v_mfma_f32_16x16x32_bf16 v[126:129], v[146:149], v[178:181], v[126:129]
	v_mfma_f32_16x16x32_bf16 v[122:125], v[154:157], v[178:181], v[122:125]
	v_mfma_f32_16x16x32_bf16 v[118:121], v[146:149], v[186:189], v[118:121]
	v_mfma_f32_16x16x32_bf16 v[110:113], v[154:157], v[186:189], v[110:113]
	v_mfma_f32_16x16x32_bf16 v[102:105], v[146:149], v[194:197], v[102:105]
	v_mfma_f32_16x16x32_bf16 v[94:97], v[154:157], v[194:197], v[94:97]
	v_mfma_f32_16x16x32_bf16 v[86:89], v[146:149], v[204:207], v[86:89]
	v_mfma_f32_16x16x32_bf16 v[78:81], v[154:157], v[204:207], v[78:81]
	s_setprio 0
	s_setprio 1
	v_mfma_f32_16x16x32_bf16 v[114:117], v[158:161], v[174:177], v[114:117]
	v_mfma_f32_16x16x32_bf16 v[106:109], v[166:169], v[174:177], v[106:109]
	v_mfma_f32_16x16x32_bf16 v[98:101], v[158:161], v[182:185], v[98:101]
	v_mfma_f32_16x16x32_bf16 v[90:93], v[166:169], v[182:185], v[90:93]
	v_mfma_f32_16x16x32_bf16 v[82:85], v[158:161], v[190:193], v[82:85]
	v_mfma_f32_16x16x32_bf16 v[74:77], v[166:169], v[190:193], v[74:77]
	v_mfma_f32_16x16x32_bf16 v[70:73], v[158:161], v[198:201], v[70:73]
	v_mfma_f32_16x16x32_bf16 v[66:69], v[166:169], v[198:201], v[66:69]
	v_mfma_f32_16x16x32_bf16 v[114:117], v[162:165], v[178:181], v[114:117]
	v_mfma_f32_16x16x32_bf16 v[106:109], v[170:173], v[178:181], v[106:109]
	v_mfma_f32_16x16x32_bf16 v[98:101], v[162:165], v[186:189], v[98:101]
	v_mfma_f32_16x16x32_bf16 v[90:93], v[170:173], v[186:189], v[90:93]
	v_mfma_f32_16x16x32_bf16 v[82:85], v[162:165], v[194:197], v[82:85]
	v_mfma_f32_16x16x32_bf16 v[74:77], v[170:173], v[194:197], v[74:77]
	v_mfma_f32_16x16x32_bf16 v[70:73], v[162:165], v[204:207], v[70:73]
	v_mfma_f32_16x16x32_bf16 v[66:69], v[170:173], v[204:207], v[66:69]
	s_setprio 0
	s_barrier
	s_or_b32 s50, s49, 0x80
	s_mov_b32 m0, s28
	v_add_u32_e32 v202, s50, v133
	ds_read_b128 v[174:177], v141 offset:49152
	ds_read_b128 v[178:181], v141 offset:50176
	ds_read_b128 v[182:185], v141 offset:51200
	ds_read_b128 v[186:189], v141 offset:52224
	ds_read_b128 v[190:193], v141 offset:53248
	ds_read_b128 v[194:197], v141 offset:54272
	ds_read_b128 v[198:201], v141 offset:55296
	ds_read_b128 v[204:207], v141 offset:56320
	global_load_lds_dwordx4 v202, s[2:3]
	v_add_u32_e32 v202, s50, v135
	s_mov_b32 m0, s29
	s_add_i32 s49, s49, 0x80080
	global_load_lds_dwordx4 v202, s[2:3]
	v_add_u32_e32 v202, s49, v133
	s_mov_b32 m0, s35
	s_nop 0
	global_load_lds_dwordx4 v202, s[2:3]
	v_add_u32_e32 v202, s49, v135
	s_mov_b32 m0, s36
	s_nop 0
	global_load_lds_dwordx4 v202, s[2:3]
	v_add_u32_e32 v202, s48, v132
	s_mov_b32 m0, s30
	s_nop 0
	global_load_lds_dwordx4 v202, s[0:1]
	v_add_u32_e32 v202, s48, v134
	s_mov_b32 m0, s31
	s_nop 0
	global_load_lds_dwordx4 v202, s[0:1]
	s_add_i32 s47, s47, 2
	s_addk_i32 s45, 0x100
	s_addk_i32 s46, 0x100
	v_add_u32_e32 v130, 0x100, v130
	s_cmp_gt_u32 s47, 29
	v_add_u32_e32 v131, 0x100, v131
	s_waitcnt vmcnt(8)
	s_waitcnt lgkmcnt(0)
	s_setprio 1
	s_barrier
	v_mfma_f32_16x16x32_bf16 v[62:65], v[142:145], v[174:177], v[62:65]
	v_mfma_f32_16x16x32_bf16 v[58:61], v[150:153], v[174:177], v[58:61]
	v_mfma_f32_16x16x32_bf16 v[54:57], v[142:145], v[182:185], v[54:57]
	v_mfma_f32_16x16x32_bf16 v[46:49], v[150:153], v[182:185], v[46:49]
	v_mfma_f32_16x16x32_bf16 v[38:41], v[142:145], v[190:193], v[38:41]
	v_mfma_f32_16x16x32_bf16 v[30:33], v[150:153], v[190:193], v[30:33]
	v_mfma_f32_16x16x32_bf16 v[22:25], v[142:145], v[198:201], v[22:25]
	v_mfma_f32_16x16x32_bf16 v[14:17], v[150:153], v[198:201], v[14:17]
	v_mfma_f32_16x16x32_bf16 v[62:65], v[146:149], v[178:181], v[62:65]
	v_mfma_f32_16x16x32_bf16 v[58:61], v[154:157], v[178:181], v[58:61]
	v_mfma_f32_16x16x32_bf16 v[54:57], v[146:149], v[186:189], v[54:57]
	v_mfma_f32_16x16x32_bf16 v[46:49], v[154:157], v[186:189], v[46:49]
	v_mfma_f32_16x16x32_bf16 v[38:41], v[146:149], v[194:197], v[38:41]
	v_mfma_f32_16x16x32_bf16 v[30:33], v[154:157], v[194:197], v[30:33]
	v_mfma_f32_16x16x32_bf16 v[22:25], v[146:149], v[204:207], v[22:25]
	v_mfma_f32_16x16x32_bf16 v[14:17], v[154:157], v[204:207], v[14:17]
	s_setprio 0
	s_setprio 1
	v_mfma_f32_16x16x32_bf16 v[50:53], v[158:161], v[174:177], v[50:53]
	v_mfma_f32_16x16x32_bf16 v[42:45], v[166:169], v[174:177], v[42:45]
	v_mfma_f32_16x16x32_bf16 v[34:37], v[158:161], v[182:185], v[34:37]
	v_mfma_f32_16x16x32_bf16 v[26:29], v[166:169], v[182:185], v[26:29]
	v_mfma_f32_16x16x32_bf16 v[18:21], v[158:161], v[190:193], v[18:21]
	v_mfma_f32_16x16x32_bf16 v[10:13], v[166:169], v[190:193], v[10:13]
	v_mfma_f32_16x16x32_bf16 v[6:9], v[158:161], v[198:201], v[6:9]
	v_mfma_f32_16x16x32_bf16 v[2:5], v[166:169], v[198:201], v[2:5]
	v_mfma_f32_16x16x32_bf16 v[50:53], v[162:165], v[178:181], v[50:53]
	v_mfma_f32_16x16x32_bf16 v[42:45], v[170:173], v[178:181], v[42:45]
	v_mfma_f32_16x16x32_bf16 v[34:37], v[162:165], v[186:189], v[34:37]
	v_mfma_f32_16x16x32_bf16 v[26:29], v[170:173], v[186:189], v[26:29]
	v_mfma_f32_16x16x32_bf16 v[18:21], v[162:165], v[194:197], v[18:21]
	v_mfma_f32_16x16x32_bf16 v[10:13], v[170:173], v[194:197], v[10:13]
	v_mfma_f32_16x16x32_bf16 v[6:9], v[162:165], v[204:207], v[6:9]
	v_mfma_f32_16x16x32_bf16 v[2:5], v[170:173], v[204:207], v[2:5]
	s_setprio 0
	s_barrier
	s_cbranch_scc0 .LBB0_616
	s_and_b64 vcc, exec, s[10:11]
	s_cbranch_vccz .LBB0_619
	s_barrier

.LBB0_703:
	s_lshl_b32 s26, s20, 20
	s_and_b64 s[54:55], s[22:23], exec
	s_cselect_b32 s54, s26, s57
	s_lshl_b32 s27, s52, 20
	s_and_b64 s[58:59], s[22:23], exec
	s_cselect_b32 s55, s27, s56
	v_add_u32_e32 v132, s57, v144
	v_add_u32_e32 v133, s57, v145
	s_addk_i32 s56, 0x100
	s_addk_i32 s57, 0x100
	s_mov_b32 s58, -2
	v_add_u32_e32 v134, s25, v141
	ds_read_b128 v[148:151], v134
	ds_read_b128 v[152:155], v134 offset:1024
	ds_read_b128 v[156:159], v134 offset:2048
	ds_read_b128 v[160:163], v134 offset:3072
	v_add_u32_e32 v134, s34, v141
	ds_read_b128 v[164:167], v134
	ds_read_b128 v[168:171], v134 offset:1024
	ds_read_b128 v[172:175], v134 offset:2048
	ds_read_b128 v[176:179], v134 offset:3072
	s_cmp_eq_u32 s58, 28
	s_cselect_b32 s61, s54, s57
	s_cselect_b32 s60, s55, s56
	s_or_b32 s59, s61, 0x80
	s_add_i32 m0, s37, 0xc000
	ds_read_b128 v[180:183], v146
	ds_read_b128 v[184:187], v146 offset:1024
	ds_read_b128 v[188:191], v146 offset:2048
	ds_read_b128 v[192:195], v146 offset:3072
	ds_read_b128 v[196:199], v146 offset:4096
	ds_read_b128 v[204:207], v146 offset:5120
	ds_read_b128 v[212:215], v146 offset:6144
	ds_read_b128 v[218:221], v146 offset:7168
	global_load_lds_dwordx4 v133, s[4:5]
	s_add_i32 m0, s37, 0xe000
	s_nop 0
	global_load_lds_dwordx4 v132, s[4:5]
	s_waitcnt vmcnt(8)
	s_waitcnt lgkmcnt(0)
	s_setprio 1
	s_barrier
	v_mfma_f32_16x16x32_bf16 v[126:129], v[148:151], v[180:183], 0
	v_mfma_f32_16x16x32_bf16 v[122:125], v[156:159], v[180:183], 0
	v_mfma_f32_16x16x32_bf16 v[110:113], v[148:151], v[188:191], 0
	v_mfma_f32_16x16x32_bf16 v[106:109], v[156:159], v[188:191], 0
	v_mfma_f32_16x16x32_bf16 v[94:97], v[148:151], v[196:199], 0
	v_mfma_f32_16x16x32_bf16 v[90:93], v[156:159], v[196:199], 0
	v_mfma_f32_16x16x32_bf16 v[78:81], v[148:151], v[212:215], 0
	v_mfma_f32_16x16x32_bf16 v[74:77], v[156:159], v[212:215], 0
	v_mfma_f32_16x16x32_bf16 v[126:129], v[152:155], v[184:187], v[126:129]
	v_mfma_f32_16x16x32_bf16 v[122:125], v[160:163], v[184:187], v[122:125]
	v_mfma_f32_16x16x32_bf16 v[110:113], v[152:155], v[192:195], v[110:113]
	v_mfma_f32_16x16x32_bf16 v[106:109], v[160:163], v[192:195], v[106:109]
	v_mfma_f32_16x16x32_bf16 v[94:97], v[152:155], v[204:207], v[94:97]
	v_mfma_f32_16x16x32_bf16 v[90:93], v[160:163], v[204:207], v[90:93]
	v_mfma_f32_16x16x32_bf16 v[78:81], v[152:155], v[218:221], v[78:81]
	v_mfma_f32_16x16x32_bf16 v[74:77], v[160:163], v[218:221], v[74:77]
	s_setprio 0
	s_setprio 1
	v_mfma_f32_16x16x32_bf16 v[118:121], v[164:167], v[180:183], 0
	v_mfma_f32_16x16x32_bf16 v[114:117], v[172:175], v[180:183], 0
	v_mfma_f32_16x16x32_bf16 v[102:105], v[164:167], v[188:191], 0
	v_mfma_f32_16x16x32_bf16 v[98:101], v[172:175], v[188:191], 0
	v_mfma_f32_16x16x32_bf16 v[86:89], v[164:167], v[196:199], 0
	v_mfma_f32_16x16x32_bf16 v[82:85], v[172:175], v[196:199], 0
	v_mfma_f32_16x16x32_bf16 v[70:73], v[164:167], v[212:215], 0
	v_mfma_f32_16x16x32_bf16 v[66:69], v[172:175], v[212:215], 0
	v_mfma_f32_16x16x32_bf16 v[118:121], v[168:171], v[184:187], v[118:121]
	v_mfma_f32_16x16x32_bf16 v[114:117], v[176:179], v[184:187], v[114:117]
	v_mfma_f32_16x16x32_bf16 v[102:105], v[168:171], v[192:195], v[102:105]
	v_mfma_f32_16x16x32_bf16 v[98:101], v[176:179], v[192:195], v[98:101]
	v_mfma_f32_16x16x32_bf16 v[86:89], v[168:171], v[204:207], v[86:89]
	v_mfma_f32_16x16x32_bf16 v[82:85], v[176:179], v[204:207], v[82:85]
	v_mfma_f32_16x16x32_bf16 v[70:73], v[168:171], v[218:221], v[70:73]
	v_mfma_f32_16x16x32_bf16 v[66:69], v[176:179], v[218:221], v[66:69]
	s_setprio 0
	s_barrier
	s_mov_b32 m0, s30
	v_add_u32_e32 v134, s60, v137
	ds_read_b128 v[180:183], v146 offset:16384
	ds_read_b128 v[184:187], v146 offset:17408
	ds_read_b128 v[188:191], v146 offset:18432
	ds_read_b128 v[192:195], v146 offset:19456
	ds_read_b128 v[196:199], v146 offset:20480
	ds_read_b128 v[204:207], v146 offset:21504
	ds_read_b128 v[212:215], v146 offset:22528
	ds_read_b128 v[218:221], v146 offset:23552
	global_load_lds_dwordx4 v134, s[6:7]
	v_add_u32_e32 v134, s60, v139
	s_mov_b32 m0, s31
	s_add_i32 s62, s60, 0x80000
	global_load_lds_dwordx4 v134, s[6:7]
	v_add_u32_e32 v134, s62, v137
	s_mov_b32 m0, s35
	s_nop 0
	global_load_lds_dwordx4 v134, s[6:7]
	v_add_u32_e32 v134, s62, v139
	s_mov_b32 m0, s36
	s_nop 0
	global_load_lds_dwordx4 v134, s[6:7]
	v_add_u32_e32 v134, s61, v136
	s_mov_b32 m0, s37
	s_nop 0
	global_load_lds_dwordx4 v134, s[4:5]
	v_add_u32_e32 v134, s61, v138
	s_mov_b32 m0, s38
	s_nop 0
	global_load_lds_dwordx4 v134, s[4:5]
	s_waitcnt vmcnt(8)
	s_waitcnt lgkmcnt(0)
	s_setprio 1
	s_barrier
	v_mfma_f32_16x16x32_bf16 v[62:65], v[148:151], v[180:183], 0
	v_mfma_f32_16x16x32_bf16 v[58:61], v[156:159], v[180:183], 0
	v_mfma_f32_16x16x32_bf16 v[46:49], v[148:151], v[188:191], 0
	v_mfma_f32_16x16x32_bf16 v[42:45], v[156:159], v[188:191], 0
	v_mfma_f32_16x16x32_bf16 v[30:33], v[148:151], v[196:199], 0
	v_mfma_f32_16x16x32_bf16 v[26:29], v[156:159], v[196:199], 0
	v_mfma_f32_16x16x32_bf16 v[14:17], v[148:151], v[212:215], 0
	v_mfma_f32_16x16x32_bf16 v[10:13], v[156:159], v[212:215], 0
	v_mfma_f32_16x16x32_bf16 v[62:65], v[152:155], v[184:187], v[62:65]
	v_mfma_f32_16x16x32_bf16 v[58:61], v[160:163], v[184:187], v[58:61]
	v_mfma_f32_16x16x32_bf16 v[46:49], v[152:155], v[192:195], v[46:49]
	v_mfma_f32_16x16x32_bf16 v[42:45], v[160:163], v[192:195], v[42:45]
	v_mfma_f32_16x16x32_bf16 v[30:33], v[152:155], v[204:207], v[30:33]
	v_mfma_f32_16x16x32_bf16 v[26:29], v[160:163], v[204:207], v[26:29]
	v_mfma_f32_16x16x32_bf16 v[14:17], v[152:155], v[218:221], v[14:17]
	v_mfma_f32_16x16x32_bf16 v[10:13], v[160:163], v[218:221], v[10:13]
	s_setprio 0
	s_setprio 1
	v_mfma_f32_16x16x32_bf16 v[54:57], v[164:167], v[180:183], 0
	v_mfma_f32_16x16x32_bf16 v[50:53], v[172:175], v[180:183], 0
	v_mfma_f32_16x16x32_bf16 v[38:41], v[164:167], v[188:191], 0
	v_mfma_f32_16x16x32_bf16 v[34:37], v[172:175], v[188:191], 0
	v_mfma_f32_16x16x32_bf16 v[22:25], v[164:167], v[196:199], 0
	v_mfma_f32_16x16x32_bf16 v[18:21], v[172:175], v[196:199], 0
	v_mfma_f32_16x16x32_bf16 v[6:9], v[164:167], v[212:215], 0
	v_mfma_f32_16x16x32_bf16 v[2:5], v[172:175], v[212:215], 0
	v_mfma_f32_16x16x32_bf16 v[54:57], v[168:171], v[184:187], v[54:57]
	v_mfma_f32_16x16x32_bf16 v[50:53], v[176:179], v[184:187], v[50:53]
	v_mfma_f32_16x16x32_bf16 v[38:41], v[168:171], v[192:195], v[38:41]
	v_mfma_f32_16x16x32_bf16 v[34:37], v[176:179], v[192:195], v[34:37]
	v_mfma_f32_16x16x32_bf16 v[22:25], v[168:171], v[204:207], v[22:25]
	v_mfma_f32_16x16x32_bf16 v[18:21], v[176:179], v[204:207], v[18:21]
	v_mfma_f32_16x16x32_bf16 v[6:9], v[168:171], v[218:221], v[6:9]
	v_mfma_f32_16x16x32_bf16 v[2:5], v[176:179], v[218:221], v[2:5]
	s_setprio 0
	s_barrier
	v_add_u32_e32 v134, s41, v141
	ds_read_b128 v[148:151], v134
	ds_read_b128 v[152:155], v134 offset:1024
	ds_read_b128 v[156:159], v134 offset:2048
	ds_read_b128 v[160:163], v134 offset:3072
	v_add_u32_e32 v134, s46, v141
	ds_read_b128 v[164:167], v134
	ds_read_b128 v[168:171], v134 offset:1024
	ds_read_b128 v[172:175], v134 offset:2048
	ds_read_b128 v[176:179], v134 offset:3072
	s_add_i32 s61, s61, 0x80000
	s_mov_b32 m0, s39
	v_add_u32_e32 v134, s61, v136
	ds_read_b128 v[180:183], v146 offset:32768
	ds_read_b128 v[184:187], v146 offset:33792
	ds_read_b128 v[188:191], v146 offset:34816
	ds_read_b128 v[192:195], v146 offset:35840
	ds_read_b128 v[196:199], v146 offset:36864
	ds_read_b128 v[204:207], v146 offset:37888
	ds_read_b128 v[212:215], v146 offset:38912
	ds_read_b128 v[218:221], v146 offset:39936
	global_load_lds_dwordx4 v134, s[4:5]
	v_add_u32_e32 v134, s61, v138
	s_mov_b32 m0, s40
	s_nop 0
	global_load_lds_dwordx4 v134, s[4:5]
	s_waitcnt vmcnt(8)
	s_waitcnt lgkmcnt(0)
	s_setprio 1
	s_barrier
	v_mfma_f32_16x16x32_bf16 v[126:129], v[148:151], v[180:183], v[126:129]
	v_mfma_f32_16x16x32_bf16 v[122:125], v[156:159], v[180:183], v[122:125]
	v_mfma_f32_16x16x32_bf16 v[110:113], v[148:151], v[188:191], v[110:113]
	v_mfma_f32_16x16x32_bf16 v[106:109], v[156:159], v[188:191], v[106:109]
	v_mfma_f32_16x16x32_bf16 v[94:97], v[148:151], v[196:199], v[94:97]
	v_mfma_f32_16x16x32_bf16 v[90:93], v[156:159], v[196:199], v[90:93]
	v_mfma_f32_16x16x32_bf16 v[78:81], v[148:151], v[212:215], v[78:81]
	v_mfma_f32_16x16x32_bf16 v[74:77], v[156:159], v[212:215], v[74:77]
	v_mfma_f32_16x16x32_bf16 v[126:129], v[152:155], v[184:187], v[126:129]
	v_mfma_f32_16x16x32_bf16 v[122:125], v[160:163], v[184:187], v[122:125]
	v_mfma_f32_16x16x32_bf16 v[110:113], v[152:155], v[192:195], v[110:113]
	v_mfma_f32_16x16x32_bf16 v[106:109], v[160:163], v[192:195], v[106:109]
	v_mfma_f32_16x16x32_bf16 v[94:97], v[152:155], v[204:207], v[94:97]
	v_mfma_f32_16x16x32_bf16 v[90:93], v[160:163], v[204:207], v[90:93]
	v_mfma_f32_16x16x32_bf16 v[78:81], v[152:155], v[218:221], v[78:81]
	v_mfma_f32_16x16x32_bf16 v[74:77], v[160:163], v[218:221], v[74:77]
	s_setprio 0
	s_setprio 1
	v_mfma_f32_16x16x32_bf16 v[118:121], v[164:167], v[180:183], v[118:121]
	v_mfma_f32_16x16x32_bf16 v[114:117], v[172:175], v[180:183], v[114:117]
	v_mfma_f32_16x16x32_bf16 v[102:105], v[164:167], v[188:191], v[102:105]
	v_mfma_f32_16x16x32_bf16 v[98:101], v[172:175], v[188:191], v[98:101]
	v_mfma_f32_16x16x32_bf16 v[86:89], v[164:167], v[196:199], v[86:89]
	v_mfma_f32_16x16x32_bf16 v[82:85], v[172:175], v[196:199], v[82:85]
	v_mfma_f32_16x16x32_bf16 v[70:73], v[164:167], v[212:215], v[70:73]
	v_mfma_f32_16x16x32_bf16 v[66:69], v[172:175], v[212:215], v[66:69]
	v_mfma_f32_16x16x32_bf16 v[118:121], v[168:171], v[184:187], v[118:121]
	v_mfma_f32_16x16x32_bf16 v[114:117], v[176:179], v[184:187], v[114:117]
	v_mfma_f32_16x16x32_bf16 v[102:105], v[168:171], v[192:195], v[102:105]
	v_mfma_f32_16x16x32_bf16 v[98:101], v[176:179], v[192:195], v[98:101]
	v_mfma_f32_16x16x32_bf16 v[86:89], v[168:171], v[204:207], v[86:89]
	v_mfma_f32_16x16x32_bf16 v[82:85], v[176:179], v[204:207], v[82:85]
	v_mfma_f32_16x16x32_bf16 v[70:73], v[168:171], v[218:221], v[70:73]
	v_mfma_f32_16x16x32_bf16 v[66:69], v[176:179], v[218:221], v[66:69]
	s_setprio 0
	s_barrier
	s_or_b32 s61, s60, 0x80
	s_mov_b32 m0, s42
	v_add_u32_e32 v134, s61, v137
	ds_read_b128 v[180:183], v146 offset:49152
	ds_read_b128 v[184:187], v146 offset:50176
	ds_read_b128 v[188:191], v146 offset:51200
	ds_read_b128 v[192:195], v146 offset:52224
	ds_read_b128 v[196:199], v146 offset:53248
	ds_read_b128 v[204:207], v146 offset:54272
	ds_read_b128 v[212:215], v146 offset:55296
	ds_read_b128 v[218:221], v146 offset:56320
	global_load_lds_dwordx4 v134, s[6:7]
	v_add_u32_e32 v134, s61, v139
	s_mov_b32 m0, s43
	s_add_i32 s60, s60, 0x80080
	global_load_lds_dwordx4 v134, s[6:7]
	v_add_u32_e32 v134, s60, v137
	s_mov_b32 m0, s47
	s_nop 0
	global_load_lds_dwordx4 v134, s[6:7]
	v_add_u32_e32 v134, s60, v139
	s_mov_b32 m0, s48
	s_nop 0
	global_load_lds_dwordx4 v134, s[6:7]
	v_add_u32_e32 v134, s59, v136
	s_mov_b32 m0, s44
	s_nop 0
	global_load_lds_dwordx4 v134, s[4:5]
	v_add_u32_e32 v134, s59, v138
	s_mov_b32 m0, s45
	s_nop 0
	global_load_lds_dwordx4 v134, s[4:5]
	s_waitcnt vmcnt(8)
	s_waitcnt lgkmcnt(0)
	s_setprio 1
	s_barrier
	v_mfma_f32_16x16x32_bf16 v[62:65], v[148:151], v[180:183], v[62:65]
	v_mfma_f32_16x16x32_bf16 v[58:61], v[156:159], v[180:183], v[58:61]
	v_mfma_f32_16x16x32_bf16 v[46:49], v[148:151], v[188:191], v[46:49]
	v_mfma_f32_16x16x32_bf16 v[42:45], v[156:159], v[188:191], v[42:45]
	v_mfma_f32_16x16x32_bf16 v[30:33], v[148:151], v[196:199], v[30:33]
	v_mfma_f32_16x16x32_bf16 v[26:29], v[156:159], v[196:199], v[26:29]
	v_mfma_f32_16x16x32_bf16 v[14:17], v[148:151], v[212:215], v[14:17]
	v_mfma_f32_16x16x32_bf16 v[10:13], v[156:159], v[212:215], v[10:13]
	v_mfma_f32_16x16x32_bf16 v[62:65], v[152:155], v[184:187], v[62:65]
	v_mfma_f32_16x16x32_bf16 v[58:61], v[160:163], v[184:187], v[58:61]
	v_mfma_f32_16x16x32_bf16 v[46:49], v[152:155], v[192:195], v[46:49]
	v_mfma_f32_16x16x32_bf16 v[42:45], v[160:163], v[192:195], v[42:45]
	v_mfma_f32_16x16x32_bf16 v[30:33], v[152:155], v[204:207], v[30:33]
	v_mfma_f32_16x16x32_bf16 v[26:29], v[160:163], v[204:207], v[26:29]
	v_mfma_f32_16x16x32_bf16 v[14:17], v[152:155], v[218:221], v[14:17]
	v_mfma_f32_16x16x32_bf16 v[10:13], v[160:163], v[218:221], v[10:13]
	s_setprio 0
	s_setprio 1
	v_mfma_f32_16x16x32_bf16 v[54:57], v[164:167], v[180:183], v[54:57]
	v_mfma_f32_16x16x32_bf16 v[50:53], v[172:175], v[180:183], v[50:53]
	v_mfma_f32_16x16x32_bf16 v[38:41], v[164:167], v[188:191], v[38:41]
	v_mfma_f32_16x16x32_bf16 v[34:37], v[172:175], v[188:191], v[34:37]
	v_mfma_f32_16x16x32_bf16 v[22:25], v[164:167], v[196:199], v[22:25]
	v_mfma_f32_16x16x32_bf16 v[18:21], v[172:175], v[196:199], v[18:21]
	v_mfma_f32_16x16x32_bf16 v[6:9], v[164:167], v[212:215], v[6:9]
	v_mfma_f32_16x16x32_bf16 v[2:5], v[172:175], v[212:215], v[2:5]
	v_mfma_f32_16x16x32_bf16 v[54:57], v[168:171], v[184:187], v[54:57]
	v_mfma_f32_16x16x32_bf16 v[50:53], v[176:179], v[184:187], v[50:53]
	v_mfma_f32_16x16x32_bf16 v[38:41], v[168:171], v[192:195], v[38:41]
	v_mfma_f32_16x16x32_bf16 v[34:37], v[176:179], v[192:195], v[34:37]
	v_mfma_f32_16x16x32_bf16 v[22:25], v[168:171], v[204:207], v[22:25]
	v_mfma_f32_16x16x32_bf16 v[18:21], v[176:179], v[204:207], v[18:21]
	v_mfma_f32_16x16x32_bf16 v[6:9], v[168:171], v[218:221], v[6:9]
	v_mfma_f32_16x16x32_bf16 v[2:5], v[176:179], v[218:221], v[2:5]
	s_setprio 0
	s_barrier
	s_add_i32 s58, s58, 2
	s_addk_i32 s56, 0x100
	s_addk_i32 s57, 0x100
	v_add_u32_e32 v132, 0x100, v132
	s_cmp_gt_u32 s58, 29
	v_add_u32_e32 v133, 0x100, v133
.LBB0_704:
	v_add_u32_e32 v134, s25, v141
	ds_read_b128 v[148:151], v134
	ds_read_b128 v[152:155], v134 offset:1024
	ds_read_b128 v[156:159], v134 offset:2048
	ds_read_b128 v[160:163], v134 offset:3072
	v_add_u32_e32 v134, s34, v141
	ds_read_b128 v[164:167], v134
	ds_read_b128 v[168:171], v134 offset:1024
	ds_read_b128 v[172:175], v134 offset:2048
	ds_read_b128 v[176:179], v134 offset:3072
	s_cmp_eq_u32 s58, 28
	s_cselect_b32 s61, s54, s57
	s_cselect_b32 s60, s55, s56
	s_or_b32 s59, s61, 0x80
	s_add_i32 m0, s37, 0xc000
	ds_read_b128 v[180:183], v146
	ds_read_b128 v[184:187], v146 offset:1024
	ds_read_b128 v[188:191], v146 offset:2048
	ds_read_b128 v[192:195], v146 offset:3072
	ds_read_b128 v[196:199], v146 offset:4096
	ds_read_b128 v[204:207], v146 offset:5120
	ds_read_b128 v[212:215], v146 offset:6144
	ds_read_b128 v[218:221], v146 offset:7168
	global_load_lds_dwordx4 v133, s[4:5]
	s_add_i32 m0, s37, 0xe000
	s_nop 0
	global_load_lds_dwordx4 v132, s[4:5]
	s_waitcnt vmcnt(8)
	s_waitcnt lgkmcnt(0)
	s_setprio 1
	s_barrier
	v_mfma_f32_16x16x32_bf16 v[126:129], v[148:151], v[180:183], v[126:129]
	v_mfma_f32_16x16x32_bf16 v[122:125], v[156:159], v[180:183], v[122:125]
	v_mfma_f32_16x16x32_bf16 v[110:113], v[148:151], v[188:191], v[110:113]
	v_mfma_f32_16x16x32_bf16 v[106:109], v[156:159], v[188:191], v[106:109]
	v_mfma_f32_16x16x32_bf16 v[94:97], v[148:151], v[196:199], v[94:97]
	v_mfma_f32_16x16x32_bf16 v[90:93], v[156:159], v[196:199], v[90:93]
	v_mfma_f32_16x16x32_bf16 v[78:81], v[148:151], v[212:215], v[78:81]
	v_mfma_f32_16x16x32_bf16 v[74:77], v[156:159], v[212:215], v[74:77]
	v_mfma_f32_16x16x32_bf16 v[126:129], v[152:155], v[184:187], v[126:129]
	v_mfma_f32_16x16x32_bf16 v[122:125], v[160:163], v[184:187], v[122:125]
	v_mfma_f32_16x16x32_bf16 v[110:113], v[152:155], v[192:195], v[110:113]
	v_mfma_f32_16x16x32_bf16 v[106:109], v[160:163], v[192:195], v[106:109]
	v_mfma_f32_16x16x32_bf16 v[94:97], v[152:155], v[204:207], v[94:97]
	v_mfma_f32_16x16x32_bf16 v[90:93], v[160:163], v[204:207], v[90:93]
	v_mfma_f32_16x16x32_bf16 v[78:81], v[152:155], v[218:221], v[78:81]
	v_mfma_f32_16x16x32_bf16 v[74:77], v[160:163], v[218:221], v[74:77]
	s_setprio 0
	s_setprio 1
	v_mfma_f32_16x16x32_bf16 v[118:121], v[164:167], v[180:183], v[118:121]
	v_mfma_f32_16x16x32_bf16 v[114:117], v[172:175], v[180:183], v[114:117]
	v_mfma_f32_16x16x32_bf16 v[102:105], v[164:167], v[188:191], v[102:105]
	v_mfma_f32_16x16x32_bf16 v[98:101], v[172:175], v[188:191], v[98:101]
	v_mfma_f32_16x16x32_bf16 v[86:89], v[164:167], v[196:199], v[86:89]
	v_mfma_f32_16x16x32_bf16 v[82:85], v[172:175], v[196:199], v[82:85]
	v_mfma_f32_16x16x32_bf16 v[70:73], v[164:167], v[212:215], v[70:73]
	v_mfma_f32_16x16x32_bf16 v[66:69], v[172:175], v[212:215], v[66:69]
	v_mfma_f32_16x16x32_bf16 v[118:121], v[168:171], v[184:187], v[118:121]
	v_mfma_f32_16x16x32_bf16 v[114:117], v[176:179], v[184:187], v[114:117]
	v_mfma_f32_16x16x32_bf16 v[102:105], v[168:171], v[192:195], v[102:105]
	v_mfma_f32_16x16x32_bf16 v[98:101], v[176:179], v[192:195], v[98:101]
	v_mfma_f32_16x16x32_bf16 v[86:89], v[168:171], v[204:207], v[86:89]
	v_mfma_f32_16x16x32_bf16 v[82:85], v[176:179], v[204:207], v[82:85]
	v_mfma_f32_16x16x32_bf16 v[70:73], v[168:171], v[218:221], v[70:73]
	v_mfma_f32_16x16x32_bf16 v[66:69], v[176:179], v[218:221], v[66:69]
	s_setprio 0
	s_barrier
	s_mov_b32 m0, s30
	v_add_u32_e32 v134, s60, v137
	ds_read_b128 v[180:183], v146 offset:16384
	ds_read_b128 v[184:187], v146 offset:17408
	ds_read_b128 v[188:191], v146 offset:18432
	ds_read_b128 v[192:195], v146 offset:19456
	ds_read_b128 v[196:199], v146 offset:20480
	ds_read_b128 v[204:207], v146 offset:21504
	ds_read_b128 v[212:215], v146 offset:22528
	ds_read_b128 v[218:221], v146 offset:23552
	global_load_lds_dwordx4 v134, s[6:7]
	v_add_u32_e32 v134, s60, v139
	s_mov_b32 m0, s31
	s_add_i32 s62, s60, 0x80000
	global_load_lds_dwordx4 v134, s[6:7]
	v_add_u32_e32 v134, s62, v137
	s_mov_b32 m0, s35
	s_nop 0
	global_load_lds_dwordx4 v134, s[6:7]
	v_add_u32_e32 v134, s62, v139
	s_mov_b32 m0, s36
	s_nop 0
	global_load_lds_dwordx4 v134, s[6:7]
	v_add_u32_e32 v134, s61, v136
	s_mov_b32 m0, s37
	s_nop 0
	global_load_lds_dwordx4 v134, s[4:5]
	v_add_u32_e32 v134, s61, v138
	s_mov_b32 m0, s38
	s_nop 0
	global_load_lds_dwordx4 v134, s[4:5]
	s_waitcnt vmcnt(8)
	s_waitcnt lgkmcnt(0)
	s_setprio 1
	s_barrier
	v_mfma_f32_16x16x32_bf16 v[62:65], v[148:151], v[180:183], v[62:65]
	v_mfma_f32_16x16x32_bf16 v[58:61], v[156:159], v[180:183], v[58:61]
	v_mfma_f32_16x16x32_bf16 v[46:49], v[148:151], v[188:191], v[46:49]
	v_mfma_f32_16x16x32_bf16 v[42:45], v[156:159], v[188:191], v[42:45]
	v_mfma_f32_16x16x32_bf16 v[30:33], v[148:151], v[196:199], v[30:33]
	v_mfma_f32_16x16x32_bf16 v[26:29], v[156:159], v[196:199], v[26:29]
	v_mfma_f32_16x16x32_bf16 v[14:17], v[148:151], v[212:215], v[14:17]
	v_mfma_f32_16x16x32_bf16 v[10:13], v[156:159], v[212:215], v[10:13]
	v_mfma_f32_16x16x32_bf16 v[62:65], v[152:155], v[184:187], v[62:65]
	v_mfma_f32_16x16x32_bf16 v[58:61], v[160:163], v[184:187], v[58:61]
	v_mfma_f32_16x16x32_bf16 v[46:49], v[152:155], v[192:195], v[46:49]
	v_mfma_f32_16x16x32_bf16 v[42:45], v[160:163], v[192:195], v[42:45]
	v_mfma_f32_16x16x32_bf16 v[30:33], v[152:155], v[204:207], v[30:33]
	v_mfma_f32_16x16x32_bf16 v[26:29], v[160:163], v[204:207], v[26:29]
	v_mfma_f32_16x16x32_bf16 v[14:17], v[152:155], v[218:221], v[14:17]
	v_mfma_f32_16x16x32_bf16 v[10:13], v[160:163], v[218:221], v[10:13]
	s_setprio 0
	s_setprio 1
	v_mfma_f32_16x16x32_bf16 v[54:57], v[164:167], v[180:183], v[54:57]
	v_mfma_f32_16x16x32_bf16 v[50:53], v[172:175], v[180:183], v[50:53]
	v_mfma_f32_16x16x32_bf16 v[38:41], v[164:167], v[188:191], v[38:41]
	v_mfma_f32_16x16x32_bf16 v[34:37], v[172:175], v[188:191], v[34:37]
	v_mfma_f32_16x16x32_bf16 v[22:25], v[164:167], v[196:199], v[22:25]
	v_mfma_f32_16x16x32_bf16 v[18:21], v[172:175], v[196:199], v[18:21]
	v_mfma_f32_16x16x32_bf16 v[6:9], v[164:167], v[212:215], v[6:9]
	v_mfma_f32_16x16x32_bf16 v[2:5], v[172:175], v[212:215], v[2:5]
	v_mfma_f32_16x16x32_bf16 v[54:57], v[168:171], v[184:187], v[54:57]
	v_mfma_f32_16x16x32_bf16 v[50:53], v[176:179], v[184:187], v[50:53]
	v_mfma_f32_16x16x32_bf16 v[38:41], v[168:171], v[192:195], v[38:41]
	v_mfma_f32_16x16x32_bf16 v[34:37], v[176:179], v[192:195], v[34:37]
	v_mfma_f32_16x16x32_bf16 v[22:25], v[168:171], v[204:207], v[22:25]
	v_mfma_f32_16x16x32_bf16 v[18:21], v[176:179], v[204:207], v[18:21]
	v_mfma_f32_16x16x32_bf16 v[6:9], v[168:171], v[218:221], v[6:9]
	v_mfma_f32_16x16x32_bf16 v[2:5], v[176:179], v[218:221], v[2:5]
	s_setprio 0
	s_barrier
	v_add_u32_e32 v134, s41, v141
	ds_read_b128 v[148:151], v134
	ds_read_b128 v[152:155], v134 offset:1024
	ds_read_b128 v[156:159], v134 offset:2048
	ds_read_b128 v[160:163], v134 offset:3072
	v_add_u32_e32 v134, s46, v141
	ds_read_b128 v[164:167], v134
	ds_read_b128 v[168:171], v134 offset:1024
	ds_read_b128 v[172:175], v134 offset:2048
	ds_read_b128 v[176:179], v134 offset:3072
	s_add_i32 s61, s61, 0x80000
	s_mov_b32 m0, s39
	v_add_u32_e32 v134, s61, v136
	ds_read_b128 v[180:183], v146 offset:32768
	ds_read_b128 v[184:187], v146 offset:33792
	ds_read_b128 v[188:191], v146 offset:34816
	ds_read_b128 v[192:195], v146 offset:35840
	ds_read_b128 v[196:199], v146 offset:36864
	ds_read_b128 v[204:207], v146 offset:37888
	ds_read_b128 v[212:215], v146 offset:38912
	ds_read_b128 v[218:221], v146 offset:39936
	global_load_lds_dwordx4 v134, s[4:5]
	v_add_u32_e32 v134, s61, v138
	s_mov_b32 m0, s40
	s_nop 0
	global_load_lds_dwordx4 v134, s[4:5]
	s_waitcnt vmcnt(8)
	s_waitcnt lgkmcnt(0)
	s_setprio 1
	s_barrier
	v_mfma_f32_16x16x32_bf16 v[126:129], v[148:151], v[180:183], v[126:129]
	v_mfma_f32_16x16x32_bf16 v[122:125], v[156:159], v[180:183], v[122:125]
	v_mfma_f32_16x16x32_bf16 v[110:113], v[148:151], v[188:191], v[110:113]
	v_mfma_f32_16x16x32_bf16 v[106:109], v[156:159], v[188:191], v[106:109]
	v_mfma_f32_16x16x32_bf16 v[94:97], v[148:151], v[196:199], v[94:97]
	v_mfma_f32_16x16x32_bf16 v[90:93], v[156:159], v[196:199], v[90:93]
	v_mfma_f32_16x16x32_bf16 v[78:81], v[148:151], v[212:215], v[78:81]
	v_mfma_f32_16x16x32_bf16 v[74:77], v[156:159], v[212:215], v[74:77]
	v_mfma_f32_16x16x32_bf16 v[126:129], v[152:155], v[184:187], v[126:129]
	v_mfma_f32_16x16x32_bf16 v[122:125], v[160:163], v[184:187], v[122:125]
	v_mfma_f32_16x16x32_bf16 v[110:113], v[152:155], v[192:195], v[110:113]
	v_mfma_f32_16x16x32_bf16 v[106:109], v[160:163], v[192:195], v[106:109]
	v_mfma_f32_16x16x32_bf16 v[94:97], v[152:155], v[204:207], v[94:97]
	v_mfma_f32_16x16x32_bf16 v[90:93], v[160:163], v[204:207], v[90:93]
	v_mfma_f32_16x16x32_bf16 v[78:81], v[152:155], v[218:221], v[78:81]
	v_mfma_f32_16x16x32_bf16 v[74:77], v[160:163], v[218:221], v[74:77]
	s_setprio 0
	s_setprio 1
	v_mfma_f32_16x16x32_bf16 v[118:121], v[164:167], v[180:183], v[118:121]
	v_mfma_f32_16x16x32_bf16 v[114:117], v[172:175], v[180:183], v[114:117]
	v_mfma_f32_16x16x32_bf16 v[102:105], v[164:167], v[188:191], v[102:105]
	v_mfma_f32_16x16x32_bf16 v[98:101], v[172:175], v[188:191], v[98:101]
	v_mfma_f32_16x16x32_bf16 v[86:89], v[164:167], v[196:199], v[86:89]
	v_mfma_f32_16x16x32_bf16 v[82:85], v[172:175], v[196:199], v[82:85]
	v_mfma_f32_16x16x32_bf16 v[70:73], v[164:167], v[212:215], v[70:73]
	v_mfma_f32_16x16x32_bf16 v[66:69], v[172:175], v[212:215], v[66:69]
	v_mfma_f32_16x16x32_bf16 v[118:121], v[168:171], v[184:187], v[118:121]
	v_mfma_f32_16x16x32_bf16 v[114:117], v[176:179], v[184:187], v[114:117]
	v_mfma_f32_16x16x32_bf16 v[102:105], v[168:171], v[192:195], v[102:105]
	v_mfma_f32_16x16x32_bf16 v[98:101], v[176:179], v[192:195], v[98:101]
	v_mfma_f32_16x16x32_bf16 v[86:89], v[168:171], v[204:207], v[86:89]
	v_mfma_f32_16x16x32_bf16 v[82:85], v[176:179], v[204:207], v[82:85]
	v_mfma_f32_16x16x32_bf16 v[70:73], v[168:171], v[218:221], v[70:73]
	v_mfma_f32_16x16x32_bf16 v[66:69], v[176:179], v[218:221], v[66:69]
	s_setprio 0
	s_barrier
	s_or_b32 s61, s60, 0x80
	s_mov_b32 m0, s42
	v_add_u32_e32 v134, s61, v137
	ds_read_b128 v[180:183], v146 offset:49152
	ds_read_b128 v[184:187], v146 offset:50176
	ds_read_b128 v[188:191], v146 offset:51200
	ds_read_b128 v[192:195], v146 offset:52224
	ds_read_b128 v[196:199], v146 offset:53248
	ds_read_b128 v[204:207], v146 offset:54272
	ds_read_b128 v[212:215], v146 offset:55296
	ds_read_b128 v[218:221], v146 offset:56320
	global_load_lds_dwordx4 v134, s[6:7]
	v_add_u32_e32 v134, s61, v139
	s_mov_b32 m0, s43
	s_add_i32 s60, s60, 0x80080
	global_load_lds_dwordx4 v134, s[6:7]
	v_add_u32_e32 v134, s60, v137
	s_mov_b32 m0, s47
	s_nop 0
	global_load_lds_dwordx4 v134, s[6:7]
	v_add_u32_e32 v134, s60, v139
	s_mov_b32 m0, s48
	s_nop 0
	global_load_lds_dwordx4 v134, s[6:7]
	v_add_u32_e32 v134, s59, v136
	s_mov_b32 m0, s44
	s_nop 0
	global_load_lds_dwordx4 v134, s[4:5]
	v_add_u32_e32 v134, s59, v138
	s_mov_b32 m0, s45
	s_nop 0
	global_load_lds_dwordx4 v134, s[4:5]
	s_add_i32 s58, s58, 2
	s_addk_i32 s56, 0x100
	s_addk_i32 s57, 0x100
	v_add_u32_e32 v132, 0x100, v132
	s_cmp_gt_u32 s58, 29
	v_add_u32_e32 v133, 0x100, v133
	s_waitcnt vmcnt(8)
	s_waitcnt lgkmcnt(0)
	s_setprio 1
	s_barrier
	v_mfma_f32_16x16x32_bf16 v[62:65], v[148:151], v[180:183], v[62:65]
	v_mfma_f32_16x16x32_bf16 v[58:61], v[156:159], v[180:183], v[58:61]
	v_mfma_f32_16x16x32_bf16 v[46:49], v[148:151], v[188:191], v[46:49]
	v_mfma_f32_16x16x32_bf16 v[42:45], v[156:159], v[188:191], v[42:45]
	v_mfma_f32_16x16x32_bf16 v[30:33], v[148:151], v[196:199], v[30:33]
	v_mfma_f32_16x16x32_bf16 v[26:29], v[156:159], v[196:199], v[26:29]
	v_mfma_f32_16x16x32_bf16 v[14:17], v[148:151], v[212:215], v[14:17]
	v_mfma_f32_16x16x32_bf16 v[10:13], v[156:159], v[212:215], v[10:13]
	v_mfma_f32_16x16x32_bf16 v[62:65], v[152:155], v[184:187], v[62:65]
	v_mfma_f32_16x16x32_bf16 v[58:61], v[160:163], v[184:187], v[58:61]
	v_mfma_f32_16x16x32_bf16 v[46:49], v[152:155], v[192:195], v[46:49]
	v_mfma_f32_16x16x32_bf16 v[42:45], v[160:163], v[192:195], v[42:45]
	v_mfma_f32_16x16x32_bf16 v[30:33], v[152:155], v[204:207], v[30:33]
	v_mfma_f32_16x16x32_bf16 v[26:29], v[160:163], v[204:207], v[26:29]
	v_mfma_f32_16x16x32_bf16 v[14:17], v[152:155], v[218:221], v[14:17]
	v_mfma_f32_16x16x32_bf16 v[10:13], v[160:163], v[218:221], v[10:13]
	s_setprio 0
	s_setprio 1
	v_mfma_f32_16x16x32_bf16 v[54:57], v[164:167], v[180:183], v[54:57]
	v_mfma_f32_16x16x32_bf16 v[50:53], v[172:175], v[180:183], v[50:53]
	v_mfma_f32_16x16x32_bf16 v[38:41], v[164:167], v[188:191], v[38:41]
	v_mfma_f32_16x16x32_bf16 v[34:37], v[172:175], v[188:191], v[34:37]
	v_mfma_f32_16x16x32_bf16 v[22:25], v[164:167], v[196:199], v[22:25]
	v_mfma_f32_16x16x32_bf16 v[18:21], v[172:175], v[196:199], v[18:21]
	v_mfma_f32_16x16x32_bf16 v[6:9], v[164:167], v[212:215], v[6:9]
	v_mfma_f32_16x16x32_bf16 v[2:5], v[172:175], v[212:215], v[2:5]
	v_mfma_f32_16x16x32_bf16 v[54:57], v[168:171], v[184:187], v[54:57]
	v_mfma_f32_16x16x32_bf16 v[50:53], v[176:179], v[184:187], v[50:53]
	v_mfma_f32_16x16x32_bf16 v[38:41], v[168:171], v[192:195], v[38:41]
	v_mfma_f32_16x16x32_bf16 v[34:37], v[176:179], v[192:195], v[34:37]
	v_mfma_f32_16x16x32_bf16 v[22:25], v[168:171], v[204:207], v[22:25]
	v_mfma_f32_16x16x32_bf16 v[18:21], v[176:179], v[204:207], v[18:21]
	v_mfma_f32_16x16x32_bf16 v[6:9], v[168:171], v[218:221], v[6:9]
	v_mfma_f32_16x16x32_bf16 v[2:5], v[176:179], v[218:221], v[2:5]
	s_setprio 0
	s_barrier
	s_cbranch_scc0 .LBB0_704
	s_and_b64 vcc, exec, s[16:17]
	s_cbranch_vccz .LBB0_707
	s_barrier

.LBB0_724:
	v_lshrrev_b32_e32 v9, 1, v5
	v_and_b32_e32 v135, 24, v9
	v_and_b32_e32 v136, 15, v5
	v_lshlrev_b32_e32 v9, 1, v135
	v_lshlrev_b32_e32 v5, 2, v5
	s_lshl_b32 s27, s27, 5
	s_lshl_b32 s26, s29, 6
	v_lshl_or_b32 v9, v136, 6, v9
	s_lshl_b32 s29, s29, 13
	v_and_b32_e32 v5, 32, v5
	s_and_b32 s27, s27, 0x60
	v_bitop3_b32 v10, v9, s29, v5 bitop3:0xde
	s_lshl_b32 s29, s27, 7
	v_bitop3_b32 v137, v9, s29, v5 bitop3:0xde
	s_add_i32 s29, s28, 0x18000
	s_or_b32 s31, s12, 0x80
	s_add_i32 s30, s29, s37
	v_add_u32_e32 v5, s31, v131
	s_mov_b32 m0, s30
	s_waitcnt vmcnt(2)
	s_barrier
	global_load_lds_dwordx4 v5, s[6:7]
	v_add_u32_e32 v5, s31, v133
	s_add_i32 s31, s30, 0x2000
	s_mov_b32 m0, s31
	s_or_b32 s35, s21, 0x80
	s_add_i32 s34, s22, 0x8000
	global_load_lds_dwordx4 v5, s[6:7]
	v_add_u32_e32 v5, s35, v130
	s_mov_b32 m0, s34
	s_add_i32 s36, s28, 0x1c000
	global_load_lds_dwordx4 v5, s[4:5]
	v_add_u32_e32 v5, s35, v132
	s_add_i32 s35, s22, 0xa000
	s_mov_b32 m0, s35
	s_or_b32 s38, s12, 0x80080
	s_add_i32 s37, s36, s37
	global_load_lds_dwordx4 v5, s[4:5]
	v_add_u32_e32 v5, s38, v131
	s_mov_b32 m0, s37
	s_add_i32 s39, s21, 0x80080
	global_load_lds_dwordx4 v5, s[6:7]
	v_add_u32_e32 v5, s38, v133
	s_add_i32 s38, s37, 0x2000
	s_mov_b32 m0, s38
	v_lshlrev_b32_e32 v7, 12, v7
	global_load_lds_dwordx4 v5, s[6:7]
	v_lshlrev_b32_e32 v5, 15, v6
	v_and_b32_e32 v5, 0xffff0000, v5
	v_and_b32_e32 v6, 1, v6
	v_add3_u32 v5, s39, v5, v7
	v_lshlrev_b32_e32 v6, 6, v6
	v_lshlrev_b32_e32 v7, 1, v8
	v_add3_u32 v138, v5, v6, v7
	v_lshlrev_b32_e32 v5, 15, v2
	v_and_b32_e32 v5, 0xffff0000, v5
	v_lshlrev_b32_e32 v3, 12, v3
	v_and_b32_e32 v2, 1, v2
	s_waitcnt vmcnt(6)
	v_add3_u32 v3, s39, v5, v3
	v_lshlrev_b32_e32 v2, 6, v2
	v_lshlrev_b32_e32 v4, 1, v4
	v_add3_u32 v139, v3, v2, v4
	v_or_b32_e32 v134, s26, v136
	s_mov_b32 s39, -2
	s_mov_b32 s40, 0
	v_add_u32_e32 v140, s28, v10
	s_barrier
	v_add_u32_e32 v141, s13, v137
	ds_read_b128 v[142:145], v141
	ds_read_b128 v[146:149], v141 offset:1024
	ds_read_b128 v[150:153], v141 offset:2048
	ds_read_b128 v[154:157], v141 offset:3072
	v_add_u32_e32 v141, s16, v137
	ds_read_b128 v[158:161], v141
	ds_read_b128 v[162:165], v141 offset:1024
	ds_read_b128 v[166:169], v141 offset:2048
	ds_read_b128 v[170:173], v141 offset:3072
	s_add_i32 s41, s40, 0x100
	s_cmp_lg_u32 s39, 28
	s_cselect_b32 s43, s41, 0
	s_add_i32 s44, s43, s21
	s_or_b32 s42, s44, 0x80
	s_add_i32 s43, s43, s12
	v_add_u32_e32 v141, s40, v139
	s_add_i32 m0, s22, 0xc000
	ds_read_b128 v[174:177], v140
	ds_read_b128 v[178:181], v140 offset:1024
	ds_read_b128 v[182:185], v140 offset:2048
	ds_read_b128 v[186:189], v140 offset:3072
	ds_read_b128 v[190:193], v140 offset:4096
	ds_read_b128 v[194:197], v140 offset:5120
	ds_read_b128 v[198:201], v140 offset:6144
	ds_read_b128 v[204:207], v140 offset:7168
	global_load_lds_dwordx4 v141, s[4:5]
	v_add_u32_e32 v141, s40, v138
	s_add_i32 m0, s22, 0xe000
	s_nop 0
	global_load_lds_dwordx4 v141, s[4:5]
	s_waitcnt vmcnt(8)
	s_waitcnt lgkmcnt(0)
	s_setprio 1
	s_barrier
	v_mfma_f32_16x16x32_bf16 v[126:129], v[142:145], v[174:177], 0
	v_mfma_f32_16x16x32_bf16 v[122:125], v[150:153], v[174:177], 0
	v_mfma_f32_16x16x32_bf16 v[110:113], v[142:145], v[182:185], 0
	v_mfma_f32_16x16x32_bf16 v[106:109], v[150:153], v[182:185], 0
	v_mfma_f32_16x16x32_bf16 v[94:97], v[142:145], v[190:193], 0
	v_mfma_f32_16x16x32_bf16 v[90:93], v[150:153], v[190:193], 0
	v_mfma_f32_16x16x32_bf16 v[78:81], v[142:145], v[198:201], 0
	v_mfma_f32_16x16x32_bf16 v[74:77], v[150:153], v[198:201], 0
	v_mfma_f32_16x16x32_bf16 v[126:129], v[146:149], v[178:181], v[126:129]
	v_mfma_f32_16x16x32_bf16 v[122:125], v[154:157], v[178:181], v[122:125]
	v_mfma_f32_16x16x32_bf16 v[110:113], v[146:149], v[186:189], v[110:113]
	v_mfma_f32_16x16x32_bf16 v[106:109], v[154:157], v[186:189], v[106:109]
	v_mfma_f32_16x16x32_bf16 v[94:97], v[146:149], v[194:197], v[94:97]
	v_mfma_f32_16x16x32_bf16 v[90:93], v[154:157], v[194:197], v[90:93]
	v_mfma_f32_16x16x32_bf16 v[78:81], v[146:149], v[204:207], v[78:81]
	v_mfma_f32_16x16x32_bf16 v[74:77], v[154:157], v[204:207], v[74:77]
	s_setprio 0
	s_setprio 1
	v_mfma_f32_16x16x32_bf16 v[118:121], v[158:161], v[174:177], 0
	v_mfma_f32_16x16x32_bf16 v[114:117], v[166:169], v[174:177], 0
	v_mfma_f32_16x16x32_bf16 v[102:105], v[158:161], v[182:185], 0
	v_mfma_f32_16x16x32_bf16 v[98:101], v[166:169], v[182:185], 0
	v_mfma_f32_16x16x32_bf16 v[86:89], v[158:161], v[190:193], 0
	v_mfma_f32_16x16x32_bf16 v[82:85], v[166:169], v[190:193], 0
	v_mfma_f32_16x16x32_bf16 v[70:73], v[158:161], v[198:201], 0
	v_mfma_f32_16x16x32_bf16 v[66:69], v[166:169], v[198:201], 0
	v_mfma_f32_16x16x32_bf16 v[118:121], v[162:165], v[178:181], v[118:121]
	v_mfma_f32_16x16x32_bf16 v[114:117], v[170:173], v[178:181], v[114:117]
	v_mfma_f32_16x16x32_bf16 v[102:105], v[162:165], v[186:189], v[102:105]
	v_mfma_f32_16x16x32_bf16 v[98:101], v[170:173], v[186:189], v[98:101]
	v_mfma_f32_16x16x32_bf16 v[86:89], v[162:165], v[194:197], v[86:89]
	v_mfma_f32_16x16x32_bf16 v[82:85], v[170:173], v[194:197], v[82:85]
	v_mfma_f32_16x16x32_bf16 v[70:73], v[162:165], v[204:207], v[70:73]
	v_mfma_f32_16x16x32_bf16 v[66:69], v[170:173], v[204:207], v[66:69]
	s_setprio 0
	s_barrier
	s_mov_b32 m0, s14
	v_add_u32_e32 v141, s43, v131
	ds_read_b128 v[174:177], v140 offset:16384
	ds_read_b128 v[178:181], v140 offset:17408
	ds_read_b128 v[182:185], v140 offset:18432
	ds_read_b128 v[186:189], v140 offset:19456
	ds_read_b128 v[190:193], v140 offset:20480
	ds_read_b128 v[194:197], v140 offset:21504
	ds_read_b128 v[198:201], v140 offset:22528
	ds_read_b128 v[204:207], v140 offset:23552
	global_load_lds_dwordx4 v141, s[6:7]
	v_add_u32_e32 v141, s43, v133
	s_mov_b32 m0, s15
	s_add_i32 s40, s43, 0x80000
	global_load_lds_dwordx4 v141, s[6:7]
	v_add_u32_e32 v141, s40, v131
	s_mov_b32 m0, s17
	s_nop 0
	global_load_lds_dwordx4 v141, s[6:7]
	v_add_u32_e32 v141, s40, v133
	s_mov_b32 m0, s20
	s_nop 0
	global_load_lds_dwordx4 v141, s[6:7]
	v_add_u32_e32 v141, s44, v130
	s_mov_b32 m0, s22
	s_nop 0
	global_load_lds_dwordx4 v141, s[4:5]
	v_add_u32_e32 v141, s44, v132
	s_mov_b32 m0, s23
	s_nop 0
	global_load_lds_dwordx4 v141, s[4:5]
	s_waitcnt vmcnt(8)
	s_waitcnt lgkmcnt(0)
	s_setprio 1
	s_barrier
	v_mfma_f32_16x16x32_bf16 v[62:65], v[142:145], v[174:177], 0
	v_mfma_f32_16x16x32_bf16 v[58:61], v[150:153], v[174:177], 0
	v_mfma_f32_16x16x32_bf16 v[46:49], v[142:145], v[182:185], 0
	v_mfma_f32_16x16x32_bf16 v[42:45], v[150:153], v[182:185], 0
	v_mfma_f32_16x16x32_bf16 v[30:33], v[142:145], v[190:193], 0
	v_mfma_f32_16x16x32_bf16 v[26:29], v[150:153], v[190:193], 0
	v_mfma_f32_16x16x32_bf16 v[14:17], v[142:145], v[198:201], 0
	v_mfma_f32_16x16x32_bf16 v[10:13], v[150:153], v[198:201], 0
	v_mfma_f32_16x16x32_bf16 v[62:65], v[146:149], v[178:181], v[62:65]
	v_mfma_f32_16x16x32_bf16 v[58:61], v[154:157], v[178:181], v[58:61]
	v_mfma_f32_16x16x32_bf16 v[46:49], v[146:149], v[186:189], v[46:49]
	v_mfma_f32_16x16x32_bf16 v[42:45], v[154:157], v[186:189], v[42:45]
	v_mfma_f32_16x16x32_bf16 v[30:33], v[146:149], v[194:197], v[30:33]
	v_mfma_f32_16x16x32_bf16 v[26:29], v[154:157], v[194:197], v[26:29]
	v_mfma_f32_16x16x32_bf16 v[14:17], v[146:149], v[204:207], v[14:17]
	v_mfma_f32_16x16x32_bf16 v[10:13], v[154:157], v[204:207], v[10:13]
	s_setprio 0
	s_setprio 1
	v_mfma_f32_16x16x32_bf16 v[54:57], v[158:161], v[174:177], 0
	v_mfma_f32_16x16x32_bf16 v[50:53], v[166:169], v[174:177], 0
	v_mfma_f32_16x16x32_bf16 v[38:41], v[158:161], v[182:185], 0
	v_mfma_f32_16x16x32_bf16 v[34:37], v[166:169], v[182:185], 0
	v_mfma_f32_16x16x32_bf16 v[22:25], v[158:161], v[190:193], 0
	v_mfma_f32_16x16x32_bf16 v[18:21], v[166:169], v[190:193], 0
	v_mfma_f32_16x16x32_bf16 v[6:9], v[158:161], v[198:201], 0
	v_mfma_f32_16x16x32_bf16 v[2:5], v[166:169], v[198:201], 0
	v_mfma_f32_16x16x32_bf16 v[54:57], v[162:165], v[178:181], v[54:57]
	v_mfma_f32_16x16x32_bf16 v[50:53], v[170:173], v[178:181], v[50:53]
	v_mfma_f32_16x16x32_bf16 v[38:41], v[162:165], v[186:189], v[38:41]
	v_mfma_f32_16x16x32_bf16 v[34:37], v[170:173], v[186:189], v[34:37]
	v_mfma_f32_16x16x32_bf16 v[22:25], v[162:165], v[194:197], v[22:25]
	v_mfma_f32_16x16x32_bf16 v[18:21], v[170:173], v[194:197], v[18:21]
	v_mfma_f32_16x16x32_bf16 v[6:9], v[162:165], v[204:207], v[6:9]
	v_mfma_f32_16x16x32_bf16 v[2:5], v[170:173], v[204:207], v[2:5]
	s_setprio 0
	s_barrier
	v_add_u32_e32 v141, s29, v137
	ds_read_b128 v[142:145], v141
	ds_read_b128 v[146:149], v141 offset:1024
	ds_read_b128 v[150:153], v141 offset:2048
	ds_read_b128 v[154:157], v141 offset:3072
	v_add_u32_e32 v141, s36, v137
	ds_read_b128 v[158:161], v141
	ds_read_b128 v[162:165], v141 offset:1024
	ds_read_b128 v[166:169], v141 offset:2048
	ds_read_b128 v[170:173], v141 offset:3072
	s_add_i32 s44, s44, 0x80000
	s_mov_b32 m0, s24
	v_add_u32_e32 v141, s44, v130
	ds_read_b128 v[174:177], v140 offset:32768
	ds_read_b128 v[178:181], v140 offset:33792
	ds_read_b128 v[182:185], v140 offset:34816
	ds_read_b128 v[186:189], v140 offset:35840
	ds_read_b128 v[190:193], v140 offset:36864
	ds_read_b128 v[194:197], v140 offset:37888
	ds_read_b128 v[198:201], v140 offset:38912
	ds_read_b128 v[204:207], v140 offset:39936
	global_load_lds_dwordx4 v141, s[4:5]
	v_add_u32_e32 v141, s44, v132
	s_mov_b32 m0, s25
	s_nop 0
	global_load_lds_dwordx4 v141, s[4:5]
	s_waitcnt vmcnt(8)
	s_waitcnt lgkmcnt(0)
	s_setprio 1
	s_barrier
	v_mfma_f32_16x16x32_bf16 v[126:129], v[142:145], v[174:177], v[126:129]
	v_mfma_f32_16x16x32_bf16 v[122:125], v[150:153], v[174:177], v[122:125]
	v_mfma_f32_16x16x32_bf16 v[110:113], v[142:145], v[182:185], v[110:113]
	v_mfma_f32_16x16x32_bf16 v[106:109], v[150:153], v[182:185], v[106:109]
	v_mfma_f32_16x16x32_bf16 v[94:97], v[142:145], v[190:193], v[94:97]
	v_mfma_f32_16x16x32_bf16 v[90:93], v[150:153], v[190:193], v[90:93]
	v_mfma_f32_16x16x32_bf16 v[78:81], v[142:145], v[198:201], v[78:81]
	v_mfma_f32_16x16x32_bf16 v[74:77], v[150:153], v[198:201], v[74:77]
	v_mfma_f32_16x16x32_bf16 v[126:129], v[146:149], v[178:181], v[126:129]
	v_mfma_f32_16x16x32_bf16 v[122:125], v[154:157], v[178:181], v[122:125]
	v_mfma_f32_16x16x32_bf16 v[110:113], v[146:149], v[186:189], v[110:113]
	v_mfma_f32_16x16x32_bf16 v[106:109], v[154:157], v[186:189], v[106:109]
	v_mfma_f32_16x16x32_bf16 v[94:97], v[146:149], v[194:197], v[94:97]
	v_mfma_f32_16x16x32_bf16 v[90:93], v[154:157], v[194:197], v[90:93]
	v_mfma_f32_16x16x32_bf16 v[78:81], v[146:149], v[204:207], v[78:81]
	v_mfma_f32_16x16x32_bf16 v[74:77], v[154:157], v[204:207], v[74:77]
	s_setprio 0
	s_setprio 1
	v_mfma_f32_16x16x32_bf16 v[118:121], v[158:161], v[174:177], v[118:121]
	v_mfma_f32_16x16x32_bf16 v[114:117], v[166:169], v[174:177], v[114:117]
	v_mfma_f32_16x16x32_bf16 v[102:105], v[158:161], v[182:185], v[102:105]
	v_mfma_f32_16x16x32_bf16 v[98:101], v[166:169], v[182:185], v[98:101]
	v_mfma_f32_16x16x32_bf16 v[86:89], v[158:161], v[190:193], v[86:89]
	v_mfma_f32_16x16x32_bf16 v[82:85], v[166:169], v[190:193], v[82:85]
	v_mfma_f32_16x16x32_bf16 v[70:73], v[158:161], v[198:201], v[70:73]
	v_mfma_f32_16x16x32_bf16 v[66:69], v[166:169], v[198:201], v[66:69]
	v_mfma_f32_16x16x32_bf16 v[118:121], v[162:165], v[178:181], v[118:121]
	v_mfma_f32_16x16x32_bf16 v[114:117], v[170:173], v[178:181], v[114:117]
	v_mfma_f32_16x16x32_bf16 v[102:105], v[162:165], v[186:189], v[102:105]
	v_mfma_f32_16x16x32_bf16 v[98:101], v[170:173], v[186:189], v[98:101]
	v_mfma_f32_16x16x32_bf16 v[86:89], v[162:165], v[194:197], v[86:89]
	v_mfma_f32_16x16x32_bf16 v[82:85], v[170:173], v[194:197], v[82:85]
	v_mfma_f32_16x16x32_bf16 v[70:73], v[162:165], v[204:207], v[70:73]
	v_mfma_f32_16x16x32_bf16 v[66:69], v[170:173], v[204:207], v[66:69]
	s_setprio 0
	s_barrier
	s_or_b32 s40, s43, 0x80
	s_mov_b32 m0, s30
	v_add_u32_e32 v141, s40, v131
	ds_read_b128 v[174:177], v140 offset:49152
	ds_read_b128 v[178:181], v140 offset:50176
	ds_read_b128 v[182:185], v140 offset:51200
	ds_read_b128 v[186:189], v140 offset:52224
	ds_read_b128 v[190:193], v140 offset:53248
	ds_read_b128 v[194:197], v140 offset:54272
	ds_read_b128 v[198:201], v140 offset:55296
	ds_read_b128 v[204:207], v140 offset:56320
	global_load_lds_dwordx4 v141, s[6:7]
	v_add_u32_e32 v141, s40, v133
	s_mov_b32 m0, s31
	s_add_i32 s43, s43, 0x80080
	global_load_lds_dwordx4 v141, s[6:7]
	v_add_u32_e32 v141, s43, v131
	s_mov_b32 m0, s37
	s_nop 0
	global_load_lds_dwordx4 v141, s[6:7]
	v_add_u32_e32 v141, s43, v133
	s_mov_b32 m0, s38
	s_nop 0
	global_load_lds_dwordx4 v141, s[6:7]
	v_add_u32_e32 v141, s42, v130
	s_mov_b32 m0, s34
	s_nop 0
	global_load_lds_dwordx4 v141, s[4:5]
	v_add_u32_e32 v141, s42, v132
	s_mov_b32 m0, s35
	s_nop 0
	global_load_lds_dwordx4 v141, s[4:5]
	s_waitcnt vmcnt(8)
	s_waitcnt lgkmcnt(0)
	s_setprio 1
	s_barrier
	v_mfma_f32_16x16x32_bf16 v[62:65], v[142:145], v[174:177], v[62:65]
	v_mfma_f32_16x16x32_bf16 v[58:61], v[150:153], v[174:177], v[58:61]
	v_mfma_f32_16x16x32_bf16 v[46:49], v[142:145], v[182:185], v[46:49]
	v_mfma_f32_16x16x32_bf16 v[42:45], v[150:153], v[182:185], v[42:45]
	v_mfma_f32_16x16x32_bf16 v[30:33], v[142:145], v[190:193], v[30:33]
	v_mfma_f32_16x16x32_bf16 v[26:29], v[150:153], v[190:193], v[26:29]
	v_mfma_f32_16x16x32_bf16 v[14:17], v[142:145], v[198:201], v[14:17]
	v_mfma_f32_16x16x32_bf16 v[10:13], v[150:153], v[198:201], v[10:13]
	v_mfma_f32_16x16x32_bf16 v[62:65], v[146:149], v[178:181], v[62:65]
	v_mfma_f32_16x16x32_bf16 v[58:61], v[154:157], v[178:181], v[58:61]
	v_mfma_f32_16x16x32_bf16 v[46:49], v[146:149], v[186:189], v[46:49]
	v_mfma_f32_16x16x32_bf16 v[42:45], v[154:157], v[186:189], v[42:45]
	v_mfma_f32_16x16x32_bf16 v[30:33], v[146:149], v[194:197], v[30:33]
	v_mfma_f32_16x16x32_bf16 v[26:29], v[154:157], v[194:197], v[26:29]
	v_mfma_f32_16x16x32_bf16 v[14:17], v[146:149], v[204:207], v[14:17]
	v_mfma_f32_16x16x32_bf16 v[10:13], v[154:157], v[204:207], v[10:13]
	s_setprio 0
	s_setprio 1
	v_mfma_f32_16x16x32_bf16 v[54:57], v[158:161], v[174:177], v[54:57]
	v_mfma_f32_16x16x32_bf16 v[50:53], v[166:169], v[174:177], v[50:53]
	v_mfma_f32_16x16x32_bf16 v[38:41], v[158:161], v[182:185], v[38:41]
	v_mfma_f32_16x16x32_bf16 v[34:37], v[166:169], v[182:185], v[34:37]
	v_mfma_f32_16x16x32_bf16 v[22:25], v[158:161], v[190:193], v[22:25]
	v_mfma_f32_16x16x32_bf16 v[18:21], v[166:169], v[190:193], v[18:21]
	v_mfma_f32_16x16x32_bf16 v[6:9], v[158:161], v[198:201], v[6:9]
	v_mfma_f32_16x16x32_bf16 v[2:5], v[166:169], v[198:201], v[2:5]
	v_mfma_f32_16x16x32_bf16 v[54:57], v[162:165], v[178:181], v[54:57]
	v_mfma_f32_16x16x32_bf16 v[50:53], v[170:173], v[178:181], v[50:53]
	v_mfma_f32_16x16x32_bf16 v[38:41], v[162:165], v[186:189], v[38:41]
	v_mfma_f32_16x16x32_bf16 v[34:37], v[170:173], v[186:189], v[34:37]
	v_mfma_f32_16x16x32_bf16 v[22:25], v[162:165], v[194:197], v[22:25]
	v_mfma_f32_16x16x32_bf16 v[18:21], v[170:173], v[194:197], v[18:21]
	v_mfma_f32_16x16x32_bf16 v[6:9], v[162:165], v[204:207], v[6:9]
	v_mfma_f32_16x16x32_bf16 v[2:5], v[170:173], v[204:207], v[2:5]
	s_setprio 0
	s_barrier
	s_add_i32 s39, s39, 2
	s_cmp_gt_u32 s39, 29
	s_mov_b32 s40, s41

.LBB0_740:
	v_lshrrev_b32_e32 v9, 1, v5
	v_and_b32_e32 v135, 24, v9
	v_and_b32_e32 v136, 15, v5
	v_lshlrev_b32_e32 v9, 1, v135
	v_lshlrev_b32_e32 v5, 2, v5
	s_lshl_b32 s20, s20, 5
	s_lshl_b32 s19, s21, 6
	v_lshl_or_b32 v9, v136, 6, v9
	s_lshl_b32 s21, s21, 13
	v_and_b32_e32 v5, 32, v5
	s_and_b32 s20, s20, 0x60
	v_bitop3_b32 v10, v9, s21, v5 bitop3:0xde
	s_lshl_b32 s21, s20, 7
	v_bitop3_b32 v137, v9, s21, v5 bitop3:0xde
	s_add_i32 s21, s28, 0x18000
	s_or_b32 s23, s2, 0x80
	s_add_i32 s22, s21, s27
	v_add_u32_e32 v5, s23, v131
	s_mov_b32 m0, s22
	s_waitcnt vmcnt(2)
	s_barrier
	global_load_lds_dwordx4 v5, s[6:7]
	v_add_u32_e32 v5, s23, v133
	s_add_i32 s23, s22, 0x2000
	s_mov_b32 m0, s23
	s_or_b32 s25, s14, 0x80
	s_add_i32 s24, s15, 0x8000
	global_load_lds_dwordx4 v5, s[6:7]
	v_add_u32_e32 v5, s25, v130
	s_mov_b32 m0, s24
	s_add_i32 s26, s28, 0x1c000
	global_load_lds_dwordx4 v5, s[4:5]
	v_add_u32_e32 v5, s25, v132
	s_add_i32 s25, s15, 0xa000
	s_mov_b32 m0, s25
	s_or_b32 s29, s2, 0x80080
	s_add_i32 s27, s26, s27
	global_load_lds_dwordx4 v5, s[4:5]
	v_add_u32_e32 v5, s29, v131
	s_mov_b32 m0, s27
	s_add_i32 s30, s14, 0x80080
	global_load_lds_dwordx4 v5, s[6:7]
	v_add_u32_e32 v5, s29, v133
	s_add_i32 s29, s27, 0x2000
	s_mov_b32 m0, s29
	v_lshlrev_b32_e32 v7, 12, v7
	global_load_lds_dwordx4 v5, s[6:7]
	v_lshlrev_b32_e32 v5, 15, v6
	v_and_b32_e32 v5, 0xffff0000, v5
	v_and_b32_e32 v6, 1, v6
	v_add3_u32 v5, s30, v5, v7
	v_lshlrev_b32_e32 v6, 6, v6
	v_lshlrev_b32_e32 v7, 1, v8
	v_add3_u32 v138, v5, v6, v7
	v_lshlrev_b32_e32 v5, 15, v2
	v_and_b32_e32 v5, 0xffff0000, v5
	v_lshlrev_b32_e32 v3, 12, v3
	v_and_b32_e32 v2, 1, v2
	s_waitcnt vmcnt(6)
	v_add3_u32 v3, s30, v5, v3
	v_lshlrev_b32_e32 v2, 6, v2
	v_lshlrev_b32_e32 v4, 1, v4
	v_add3_u32 v139, v3, v2, v4
	v_or_b32_e32 v134, s19, v136
	s_mov_b32 s30, -2
	s_mov_b32 s31, 0
	v_add_u32_e32 v140, s28, v10
	s_barrier
	v_add_u32_e32 v141, s3, v137
	ds_read_b128 v[142:145], v141
	ds_read_b128 v[146:149], v141 offset:1024
	ds_read_b128 v[150:153], v141 offset:2048
	ds_read_b128 v[154:157], v141 offset:3072
	v_add_u32_e32 v141, s11, v137
	ds_read_b128 v[158:161], v141
	ds_read_b128 v[162:165], v141 offset:1024
	ds_read_b128 v[166:169], v141 offset:2048
	ds_read_b128 v[170:173], v141 offset:3072
	s_add_i32 s34, s31, 0x100
	s_cmp_lg_u32 s30, 28
	s_cselect_b32 s36, s34, 0
	s_add_i32 s37, s36, s14
	s_or_b32 s35, s37, 0x80
	s_add_i32 s36, s36, s2
	v_add_u32_e32 v141, s31, v139
	s_add_i32 m0, s15, 0xc000
	ds_read_b128 v[174:177], v140
	ds_read_b128 v[178:181], v140 offset:1024
	ds_read_b128 v[182:185], v140 offset:2048
	ds_read_b128 v[186:189], v140 offset:3072
	ds_read_b128 v[190:193], v140 offset:4096
	ds_read_b128 v[194:197], v140 offset:5120
	ds_read_b128 v[198:201], v140 offset:6144
	ds_read_b128 v[204:207], v140 offset:7168
	global_load_lds_dwordx4 v141, s[4:5]
	v_add_u32_e32 v141, s31, v138
	s_add_i32 m0, s15, 0xe000
	s_nop 0
	global_load_lds_dwordx4 v141, s[4:5]
	s_waitcnt vmcnt(8)
	s_waitcnt lgkmcnt(0)
	s_setprio 1
	s_barrier
	v_mfma_f32_16x16x32_bf16 v[126:129], v[142:145], v[174:177], 0
	v_mfma_f32_16x16x32_bf16 v[122:125], v[150:153], v[174:177], 0
	v_mfma_f32_16x16x32_bf16 v[110:113], v[142:145], v[182:185], 0
	v_mfma_f32_16x16x32_bf16 v[106:109], v[150:153], v[182:185], 0
	v_mfma_f32_16x16x32_bf16 v[94:97], v[142:145], v[190:193], 0
	v_mfma_f32_16x16x32_bf16 v[90:93], v[150:153], v[190:193], 0
	v_mfma_f32_16x16x32_bf16 v[78:81], v[142:145], v[198:201], 0
	v_mfma_f32_16x16x32_bf16 v[74:77], v[150:153], v[198:201], 0
	v_mfma_f32_16x16x32_bf16 v[126:129], v[146:149], v[178:181], v[126:129]
	v_mfma_f32_16x16x32_bf16 v[122:125], v[154:157], v[178:181], v[122:125]
	v_mfma_f32_16x16x32_bf16 v[110:113], v[146:149], v[186:189], v[110:113]
	v_mfma_f32_16x16x32_bf16 v[106:109], v[154:157], v[186:189], v[106:109]
	v_mfma_f32_16x16x32_bf16 v[94:97], v[146:149], v[194:197], v[94:97]
	v_mfma_f32_16x16x32_bf16 v[90:93], v[154:157], v[194:197], v[90:93]
	v_mfma_f32_16x16x32_bf16 v[78:81], v[146:149], v[204:207], v[78:81]
	v_mfma_f32_16x16x32_bf16 v[74:77], v[154:157], v[204:207], v[74:77]
	s_setprio 0
	s_setprio 1
	v_mfma_f32_16x16x32_bf16 v[118:121], v[158:161], v[174:177], 0
	v_mfma_f32_16x16x32_bf16 v[114:117], v[166:169], v[174:177], 0
	v_mfma_f32_16x16x32_bf16 v[102:105], v[158:161], v[182:185], 0
	v_mfma_f32_16x16x32_bf16 v[98:101], v[166:169], v[182:185], 0
	v_mfma_f32_16x16x32_bf16 v[86:89], v[158:161], v[190:193], 0
	v_mfma_f32_16x16x32_bf16 v[82:85], v[166:169], v[190:193], 0
	v_mfma_f32_16x16x32_bf16 v[70:73], v[158:161], v[198:201], 0
	v_mfma_f32_16x16x32_bf16 v[66:69], v[166:169], v[198:201], 0
	v_mfma_f32_16x16x32_bf16 v[118:121], v[162:165], v[178:181], v[118:121]
	v_mfma_f32_16x16x32_bf16 v[114:117], v[170:173], v[178:181], v[114:117]
	v_mfma_f32_16x16x32_bf16 v[102:105], v[162:165], v[186:189], v[102:105]
	v_mfma_f32_16x16x32_bf16 v[98:101], v[170:173], v[186:189], v[98:101]
	v_mfma_f32_16x16x32_bf16 v[86:89], v[162:165], v[194:197], v[86:89]
	v_mfma_f32_16x16x32_bf16 v[82:85], v[170:173], v[194:197], v[82:85]
	v_mfma_f32_16x16x32_bf16 v[70:73], v[162:165], v[204:207], v[70:73]
	v_mfma_f32_16x16x32_bf16 v[66:69], v[170:173], v[204:207], v[66:69]
	s_setprio 0
	s_barrier
	s_mov_b32 m0, s9
	v_add_u32_e32 v141, s36, v131
	ds_read_b128 v[174:177], v140 offset:16384
	ds_read_b128 v[178:181], v140 offset:17408
	ds_read_b128 v[182:185], v140 offset:18432
	ds_read_b128 v[186:189], v140 offset:19456
	ds_read_b128 v[190:193], v140 offset:20480
	ds_read_b128 v[194:197], v140 offset:21504
	ds_read_b128 v[198:201], v140 offset:22528
	ds_read_b128 v[204:207], v140 offset:23552
	global_load_lds_dwordx4 v141, s[6:7]
	v_add_u32_e32 v141, s36, v133
	s_mov_b32 m0, s10
	s_add_i32 s31, s36, 0x80000
	global_load_lds_dwordx4 v141, s[6:7]
	v_add_u32_e32 v141, s31, v131
	s_mov_b32 m0, s12
	s_nop 0
	global_load_lds_dwordx4 v141, s[6:7]
	v_add_u32_e32 v141, s31, v133
	s_mov_b32 m0, s13
	s_nop 0
	global_load_lds_dwordx4 v141, s[6:7]
	v_add_u32_e32 v141, s37, v130
	s_mov_b32 m0, s15
	s_nop 0
	global_load_lds_dwordx4 v141, s[4:5]
	v_add_u32_e32 v141, s37, v132
	s_mov_b32 m0, s16
	s_nop 0
	global_load_lds_dwordx4 v141, s[4:5]
	s_waitcnt vmcnt(8)
	s_waitcnt lgkmcnt(0)
	s_setprio 1
	s_barrier
	v_mfma_f32_16x16x32_bf16 v[62:65], v[142:145], v[174:177], 0
	v_mfma_f32_16x16x32_bf16 v[58:61], v[150:153], v[174:177], 0
	v_mfma_f32_16x16x32_bf16 v[46:49], v[142:145], v[182:185], 0
	v_mfma_f32_16x16x32_bf16 v[42:45], v[150:153], v[182:185], 0
	v_mfma_f32_16x16x32_bf16 v[30:33], v[142:145], v[190:193], 0
	v_mfma_f32_16x16x32_bf16 v[26:29], v[150:153], v[190:193], 0
	v_mfma_f32_16x16x32_bf16 v[14:17], v[142:145], v[198:201], 0
	v_mfma_f32_16x16x32_bf16 v[10:13], v[150:153], v[198:201], 0
	v_mfma_f32_16x16x32_bf16 v[62:65], v[146:149], v[178:181], v[62:65]
	v_mfma_f32_16x16x32_bf16 v[58:61], v[154:157], v[178:181], v[58:61]
	v_mfma_f32_16x16x32_bf16 v[46:49], v[146:149], v[186:189], v[46:49]
	v_mfma_f32_16x16x32_bf16 v[42:45], v[154:157], v[186:189], v[42:45]
	v_mfma_f32_16x16x32_bf16 v[30:33], v[146:149], v[194:197], v[30:33]
	v_mfma_f32_16x16x32_bf16 v[26:29], v[154:157], v[194:197], v[26:29]
	v_mfma_f32_16x16x32_bf16 v[14:17], v[146:149], v[204:207], v[14:17]
	v_mfma_f32_16x16x32_bf16 v[10:13], v[154:157], v[204:207], v[10:13]
	s_setprio 0
	s_setprio 1
	v_mfma_f32_16x16x32_bf16 v[54:57], v[158:161], v[174:177], 0
	v_mfma_f32_16x16x32_bf16 v[50:53], v[166:169], v[174:177], 0
	v_mfma_f32_16x16x32_bf16 v[38:41], v[158:161], v[182:185], 0
	v_mfma_f32_16x16x32_bf16 v[34:37], v[166:169], v[182:185], 0
	v_mfma_f32_16x16x32_bf16 v[22:25], v[158:161], v[190:193], 0
	v_mfma_f32_16x16x32_bf16 v[18:21], v[166:169], v[190:193], 0
	v_mfma_f32_16x16x32_bf16 v[6:9], v[158:161], v[198:201], 0
	v_mfma_f32_16x16x32_bf16 v[2:5], v[166:169], v[198:201], 0
	v_mfma_f32_16x16x32_bf16 v[54:57], v[162:165], v[178:181], v[54:57]
	v_mfma_f32_16x16x32_bf16 v[50:53], v[170:173], v[178:181], v[50:53]
	v_mfma_f32_16x16x32_bf16 v[38:41], v[162:165], v[186:189], v[38:41]
	v_mfma_f32_16x16x32_bf16 v[34:37], v[170:173], v[186:189], v[34:37]
	v_mfma_f32_16x16x32_bf16 v[22:25], v[162:165], v[194:197], v[22:25]
	v_mfma_f32_16x16x32_bf16 v[18:21], v[170:173], v[194:197], v[18:21]
	v_mfma_f32_16x16x32_bf16 v[6:9], v[162:165], v[204:207], v[6:9]
	v_mfma_f32_16x16x32_bf16 v[2:5], v[170:173], v[204:207], v[2:5]
	s_setprio 0
	s_barrier
	v_add_u32_e32 v141, s21, v137
	ds_read_b128 v[142:145], v141
	ds_read_b128 v[146:149], v141 offset:1024
	ds_read_b128 v[150:153], v141 offset:2048
	ds_read_b128 v[154:157], v141 offset:3072
	v_add_u32_e32 v141, s26, v137
	ds_read_b128 v[158:161], v141
	ds_read_b128 v[162:165], v141 offset:1024
	ds_read_b128 v[166:169], v141 offset:2048
	ds_read_b128 v[170:173], v141 offset:3072
	s_add_i32 s37, s37, 0x80000
	s_mov_b32 m0, s17
	v_add_u32_e32 v141, s37, v130
	ds_read_b128 v[174:177], v140 offset:32768
	ds_read_b128 v[178:181], v140 offset:33792
	ds_read_b128 v[182:185], v140 offset:34816
	ds_read_b128 v[186:189], v140 offset:35840
	ds_read_b128 v[190:193], v140 offset:36864
	ds_read_b128 v[194:197], v140 offset:37888
	ds_read_b128 v[198:201], v140 offset:38912
	ds_read_b128 v[204:207], v140 offset:39936
	global_load_lds_dwordx4 v141, s[4:5]
	v_add_u32_e32 v141, s37, v132
	s_mov_b32 m0, s18
	s_nop 0
	global_load_lds_dwordx4 v141, s[4:5]
	s_waitcnt vmcnt(8)
	s_waitcnt lgkmcnt(0)
	s_setprio 1
	s_barrier
	v_mfma_f32_16x16x32_bf16 v[126:129], v[142:145], v[174:177], v[126:129]
	v_mfma_f32_16x16x32_bf16 v[122:125], v[150:153], v[174:177], v[122:125]
	v_mfma_f32_16x16x32_bf16 v[110:113], v[142:145], v[182:185], v[110:113]
	v_mfma_f32_16x16x32_bf16 v[106:109], v[150:153], v[182:185], v[106:109]
	v_mfma_f32_16x16x32_bf16 v[94:97], v[142:145], v[190:193], v[94:97]
	v_mfma_f32_16x16x32_bf16 v[90:93], v[150:153], v[190:193], v[90:93]
	v_mfma_f32_16x16x32_bf16 v[78:81], v[142:145], v[198:201], v[78:81]
	v_mfma_f32_16x16x32_bf16 v[74:77], v[150:153], v[198:201], v[74:77]
	v_mfma_f32_16x16x32_bf16 v[126:129], v[146:149], v[178:181], v[126:129]
	v_mfma_f32_16x16x32_bf16 v[122:125], v[154:157], v[178:181], v[122:125]
	v_mfma_f32_16x16x32_bf16 v[110:113], v[146:149], v[186:189], v[110:113]
	v_mfma_f32_16x16x32_bf16 v[106:109], v[154:157], v[186:189], v[106:109]
	v_mfma_f32_16x16x32_bf16 v[94:97], v[146:149], v[194:197], v[94:97]
	v_mfma_f32_16x16x32_bf16 v[90:93], v[154:157], v[194:197], v[90:93]
	v_mfma_f32_16x16x32_bf16 v[78:81], v[146:149], v[204:207], v[78:81]
	v_mfma_f32_16x16x32_bf16 v[74:77], v[154:157], v[204:207], v[74:77]
	s_setprio 0
	s_setprio 1
	v_mfma_f32_16x16x32_bf16 v[118:121], v[158:161], v[174:177], v[118:121]
	v_mfma_f32_16x16x32_bf16 v[114:117], v[166:169], v[174:177], v[114:117]
	v_mfma_f32_16x16x32_bf16 v[102:105], v[158:161], v[182:185], v[102:105]
	v_mfma_f32_16x16x32_bf16 v[98:101], v[166:169], v[182:185], v[98:101]
	v_mfma_f32_16x16x32_bf16 v[86:89], v[158:161], v[190:193], v[86:89]
	v_mfma_f32_16x16x32_bf16 v[82:85], v[166:169], v[190:193], v[82:85]
	v_mfma_f32_16x16x32_bf16 v[70:73], v[158:161], v[198:201], v[70:73]
	v_mfma_f32_16x16x32_bf16 v[66:69], v[166:169], v[198:201], v[66:69]
	v_mfma_f32_16x16x32_bf16 v[118:121], v[162:165], v[178:181], v[118:121]
	v_mfma_f32_16x16x32_bf16 v[114:117], v[170:173], v[178:181], v[114:117]
	v_mfma_f32_16x16x32_bf16 v[102:105], v[162:165], v[186:189], v[102:105]
	v_mfma_f32_16x16x32_bf16 v[98:101], v[170:173], v[186:189], v[98:101]
	v_mfma_f32_16x16x32_bf16 v[86:89], v[162:165], v[194:197], v[86:89]
	v_mfma_f32_16x16x32_bf16 v[82:85], v[170:173], v[194:197], v[82:85]
	v_mfma_f32_16x16x32_bf16 v[70:73], v[162:165], v[204:207], v[70:73]
	v_mfma_f32_16x16x32_bf16 v[66:69], v[170:173], v[204:207], v[66:69]
	s_setprio 0
	s_barrier
	s_or_b32 s31, s36, 0x80
	s_mov_b32 m0, s22
	v_add_u32_e32 v141, s31, v131
	ds_read_b128 v[174:177], v140 offset:49152
	ds_read_b128 v[178:181], v140 offset:50176
	ds_read_b128 v[182:185], v140 offset:51200
	ds_read_b128 v[186:189], v140 offset:52224
	ds_read_b128 v[190:193], v140 offset:53248
	ds_read_b128 v[194:197], v140 offset:54272
	ds_read_b128 v[198:201], v140 offset:55296
	ds_read_b128 v[204:207], v140 offset:56320
	global_load_lds_dwordx4 v141, s[6:7]
	v_add_u32_e32 v141, s31, v133
	s_mov_b32 m0, s23
	s_add_i32 s36, s36, 0x80080
	global_load_lds_dwordx4 v141, s[6:7]
	v_add_u32_e32 v141, s36, v131
	s_mov_b32 m0, s27
	s_nop 0
	global_load_lds_dwordx4 v141, s[6:7]
	v_add_u32_e32 v141, s36, v133
	s_mov_b32 m0, s29
	s_nop 0
	global_load_lds_dwordx4 v141, s[6:7]
	v_add_u32_e32 v141, s35, v130
	s_mov_b32 m0, s24
	s_nop 0
	global_load_lds_dwordx4 v141, s[4:5]
	v_add_u32_e32 v141, s35, v132
	s_mov_b32 m0, s25
	s_nop 0
	global_load_lds_dwordx4 v141, s[4:5]
	s_waitcnt vmcnt(8)
	s_waitcnt lgkmcnt(0)
	s_setprio 1
	s_barrier
	v_mfma_f32_16x16x32_bf16 v[62:65], v[142:145], v[174:177], v[62:65]
	v_mfma_f32_16x16x32_bf16 v[58:61], v[150:153], v[174:177], v[58:61]
	v_mfma_f32_16x16x32_bf16 v[46:49], v[142:145], v[182:185], v[46:49]
	v_mfma_f32_16x16x32_bf16 v[42:45], v[150:153], v[182:185], v[42:45]
	v_mfma_f32_16x16x32_bf16 v[30:33], v[142:145], v[190:193], v[30:33]
	v_mfma_f32_16x16x32_bf16 v[26:29], v[150:153], v[190:193], v[26:29]
	v_mfma_f32_16x16x32_bf16 v[14:17], v[142:145], v[198:201], v[14:17]
	v_mfma_f32_16x16x32_bf16 v[10:13], v[150:153], v[198:201], v[10:13]
	v_mfma_f32_16x16x32_bf16 v[62:65], v[146:149], v[178:181], v[62:65]
	v_mfma_f32_16x16x32_bf16 v[58:61], v[154:157], v[178:181], v[58:61]
	v_mfma_f32_16x16x32_bf16 v[46:49], v[146:149], v[186:189], v[46:49]
	v_mfma_f32_16x16x32_bf16 v[42:45], v[154:157], v[186:189], v[42:45]
	v_mfma_f32_16x16x32_bf16 v[30:33], v[146:149], v[194:197], v[30:33]
	v_mfma_f32_16x16x32_bf16 v[26:29], v[154:157], v[194:197], v[26:29]
	v_mfma_f32_16x16x32_bf16 v[14:17], v[146:149], v[204:207], v[14:17]
	v_mfma_f32_16x16x32_bf16 v[10:13], v[154:157], v[204:207], v[10:13]
	s_setprio 0
	s_setprio 1
	v_mfma_f32_16x16x32_bf16 v[54:57], v[158:161], v[174:177], v[54:57]
	v_mfma_f32_16x16x32_bf16 v[50:53], v[166:169], v[174:177], v[50:53]
	v_mfma_f32_16x16x32_bf16 v[38:41], v[158:161], v[182:185], v[38:41]
	v_mfma_f32_16x16x32_bf16 v[34:37], v[166:169], v[182:185], v[34:37]
	v_mfma_f32_16x16x32_bf16 v[22:25], v[158:161], v[190:193], v[22:25]
	v_mfma_f32_16x16x32_bf16 v[18:21], v[166:169], v[190:193], v[18:21]
	v_mfma_f32_16x16x32_bf16 v[6:9], v[158:161], v[198:201], v[6:9]
	v_mfma_f32_16x16x32_bf16 v[2:5], v[166:169], v[198:201], v[2:5]
	v_mfma_f32_16x16x32_bf16 v[54:57], v[162:165], v[178:181], v[54:57]
	v_mfma_f32_16x16x32_bf16 v[50:53], v[170:173], v[178:181], v[50:53]
	v_mfma_f32_16x16x32_bf16 v[38:41], v[162:165], v[186:189], v[38:41]
	v_mfma_f32_16x16x32_bf16 v[34:37], v[170:173], v[186:189], v[34:37]
	v_mfma_f32_16x16x32_bf16 v[22:25], v[162:165], v[194:197], v[22:25]
	v_mfma_f32_16x16x32_bf16 v[18:21], v[170:173], v[194:197], v[18:21]
	v_mfma_f32_16x16x32_bf16 v[6:9], v[162:165], v[204:207], v[6:9]
	v_mfma_f32_16x16x32_bf16 v[2:5], v[170:173], v[204:207], v[2:5]
	s_setprio 0
	s_barrier
	s_add_i32 s30, s30, 2
	s_cmp_gt_u32 s30, 29
	s_mov_b32 s31, s34

.LBB0_775:
	s_or_b64 exec, exec, s[0:1]
	v_readlane_b32 s0, v253, 2
	v_readlane_b32 s14, v253, 0
	v_readlane_b32 s15, v253, 1
	s_mov_b32 s12, s65
	v_readlane_b32 s1, v253, 3
	v_mov_b32_e32 v3, v0
	s_waitcnt lgkmcnt(0)
	s_barrier
	s_cmpk_gt_i32 s14, 0x5ff
	v_readfirstlane_b32 s10, v3
	s_cbranch_scc1 .LBB0_791
	v_bfe_i32 v4, v3, 27, 1
	v_lshlrev_b32_e32 v6, 4, v3
	v_lshrrev_b32_e32 v4, 22, v4
	v_add_u32_e32 v4, v6, v4
	v_and_b32_e32 v4, 0xfffffc00, v4
	v_sub_u32_e32 v4, v6, v4
	v_ashrrev_i32_e32 v2, 31, v3
	v_lshrrev_b32_e32 v5, 4, v4
	v_lshrrev_b32_e32 v2, 26, v2
	v_bitop3_b32 v5, v5, v4, 32 bitop3:0x6c
	v_ashrrev_i32_e32 v4, 31, v4
	v_add_u32_e32 v2, v3, v2
	v_lshrrev_b32_e32 v4, 26, v4
	v_ashrrev_i32_e32 v2, 6, v2
	v_add_u32_e32 v4, v5, v4
	v_lshlrev_b32_e32 v7, 3, v2
	v_ashrrev_i32_e32 v4, 6, v4
	v_and_b32_e32 v7, -16, v7
	v_mul_i32_i24_e32 v9, 64, v4
	v_add_u32_e32 v7, v4, v7
	v_sub_u32_e32 v5, v5, v9
	v_lshlrev_b32_e32 v8, 5, v2
	v_ashrrev_i16_sdwa v5, v1, sext(v5) dst_sel:DWORD dst_unused:UNUSED_PAD src0_sel:DWORD src1_sel:BYTE_0
	v_lshlrev_b32_e32 v9, 1, v7
	v_lshrrev_b32_e32 v10, 2, v7
	v_and_b32_e32 v11, 3, v4
	s_mov_b32 s6, 0x7fffe0
	v_and_b32_e32 v8, 32, v8
	v_bfe_i32 v5, v5, 0, 16
	v_and_b32_e32 v9, 24, v9
	v_and_b32_e32 v10, 4, v10
	v_and_or_b32 v11, v7, s6, v11
	s_movk_i32 s7, 0x1600
	v_add_u32_e32 v8, v8, v5
	v_or3_b32 v9, v11, v10, v9
	v_mul_lo_u32 v7, v7, s7
	v_add_lshl_u32 v132, v8, v7, 1
	v_mul_u32_u24_e32 v7, 0x1600, v9
	v_add_lshl_u32 v133, v7, v8, 1
	v_add_u32_e32 v7, 0x2000, v6
	v_ashrrev_i32_e32 v6, 31, v7
	v_lshrrev_b32_e32 v6, 22, v6
	v_add_u32_e32 v6, v7, v6
	v_ashrrev_i32_e32 v6, 10, v6
	s_load_dwordx2 s[4:5], s[0:1], 0x98
	v_mul_i32_i24_e32 v8, 0x400, v6
	v_sub_u32_e32 v7, v7, v8
	v_lshrrev_b32_e32 v8, 4, v7
	v_bitop3_b32 v8, v8, v7, 32 bitop3:0x6c
	v_lshlrev_b32_e32 v7, 3, v6
	v_and_b32_e32 v9, -16, v7
	v_ashrrev_i32_e32 v7, 31, v8
	s_waitcnt lgkmcnt(0)
	s_add_u32 s0, s4, 0x18100000
	v_lshrrev_b32_e32 v7, 26, v7
	s_addc_u32 s1, s5, 0
	v_add_u32_e32 v10, v8, v7
	s_add_u32 s2, s4, 0x9b00000
	v_ashrrev_i32_e32 v7, 6, v10
	v_and_b32_e32 v10, 0xc0, v10
	s_addc_u32 s3, s5, 0
	v_add_u32_e32 v9, v7, v9
	v_sub_u32_e32 v8, v8, v10
	v_and_b32_e32 v13, 3, v7
	s_ashr_i32 s16, s14, 31
	v_lshlrev_b32_e32 v11, 5, v6
	v_ashrrev_i16_sdwa v8, v1, sext(v8) dst_sel:DWORD dst_unused:UNUSED_PAD src0_sel:DWORD src1_sel:BYTE_0
	v_and_or_b32 v13, v9, s6, v13
	s_lshr_b32 s6, s16, 29
	v_and_b32_e32 v11, 32, v11
	v_bfe_i32 v8, v8, 0, 16
	s_add_i32 s6, s14, s6
	s_ashr_i32 s11, s10, 6
	v_add_u32_e32 v10, v11, v8
	v_lshlrev_b32_e32 v11, 1, v9
	v_lshrrev_b32_e32 v12, 2, v9
	v_mul_lo_u32 v9, v9, s7
	s_ashr_i32 s7, s6, 3
	s_and_b32 s6, s6, -8
	s_ashr_i32 s13, s10, 8
	s_lshl_b32 s35, s11, 10
	s_sub_i32 s6, s14, s6
	s_cmp_lt_i32 s6, 0
	s_movk_i32 s8, 0xc1
	s_cselect_b32 s8, s8, 0xc0
	s_mul_i32 s6, s6, s8
	s_add_i32 s6, s6, s7
	s_ashr_i32 s7, s6, 31
	s_lshr_b32 s7, s7, 28
	s_add_i32 s7, s6, s7
	s_ashr_i32 s8, s7, 4
	s_and_b32 s7, s7, 0xfff0
	s_sub_i32 s6, s6, s7
	s_bfe_u32 s7, s6, 0x10007
	s_add_i32 s7, s6, s7
	s_bfe_i32 s9, s7, 0x80000
	v_and_b32_e32 v11, 24, v11
	v_and_b32_e32 v12, 4, v12
	s_sext_i32_i16 s9, s9
	v_or3_b32 v11, v13, v12, v11
	s_and_b32 s7, s7, 0xfe
	s_ashr_i32 s41, s9, 1
	s_add_i32 s17, s12, 0x10000
	v_add_lshl_u32 v134, v10, v9, 1
	v_mul_u32_u24_e32 v9, 0x1600, v11
	s_sub_i32 s6, s6, s7
	s_mul_i32 s46, s41, 0x2c0000
	s_add_i32 s18, s17, s35
	v_add_lshl_u32 v135, v9, v10, 1
	s_lshl_b32 s8, s8, 1
	s_sext_i32_i8 s6, s6
	v_add_u32_e32 v9, s46, v133
	s_mov_b32 m0, s18
	s_add_i32 s19, s18, 0x2000
	s_add_i32 s20, s12, 0x14000
	s_add_i32 s42, s8, s6
	s_sub_i32 s42, 0xbf, s42
	global_load_lds_dwordx4 v9, s[2:3]
	v_add_u32_e32 v9, s46, v135
	s_mov_b32 m0, s19
	s_add_i32 s6, s46, 0x160000
	s_add_i32 s21, s20, s35
	global_load_lds_dwordx4 v9, s[2:3]
	v_add_u32_e32 v9, s6, v133
	s_mov_b32 m0, s21
	s_add_i32 s22, s21, 0x2000
	global_load_lds_dwordx4 v9, s[2:3]
	v_add_u32_e32 v9, s6, v135
	s_mov_b32 m0, s22
	s_mul_i32 s45, s42, 0x2c0000
	s_add_i32 s23, s12, s35
	global_load_lds_dwordx4 v9, s[2:3]
	v_add_u32_e32 v9, s45, v132
	s_mov_b32 m0, s23
	s_add_i32 s24, s23, 0x2000
	global_load_lds_dwordx4 v9, s[0:1]
	v_add_u32_e32 v9, s45, v134
	s_mov_b32 m0, s24
	s_add_i32 s6, s45, 0x160000
	s_add_i32 s25, s23, 0x4000
	global_load_lds_dwordx4 v9, s[0:1]
	v_add_u32_e32 v9, s6, v132
	s_mov_b32 m0, s25
	s_add_i32 s26, s23, 0x6000
	global_load_lds_dwordx4 v9, s[0:1]
	v_add_u32_e32 v9, s6, v134
	s_mov_b32 m0, s26
	s_cmp_eq_u32 s13, 1
	global_load_lds_dwordx4 v9, s[0:1]
	s_cselect_b64 s[6:7], -1, 0
	s_cmp_lg_u32 s13, 1
	s_cbranch_scc1 .LBB0_778
	s_barrier

.LBB0_783:
	s_mul_i32 s12, s40, 0x2c0000
	s_and_b64 s[48:49], s[4:5], exec
	s_mul_i32 s13, s39, 0x2c0000
	s_cselect_b32 s43, s12, s45
	s_cselect_b32 s44, s13, s46
	s_add_i32 s45, s45, 0x160080
	s_addk_i32 s46, 0x100
	s_mov_b32 s47, -2
	v_add_u32_e32 v130, s17, v137
	ds_read_b128 v[142:145], v130
	ds_read_b128 v[146:149], v130 offset:1024
	ds_read_b128 v[150:153], v130 offset:2048
	ds_read_b128 v[154:157], v130 offset:3072
	v_add_u32_e32 v130, s20, v137
	ds_read_b128 v[158:161], v130
	ds_read_b128 v[162:165], v130 offset:1024
	ds_read_b128 v[166:169], v130 offset:2048
	ds_read_b128 v[170:173], v130 offset:3072
	s_add_i32 s48, s45, 0xffea0080
	s_cmpk_eq_i32 s47, 0x54
	s_cselect_b32 s50, s43, s48
	s_cselect_b32 s49, s44, s46
	s_or_b32 s48, s50, 0x80
	v_add_u32_e32 v130, s45, v140
	s_add_i32 m0, s23, 0xc000
	ds_read_b128 v[174:177], v141
	ds_read_b128 v[178:181], v141 offset:1024
	ds_read_b128 v[182:185], v141 offset:2048
	ds_read_b128 v[186:189], v141 offset:3072
	ds_read_b128 v[190:193], v141 offset:4096
	ds_read_b128 v[194:197], v141 offset:5120
	ds_read_b128 v[198:201], v141 offset:6144
	ds_read_b128 v[204:207], v141 offset:7168
	global_load_lds_dwordx4 v130, s[0:1]
	v_add_u32_e32 v130, s45, v139
	s_add_i32 m0, s23, 0xe000
	s_nop 0
	global_load_lds_dwordx4 v130, s[0:1]
	s_waitcnt vmcnt(8)
	s_waitcnt lgkmcnt(0)
	s_setprio 1
	s_barrier
	v_mfma_f32_16x16x32_bf16 v[126:129], v[142:145], v[174:177], 0
	v_mfma_f32_16x16x32_bf16 v[122:125], v[150:153], v[174:177], 0
	v_mfma_f32_16x16x32_bf16 v[118:121], v[142:145], v[182:185], 0
	v_mfma_f32_16x16x32_bf16 v[110:113], v[150:153], v[182:185], 0
	v_mfma_f32_16x16x32_bf16 v[102:105], v[142:145], v[190:193], 0
	v_mfma_f32_16x16x32_bf16 v[94:97], v[150:153], v[190:193], 0
	v_mfma_f32_16x16x32_bf16 v[86:89], v[142:145], v[198:201], 0
	v_mfma_f32_16x16x32_bf16 v[78:81], v[150:153], v[198:201], 0
	v_mfma_f32_16x16x32_bf16 v[126:129], v[146:149], v[178:181], v[126:129]
	v_mfma_f32_16x16x32_bf16 v[122:125], v[154:157], v[178:181], v[122:125]
	v_mfma_f32_16x16x32_bf16 v[118:121], v[146:149], v[186:189], v[118:121]
	v_mfma_f32_16x16x32_bf16 v[110:113], v[154:157], v[186:189], v[110:113]
	v_mfma_f32_16x16x32_bf16 v[102:105], v[146:149], v[194:197], v[102:105]
	v_mfma_f32_16x16x32_bf16 v[94:97], v[154:157], v[194:197], v[94:97]
	v_mfma_f32_16x16x32_bf16 v[86:89], v[146:149], v[204:207], v[86:89]
	v_mfma_f32_16x16x32_bf16 v[78:81], v[154:157], v[204:207], v[78:81]
	s_setprio 0
	s_setprio 1
	v_mfma_f32_16x16x32_bf16 v[114:117], v[158:161], v[174:177], 0
	v_mfma_f32_16x16x32_bf16 v[106:109], v[166:169], v[174:177], 0
	v_mfma_f32_16x16x32_bf16 v[98:101], v[158:161], v[182:185], 0
	v_mfma_f32_16x16x32_bf16 v[90:93], v[166:169], v[182:185], 0
	v_mfma_f32_16x16x32_bf16 v[82:85], v[158:161], v[190:193], 0
	v_mfma_f32_16x16x32_bf16 v[74:77], v[166:169], v[190:193], 0
	v_mfma_f32_16x16x32_bf16 v[70:73], v[158:161], v[198:201], 0
	v_mfma_f32_16x16x32_bf16 v[66:69], v[166:169], v[198:201], 0
	v_mfma_f32_16x16x32_bf16 v[114:117], v[162:165], v[178:181], v[114:117]
	v_mfma_f32_16x16x32_bf16 v[106:109], v[170:173], v[178:181], v[106:109]
	v_mfma_f32_16x16x32_bf16 v[98:101], v[162:165], v[186:189], v[98:101]
	v_mfma_f32_16x16x32_bf16 v[90:93], v[170:173], v[186:189], v[90:93]
	v_mfma_f32_16x16x32_bf16 v[82:85], v[162:165], v[194:197], v[82:85]
	v_mfma_f32_16x16x32_bf16 v[74:77], v[170:173], v[194:197], v[74:77]
	v_mfma_f32_16x16x32_bf16 v[70:73], v[162:165], v[204:207], v[70:73]
	v_mfma_f32_16x16x32_bf16 v[66:69], v[170:173], v[204:207], v[66:69]
	s_setprio 0
	s_barrier
	s_mov_b32 m0, s18
	v_add_u32_e32 v130, s49, v133
	ds_read_b128 v[174:177], v141 offset:16384
	ds_read_b128 v[178:181], v141 offset:17408
	ds_read_b128 v[182:185], v141 offset:18432
	ds_read_b128 v[186:189], v141 offset:19456
	ds_read_b128 v[190:193], v141 offset:20480
	ds_read_b128 v[194:197], v141 offset:21504
	ds_read_b128 v[198:201], v141 offset:22528
	ds_read_b128 v[204:207], v141 offset:23552
	global_load_lds_dwordx4 v130, s[2:3]
	v_add_u32_e32 v130, s49, v135
	s_mov_b32 m0, s19
	s_add_i32 s51, s49, 0x160000
	global_load_lds_dwordx4 v130, s[2:3]
	v_add_u32_e32 v130, s51, v133
	s_mov_b32 m0, s21
	s_nop 0
	global_load_lds_dwordx4 v130, s[2:3]
	v_add_u32_e32 v130, s51, v135
	s_mov_b32 m0, s22
	s_nop 0
	global_load_lds_dwordx4 v130, s[2:3]
	v_add_u32_e32 v130, s50, v132
	s_mov_b32 m0, s23
	s_nop 0
	global_load_lds_dwordx4 v130, s[0:1]
	v_add_u32_e32 v130, s50, v134
	s_mov_b32 m0, s24
	s_nop 0
	global_load_lds_dwordx4 v130, s[0:1]
	s_waitcnt vmcnt(8)
	s_waitcnt lgkmcnt(0)
	s_setprio 1
	s_barrier
	v_mfma_f32_16x16x32_bf16 v[62:65], v[142:145], v[174:177], 0
	v_mfma_f32_16x16x32_bf16 v[58:61], v[150:153], v[174:177], 0
	v_mfma_f32_16x16x32_bf16 v[54:57], v[142:145], v[182:185], 0
	v_mfma_f32_16x16x32_bf16 v[46:49], v[150:153], v[182:185], 0
	v_mfma_f32_16x16x32_bf16 v[38:41], v[142:145], v[190:193], 0
	v_mfma_f32_16x16x32_bf16 v[30:33], v[150:153], v[190:193], 0
	v_mfma_f32_16x16x32_bf16 v[22:25], v[142:145], v[198:201], 0
	v_mfma_f32_16x16x32_bf16 v[14:17], v[150:153], v[198:201], 0
	v_mfma_f32_16x16x32_bf16 v[62:65], v[146:149], v[178:181], v[62:65]
	v_mfma_f32_16x16x32_bf16 v[58:61], v[154:157], v[178:181], v[58:61]
	v_mfma_f32_16x16x32_bf16 v[54:57], v[146:149], v[186:189], v[54:57]
	v_mfma_f32_16x16x32_bf16 v[46:49], v[154:157], v[186:189], v[46:49]
	v_mfma_f32_16x16x32_bf16 v[38:41], v[146:149], v[194:197], v[38:41]
	v_mfma_f32_16x16x32_bf16 v[30:33], v[154:157], v[194:197], v[30:33]
	v_mfma_f32_16x16x32_bf16 v[22:25], v[146:149], v[204:207], v[22:25]
	v_mfma_f32_16x16x32_bf16 v[14:17], v[154:157], v[204:207], v[14:17]
	s_setprio 0
	s_setprio 1
	v_mfma_f32_16x16x32_bf16 v[50:53], v[158:161], v[174:177], 0
	v_mfma_f32_16x16x32_bf16 v[42:45], v[166:169], v[174:177], 0
	v_mfma_f32_16x16x32_bf16 v[34:37], v[158:161], v[182:185], 0
	v_mfma_f32_16x16x32_bf16 v[26:29], v[166:169], v[182:185], 0
	v_mfma_f32_16x16x32_bf16 v[18:21], v[158:161], v[190:193], 0
	v_mfma_f32_16x16x32_bf16 v[10:13], v[166:169], v[190:193], 0
	v_mfma_f32_16x16x32_bf16 v[6:9], v[158:161], v[198:201], 0
	v_mfma_f32_16x16x32_bf16 v[2:5], v[166:169], v[198:201], 0
	v_mfma_f32_16x16x32_bf16 v[50:53], v[162:165], v[178:181], v[50:53]
	v_mfma_f32_16x16x32_bf16 v[42:45], v[170:173], v[178:181], v[42:45]
	v_mfma_f32_16x16x32_bf16 v[34:37], v[162:165], v[186:189], v[34:37]
	v_mfma_f32_16x16x32_bf16 v[26:29], v[170:173], v[186:189], v[26:29]
	v_mfma_f32_16x16x32_bf16 v[18:21], v[162:165], v[194:197], v[18:21]
	v_mfma_f32_16x16x32_bf16 v[10:13], v[170:173], v[194:197], v[10:13]
	v_mfma_f32_16x16x32_bf16 v[6:9], v[162:165], v[204:207], v[6:9]
	v_mfma_f32_16x16x32_bf16 v[2:5], v[170:173], v[204:207], v[2:5]
	s_setprio 0
	s_barrier
	v_add_u32_e32 v130, s27, v137
	ds_read_b128 v[142:145], v130
	ds_read_b128 v[146:149], v130 offset:1024
	ds_read_b128 v[150:153], v130 offset:2048
	ds_read_b128 v[154:157], v130 offset:3072
	v_add_u32_e32 v130, s34, v137
	ds_read_b128 v[158:161], v130
	ds_read_b128 v[162:165], v130 offset:1024
	ds_read_b128 v[166:169], v130 offset:2048
	ds_read_b128 v[170:173], v130 offset:3072
	s_add_i32 s50, s50, 0x160000
	s_mov_b32 m0, s25
	v_add_u32_e32 v130, s50, v132
	ds_read_b128 v[174:177], v141 offset:32768
	ds_read_b128 v[178:181], v141 offset:33792
	ds_read_b128 v[182:185], v141 offset:34816
	ds_read_b128 v[186:189], v141 offset:35840
	ds_read_b128 v[190:193], v141 offset:36864
	ds_read_b128 v[194:197], v141 offset:37888
	ds_read_b128 v[198:201], v141 offset:38912
	ds_read_b128 v[204:207], v141 offset:39936
	global_load_lds_dwordx4 v130, s[0:1]
	v_add_u32_e32 v130, s50, v134
	s_mov_b32 m0, s26
	s_nop 0
	global_load_lds_dwordx4 v130, s[0:1]
	s_waitcnt vmcnt(8)
	s_waitcnt lgkmcnt(0)
	s_setprio 1
	s_barrier
	v_mfma_f32_16x16x32_bf16 v[126:129], v[142:145], v[174:177], v[126:129]
	v_mfma_f32_16x16x32_bf16 v[122:125], v[150:153], v[174:177], v[122:125]
	v_mfma_f32_16x16x32_bf16 v[118:121], v[142:145], v[182:185], v[118:121]
	v_mfma_f32_16x16x32_bf16 v[110:113], v[150:153], v[182:185], v[110:113]
	v_mfma_f32_16x16x32_bf16 v[102:105], v[142:145], v[190:193], v[102:105]
	v_mfma_f32_16x16x32_bf16 v[94:97], v[150:153], v[190:193], v[94:97]
	v_mfma_f32_16x16x32_bf16 v[86:89], v[142:145], v[198:201], v[86:89]
	v_mfma_f32_16x16x32_bf16 v[78:81], v[150:153], v[198:201], v[78:81]
	v_mfma_f32_16x16x32_bf16 v[126:129], v[146:149], v[178:181], v[126:129]
	v_mfma_f32_16x16x32_bf16 v[122:125], v[154:157], v[178:181], v[122:125]
	v_mfma_f32_16x16x32_bf16 v[118:121], v[146:149], v[186:189], v[118:121]
	v_mfma_f32_16x16x32_bf16 v[110:113], v[154:157], v[186:189], v[110:113]
	v_mfma_f32_16x16x32_bf16 v[102:105], v[146:149], v[194:197], v[102:105]
	v_mfma_f32_16x16x32_bf16 v[94:97], v[154:157], v[194:197], v[94:97]
	v_mfma_f32_16x16x32_bf16 v[86:89], v[146:149], v[204:207], v[86:89]
	v_mfma_f32_16x16x32_bf16 v[78:81], v[154:157], v[204:207], v[78:81]
	s_setprio 0
	s_setprio 1
	v_mfma_f32_16x16x32_bf16 v[114:117], v[158:161], v[174:177], v[114:117]
	v_mfma_f32_16x16x32_bf16 v[106:109], v[166:169], v[174:177], v[106:109]
	v_mfma_f32_16x16x32_bf16 v[98:101], v[158:161], v[182:185], v[98:101]
	v_mfma_f32_16x16x32_bf16 v[90:93], v[166:169], v[182:185], v[90:93]
	v_mfma_f32_16x16x32_bf16 v[82:85], v[158:161], v[190:193], v[82:85]
	v_mfma_f32_16x16x32_bf16 v[74:77], v[166:169], v[190:193], v[74:77]
	v_mfma_f32_16x16x32_bf16 v[70:73], v[158:161], v[198:201], v[70:73]
	v_mfma_f32_16x16x32_bf16 v[66:69], v[166:169], v[198:201], v[66:69]
	v_mfma_f32_16x16x32_bf16 v[114:117], v[162:165], v[178:181], v[114:117]
	v_mfma_f32_16x16x32_bf16 v[106:109], v[170:173], v[178:181], v[106:109]
	v_mfma_f32_16x16x32_bf16 v[98:101], v[162:165], v[186:189], v[98:101]
	v_mfma_f32_16x16x32_bf16 v[90:93], v[170:173], v[186:189], v[90:93]
	v_mfma_f32_16x16x32_bf16 v[82:85], v[162:165], v[194:197], v[82:85]
	v_mfma_f32_16x16x32_bf16 v[74:77], v[170:173], v[194:197], v[74:77]
	v_mfma_f32_16x16x32_bf16 v[70:73], v[162:165], v[204:207], v[70:73]
	v_mfma_f32_16x16x32_bf16 v[66:69], v[170:173], v[204:207], v[66:69]
	s_setprio 0
	s_barrier
	s_or_b32 s50, s49, 0x80
	s_mov_b32 m0, s28
	v_add_u32_e32 v130, s50, v133
	ds_read_b128 v[174:177], v141 offset:49152
	ds_read_b128 v[178:181], v141 offset:50176
	ds_read_b128 v[182:185], v141 offset:51200
	ds_read_b128 v[186:189], v141 offset:52224
	ds_read_b128 v[190:193], v141 offset:53248
	ds_read_b128 v[194:197], v141 offset:54272
	ds_read_b128 v[198:201], v141 offset:55296
	ds_read_b128 v[204:207], v141 offset:56320
	global_load_lds_dwordx4 v130, s[2:3]
	v_add_u32_e32 v130, s50, v135
	s_mov_b32 m0, s29
	s_add_i32 s49, s49, 0x160080
	global_load_lds_dwordx4 v130, s[2:3]
	v_add_u32_e32 v130, s49, v133
	s_mov_b32 m0, s35
	s_nop 0
	global_load_lds_dwordx4 v130, s[2:3]
	v_add_u32_e32 v130, s49, v135
	s_mov_b32 m0, s36
	s_nop 0
	global_load_lds_dwordx4 v130, s[2:3]
	v_add_u32_e32 v130, s48, v132
	s_mov_b32 m0, s30
	s_nop 0
	global_load_lds_dwordx4 v130, s[0:1]
	v_add_u32_e32 v130, s48, v134
	s_mov_b32 m0, s31
	s_nop 0
	global_load_lds_dwordx4 v130, s[0:1]
	s_waitcnt vmcnt(8)
	s_waitcnt lgkmcnt(0)
	s_setprio 1
	s_barrier
	v_mfma_f32_16x16x32_bf16 v[62:65], v[142:145], v[174:177], v[62:65]
	v_mfma_f32_16x16x32_bf16 v[58:61], v[150:153], v[174:177], v[58:61]
	v_mfma_f32_16x16x32_bf16 v[54:57], v[142:145], v[182:185], v[54:57]
	v_mfma_f32_16x16x32_bf16 v[46:49], v[150:153], v[182:185], v[46:49]
	v_mfma_f32_16x16x32_bf16 v[38:41], v[142:145], v[190:193], v[38:41]
	v_mfma_f32_16x16x32_bf16 v[30:33], v[150:153], v[190:193], v[30:33]
	v_mfma_f32_16x16x32_bf16 v[22:25], v[142:145], v[198:201], v[22:25]
	v_mfma_f32_16x16x32_bf16 v[14:17], v[150:153], v[198:201], v[14:17]
	v_mfma_f32_16x16x32_bf16 v[62:65], v[146:149], v[178:181], v[62:65]
	v_mfma_f32_16x16x32_bf16 v[58:61], v[154:157], v[178:181], v[58:61]
	v_mfma_f32_16x16x32_bf16 v[54:57], v[146:149], v[186:189], v[54:57]
	v_mfma_f32_16x16x32_bf16 v[46:49], v[154:157], v[186:189], v[46:49]
	v_mfma_f32_16x16x32_bf16 v[38:41], v[146:149], v[194:197], v[38:41]
	v_mfma_f32_16x16x32_bf16 v[30:33], v[154:157], v[194:197], v[30:33]
	v_mfma_f32_16x16x32_bf16 v[22:25], v[146:149], v[204:207], v[22:25]
	v_mfma_f32_16x16x32_bf16 v[14:17], v[154:157], v[204:207], v[14:17]
	s_setprio 0
	s_setprio 1
	v_mfma_f32_16x16x32_bf16 v[50:53], v[158:161], v[174:177], v[50:53]
	v_mfma_f32_16x16x32_bf16 v[42:45], v[166:169], v[174:177], v[42:45]
	v_mfma_f32_16x16x32_bf16 v[34:37], v[158:161], v[182:185], v[34:37]
	v_mfma_f32_16x16x32_bf16 v[26:29], v[166:169], v[182:185], v[26:29]
	v_mfma_f32_16x16x32_bf16 v[18:21], v[158:161], v[190:193], v[18:21]
	v_mfma_f32_16x16x32_bf16 v[10:13], v[166:169], v[190:193], v[10:13]
	v_mfma_f32_16x16x32_bf16 v[6:9], v[158:161], v[198:201], v[6:9]
	v_mfma_f32_16x16x32_bf16 v[2:5], v[166:169], v[198:201], v[2:5]
	v_mfma_f32_16x16x32_bf16 v[50:53], v[162:165], v[178:181], v[50:53]
	v_mfma_f32_16x16x32_bf16 v[42:45], v[170:173], v[178:181], v[42:45]
	v_mfma_f32_16x16x32_bf16 v[34:37], v[162:165], v[186:189], v[34:37]
	v_mfma_f32_16x16x32_bf16 v[26:29], v[170:173], v[186:189], v[26:29]
	v_mfma_f32_16x16x32_bf16 v[18:21], v[162:165], v[194:197], v[18:21]
	v_mfma_f32_16x16x32_bf16 v[10:13], v[170:173], v[194:197], v[10:13]
	v_mfma_f32_16x16x32_bf16 v[6:9], v[162:165], v[204:207], v[6:9]
	v_mfma_f32_16x16x32_bf16 v[2:5], v[170:173], v[204:207], v[2:5]
	s_setprio 0
	s_barrier
	s_add_i32 s47, s47, 2
	s_addk_i32 s45, 0x100
	s_addk_i32 s46, 0x100
	s_cmpk_gt_u32 s47, 0x55
.LBB0_784:
	v_add_u32_e32 v130, s17, v137
	ds_read_b128 v[142:145], v130
	ds_read_b128 v[146:149], v130 offset:1024
	ds_read_b128 v[150:153], v130 offset:2048
	ds_read_b128 v[154:157], v130 offset:3072
	v_add_u32_e32 v130, s20, v137
	ds_read_b128 v[158:161], v130
	ds_read_b128 v[162:165], v130 offset:1024
	ds_read_b128 v[166:169], v130 offset:2048
	ds_read_b128 v[170:173], v130 offset:3072
	s_add_i32 s48, s45, 0xffea0080
	s_cmpk_eq_i32 s47, 0x54
	s_cselect_b32 s50, s43, s48
	s_cselect_b32 s49, s44, s46
	s_or_b32 s48, s50, 0x80
	v_add_u32_e32 v130, s45, v140
	s_add_i32 m0, s23, 0xc000
	ds_read_b128 v[174:177], v141
	ds_read_b128 v[178:181], v141 offset:1024
	ds_read_b128 v[182:185], v141 offset:2048
	ds_read_b128 v[186:189], v141 offset:3072
	ds_read_b128 v[190:193], v141 offset:4096
	ds_read_b128 v[194:197], v141 offset:5120
	ds_read_b128 v[198:201], v141 offset:6144
	ds_read_b128 v[204:207], v141 offset:7168
	global_load_lds_dwordx4 v130, s[0:1]
	v_add_u32_e32 v130, s45, v139
	s_add_i32 m0, s23, 0xe000
	s_nop 0
	global_load_lds_dwordx4 v130, s[0:1]
	s_waitcnt vmcnt(8)
	s_waitcnt lgkmcnt(0)
	s_setprio 1
	s_barrier
	v_mfma_f32_16x16x32_bf16 v[126:129], v[142:145], v[174:177], v[126:129]
	v_mfma_f32_16x16x32_bf16 v[122:125], v[150:153], v[174:177], v[122:125]
	v_mfma_f32_16x16x32_bf16 v[118:121], v[142:145], v[182:185], v[118:121]
	v_mfma_f32_16x16x32_bf16 v[110:113], v[150:153], v[182:185], v[110:113]
	v_mfma_f32_16x16x32_bf16 v[102:105], v[142:145], v[190:193], v[102:105]
	v_mfma_f32_16x16x32_bf16 v[94:97], v[150:153], v[190:193], v[94:97]
	v_mfma_f32_16x16x32_bf16 v[86:89], v[142:145], v[198:201], v[86:89]
	v_mfma_f32_16x16x32_bf16 v[78:81], v[150:153], v[198:201], v[78:81]
	v_mfma_f32_16x16x32_bf16 v[126:129], v[146:149], v[178:181], v[126:129]
	v_mfma_f32_16x16x32_bf16 v[122:125], v[154:157], v[178:181], v[122:125]
	v_mfma_f32_16x16x32_bf16 v[118:121], v[146:149], v[186:189], v[118:121]
	v_mfma_f32_16x16x32_bf16 v[110:113], v[154:157], v[186:189], v[110:113]
	v_mfma_f32_16x16x32_bf16 v[102:105], v[146:149], v[194:197], v[102:105]
	v_mfma_f32_16x16x32_bf16 v[94:97], v[154:157], v[194:197], v[94:97]
	v_mfma_f32_16x16x32_bf16 v[86:89], v[146:149], v[204:207], v[86:89]
	v_mfma_f32_16x16x32_bf16 v[78:81], v[154:157], v[204:207], v[78:81]
	s_setprio 0
	s_setprio 1
	v_mfma_f32_16x16x32_bf16 v[114:117], v[158:161], v[174:177], v[114:117]
	v_mfma_f32_16x16x32_bf16 v[106:109], v[166:169], v[174:177], v[106:109]
	v_mfma_f32_16x16x32_bf16 v[98:101], v[158:161], v[182:185], v[98:101]
	v_mfma_f32_16x16x32_bf16 v[90:93], v[166:169], v[182:185], v[90:93]
	v_mfma_f32_16x16x32_bf16 v[82:85], v[158:161], v[190:193], v[82:85]
	v_mfma_f32_16x16x32_bf16 v[74:77], v[166:169], v[190:193], v[74:77]
	v_mfma_f32_16x16x32_bf16 v[70:73], v[158:161], v[198:201], v[70:73]
	v_mfma_f32_16x16x32_bf16 v[66:69], v[166:169], v[198:201], v[66:69]
	v_mfma_f32_16x16x32_bf16 v[114:117], v[162:165], v[178:181], v[114:117]
	v_mfma_f32_16x16x32_bf16 v[106:109], v[170:173], v[178:181], v[106:109]
	v_mfma_f32_16x16x32_bf16 v[98:101], v[162:165], v[186:189], v[98:101]
	v_mfma_f32_16x16x32_bf16 v[90:93], v[170:173], v[186:189], v[90:93]
	v_mfma_f32_16x16x32_bf16 v[82:85], v[162:165], v[194:197], v[82:85]
	v_mfma_f32_16x16x32_bf16 v[74:77], v[170:173], v[194:197], v[74:77]
	v_mfma_f32_16x16x32_bf16 v[70:73], v[162:165], v[204:207], v[70:73]
	v_mfma_f32_16x16x32_bf16 v[66:69], v[170:173], v[204:207], v[66:69]
	s_setprio 0
	s_barrier
	s_mov_b32 m0, s18
	v_add_u32_e32 v130, s49, v133
	ds_read_b128 v[174:177], v141 offset:16384
	ds_read_b128 v[178:181], v141 offset:17408
	ds_read_b128 v[182:185], v141 offset:18432
	ds_read_b128 v[186:189], v141 offset:19456
	ds_read_b128 v[190:193], v141 offset:20480
	ds_read_b128 v[194:197], v141 offset:21504
	ds_read_b128 v[198:201], v141 offset:22528
	ds_read_b128 v[204:207], v141 offset:23552
	global_load_lds_dwordx4 v130, s[2:3]
	v_add_u32_e32 v130, s49, v135
	s_mov_b32 m0, s19
	s_add_i32 s51, s49, 0x160000
	global_load_lds_dwordx4 v130, s[2:3]
	v_add_u32_e32 v130, s51, v133
	s_mov_b32 m0, s21
	s_nop 0
	global_load_lds_dwordx4 v130, s[2:3]
	v_add_u32_e32 v130, s51, v135
	s_mov_b32 m0, s22
	s_nop 0
	global_load_lds_dwordx4 v130, s[2:3]
	v_add_u32_e32 v130, s50, v132
	s_mov_b32 m0, s23
	s_nop 0
	global_load_lds_dwordx4 v130, s[0:1]
	v_add_u32_e32 v130, s50, v134
	s_mov_b32 m0, s24
	s_nop 0
	global_load_lds_dwordx4 v130, s[0:1]
	s_waitcnt vmcnt(8)
	s_waitcnt lgkmcnt(0)
	s_setprio 1
	s_barrier
	v_mfma_f32_16x16x32_bf16 v[62:65], v[142:145], v[174:177], v[62:65]
	v_mfma_f32_16x16x32_bf16 v[58:61], v[150:153], v[174:177], v[58:61]
	v_mfma_f32_16x16x32_bf16 v[54:57], v[142:145], v[182:185], v[54:57]
	v_mfma_f32_16x16x32_bf16 v[46:49], v[150:153], v[182:185], v[46:49]
	v_mfma_f32_16x16x32_bf16 v[38:41], v[142:145], v[190:193], v[38:41]
	v_mfma_f32_16x16x32_bf16 v[30:33], v[150:153], v[190:193], v[30:33]
	v_mfma_f32_16x16x32_bf16 v[22:25], v[142:145], v[198:201], v[22:25]
	v_mfma_f32_16x16x32_bf16 v[14:17], v[150:153], v[198:201], v[14:17]
	v_mfma_f32_16x16x32_bf16 v[62:65], v[146:149], v[178:181], v[62:65]
	v_mfma_f32_16x16x32_bf16 v[58:61], v[154:157], v[178:181], v[58:61]
	v_mfma_f32_16x16x32_bf16 v[54:57], v[146:149], v[186:189], v[54:57]
	v_mfma_f32_16x16x32_bf16 v[46:49], v[154:157], v[186:189], v[46:49]
	v_mfma_f32_16x16x32_bf16 v[38:41], v[146:149], v[194:197], v[38:41]
	v_mfma_f32_16x16x32_bf16 v[30:33], v[154:157], v[194:197], v[30:33]
	v_mfma_f32_16x16x32_bf16 v[22:25], v[146:149], v[204:207], v[22:25]
	v_mfma_f32_16x16x32_bf16 v[14:17], v[154:157], v[204:207], v[14:17]
	s_setprio 0
	s_setprio 1
	v_mfma_f32_16x16x32_bf16 v[50:53], v[158:161], v[174:177], v[50:53]
	v_mfma_f32_16x16x32_bf16 v[42:45], v[166:169], v[174:177], v[42:45]
	v_mfma_f32_16x16x32_bf16 v[34:37], v[158:161], v[182:185], v[34:37]
	v_mfma_f32_16x16x32_bf16 v[26:29], v[166:169], v[182:185], v[26:29]
	v_mfma_f32_16x16x32_bf16 v[18:21], v[158:161], v[190:193], v[18:21]
	v_mfma_f32_16x16x32_bf16 v[10:13], v[166:169], v[190:193], v[10:13]
	v_mfma_f32_16x16x32_bf16 v[6:9], v[158:161], v[198:201], v[6:9]
	v_mfma_f32_16x16x32_bf16 v[2:5], v[166:169], v[198:201], v[2:5]
	v_mfma_f32_16x16x32_bf16 v[50:53], v[162:165], v[178:181], v[50:53]
	v_mfma_f32_16x16x32_bf16 v[42:45], v[170:173], v[178:181], v[42:45]
	v_mfma_f32_16x16x32_bf16 v[34:37], v[162:165], v[186:189], v[34:37]
	v_mfma_f32_16x16x32_bf16 v[26:29], v[170:173], v[186:189], v[26:29]
	v_mfma_f32_16x16x32_bf16 v[18:21], v[162:165], v[194:197], v[18:21]
	v_mfma_f32_16x16x32_bf16 v[10:13], v[170:173], v[194:197], v[10:13]
	v_mfma_f32_16x16x32_bf16 v[6:9], v[162:165], v[204:207], v[6:9]
	v_mfma_f32_16x16x32_bf16 v[2:5], v[170:173], v[204:207], v[2:5]
	s_setprio 0
	s_barrier
	v_add_u32_e32 v130, s27, v137
	ds_read_b128 v[142:145], v130
	ds_read_b128 v[146:149], v130 offset:1024
	ds_read_b128 v[150:153], v130 offset:2048
	ds_read_b128 v[154:157], v130 offset:3072
	v_add_u32_e32 v130, s34, v137
	ds_read_b128 v[158:161], v130
	ds_read_b128 v[162:165], v130 offset:1024
	ds_read_b128 v[166:169], v130 offset:2048
	ds_read_b128 v[170:173], v130 offset:3072
	s_add_i32 s50, s50, 0x160000
	s_mov_b32 m0, s25
	v_add_u32_e32 v130, s50, v132
	ds_read_b128 v[174:177], v141 offset:32768
	ds_read_b128 v[178:181], v141 offset:33792
	ds_read_b128 v[182:185], v141 offset:34816
	ds_read_b128 v[186:189], v141 offset:35840
	ds_read_b128 v[190:193], v141 offset:36864
	ds_read_b128 v[194:197], v141 offset:37888
	ds_read_b128 v[198:201], v141 offset:38912
	ds_read_b128 v[204:207], v141 offset:39936
	global_load_lds_dwordx4 v130, s[0:1]
	v_add_u32_e32 v130, s50, v134
	s_mov_b32 m0, s26
	s_nop 0
	global_load_lds_dwordx4 v130, s[0:1]
	s_waitcnt vmcnt(8)
	s_waitcnt lgkmcnt(0)
	s_setprio 1
	s_barrier
	v_mfma_f32_16x16x32_bf16 v[126:129], v[142:145], v[174:177], v[126:129]
	v_mfma_f32_16x16x32_bf16 v[122:125], v[150:153], v[174:177], v[122:125]
	v_mfma_f32_16x16x32_bf16 v[118:121], v[142:145], v[182:185], v[118:121]
	v_mfma_f32_16x16x32_bf16 v[110:113], v[150:153], v[182:185], v[110:113]
	v_mfma_f32_16x16x32_bf16 v[102:105], v[142:145], v[190:193], v[102:105]
	v_mfma_f32_16x16x32_bf16 v[94:97], v[150:153], v[190:193], v[94:97]
	v_mfma_f32_16x16x32_bf16 v[86:89], v[142:145], v[198:201], v[86:89]
	v_mfma_f32_16x16x32_bf16 v[78:81], v[150:153], v[198:201], v[78:81]
	v_mfma_f32_16x16x32_bf16 v[126:129], v[146:149], v[178:181], v[126:129]
	v_mfma_f32_16x16x32_bf16 v[122:125], v[154:157], v[178:181], v[122:125]
	v_mfma_f32_16x16x32_bf16 v[118:121], v[146:149], v[186:189], v[118:121]
	v_mfma_f32_16x16x32_bf16 v[110:113], v[154:157], v[186:189], v[110:113]
	v_mfma_f32_16x16x32_bf16 v[102:105], v[146:149], v[194:197], v[102:105]
	v_mfma_f32_16x16x32_bf16 v[94:97], v[154:157], v[194:197], v[94:97]
	v_mfma_f32_16x16x32_bf16 v[86:89], v[146:149], v[204:207], v[86:89]
	v_mfma_f32_16x16x32_bf16 v[78:81], v[154:157], v[204:207], v[78:81]
	s_setprio 0
	s_setprio 1
	v_mfma_f32_16x16x32_bf16 v[114:117], v[158:161], v[174:177], v[114:117]
	v_mfma_f32_16x16x32_bf16 v[106:109], v[166:169], v[174:177], v[106:109]
	v_mfma_f32_16x16x32_bf16 v[98:101], v[158:161], v[182:185], v[98:101]
	v_mfma_f32_16x16x32_bf16 v[90:93], v[166:169], v[182:185], v[90:93]
	v_mfma_f32_16x16x32_bf16 v[82:85], v[158:161], v[190:193], v[82:85]
	v_mfma_f32_16x16x32_bf16 v[74:77], v[166:169], v[190:193], v[74:77]
	v_mfma_f32_16x16x32_bf16 v[70:73], v[158:161], v[198:201], v[70:73]
	v_mfma_f32_16x16x32_bf16 v[66:69], v[166:169], v[198:201], v[66:69]
	v_mfma_f32_16x16x32_bf16 v[114:117], v[162:165], v[178:181], v[114:117]
	v_mfma_f32_16x16x32_bf16 v[106:109], v[170:173], v[178:181], v[106:109]
	v_mfma_f32_16x16x32_bf16 v[98:101], v[162:165], v[186:189], v[98:101]
	v_mfma_f32_16x16x32_bf16 v[90:93], v[170:173], v[186:189], v[90:93]
	v_mfma_f32_16x16x32_bf16 v[82:85], v[162:165], v[194:197], v[82:85]
	v_mfma_f32_16x16x32_bf16 v[74:77], v[170:173], v[194:197], v[74:77]
	v_mfma_f32_16x16x32_bf16 v[70:73], v[162:165], v[204:207], v[70:73]
	v_mfma_f32_16x16x32_bf16 v[66:69], v[170:173], v[204:207], v[66:69]
	s_setprio 0
	s_barrier
	s_or_b32 s50, s49, 0x80
	s_mov_b32 m0, s28
	v_add_u32_e32 v130, s50, v133
	ds_read_b128 v[174:177], v141 offset:49152
	ds_read_b128 v[178:181], v141 offset:50176
	ds_read_b128 v[182:185], v141 offset:51200
	ds_read_b128 v[186:189], v141 offset:52224
	ds_read_b128 v[190:193], v141 offset:53248
	ds_read_b128 v[194:197], v141 offset:54272
	ds_read_b128 v[198:201], v141 offset:55296
	ds_read_b128 v[204:207], v141 offset:56320
	global_load_lds_dwordx4 v130, s[2:3]
	v_add_u32_e32 v130, s50, v135
	s_mov_b32 m0, s29
	s_add_i32 s49, s49, 0x160080
	global_load_lds_dwordx4 v130, s[2:3]
	v_add_u32_e32 v130, s49, v133
	s_mov_b32 m0, s35
	s_nop 0
	global_load_lds_dwordx4 v130, s[2:3]
	v_add_u32_e32 v130, s49, v135
	s_mov_b32 m0, s36
	s_nop 0
	global_load_lds_dwordx4 v130, s[2:3]
	v_add_u32_e32 v130, s48, v132
	s_mov_b32 m0, s30
	s_nop 0
	global_load_lds_dwordx4 v130, s[0:1]
	v_add_u32_e32 v130, s48, v134
	s_mov_b32 m0, s31
	s_nop 0
	global_load_lds_dwordx4 v130, s[0:1]
	s_add_i32 s47, s47, 2
	s_addk_i32 s45, 0x100
	s_addk_i32 s46, 0x100
	s_cmpk_gt_u32 s47, 0x55
	s_waitcnt vmcnt(8)
	s_waitcnt lgkmcnt(0)
	s_setprio 1
	s_barrier
	v_mfma_f32_16x16x32_bf16 v[62:65], v[142:145], v[174:177], v[62:65]
	v_mfma_f32_16x16x32_bf16 v[58:61], v[150:153], v[174:177], v[58:61]
	v_mfma_f32_16x16x32_bf16 v[54:57], v[142:145], v[182:185], v[54:57]
	v_mfma_f32_16x16x32_bf16 v[46:49], v[150:153], v[182:185], v[46:49]
	v_mfma_f32_16x16x32_bf16 v[38:41], v[142:145], v[190:193], v[38:41]
	v_mfma_f32_16x16x32_bf16 v[30:33], v[150:153], v[190:193], v[30:33]
	v_mfma_f32_16x16x32_bf16 v[22:25], v[142:145], v[198:201], v[22:25]
	v_mfma_f32_16x16x32_bf16 v[14:17], v[150:153], v[198:201], v[14:17]
	v_mfma_f32_16x16x32_bf16 v[62:65], v[146:149], v[178:181], v[62:65]
	v_mfma_f32_16x16x32_bf16 v[58:61], v[154:157], v[178:181], v[58:61]
	v_mfma_f32_16x16x32_bf16 v[54:57], v[146:149], v[186:189], v[54:57]
	v_mfma_f32_16x16x32_bf16 v[46:49], v[154:157], v[186:189], v[46:49]
	v_mfma_f32_16x16x32_bf16 v[38:41], v[146:149], v[194:197], v[38:41]
	v_mfma_f32_16x16x32_bf16 v[30:33], v[154:157], v[194:197], v[30:33]
	v_mfma_f32_16x16x32_bf16 v[22:25], v[146:149], v[204:207], v[22:25]
	v_mfma_f32_16x16x32_bf16 v[14:17], v[154:157], v[204:207], v[14:17]
	s_setprio 0
	s_setprio 1
	v_mfma_f32_16x16x32_bf16 v[50:53], v[158:161], v[174:177], v[50:53]
	v_mfma_f32_16x16x32_bf16 v[42:45], v[166:169], v[174:177], v[42:45]
	v_mfma_f32_16x16x32_bf16 v[34:37], v[158:161], v[182:185], v[34:37]
	v_mfma_f32_16x16x32_bf16 v[26:29], v[166:169], v[182:185], v[26:29]
	v_mfma_f32_16x16x32_bf16 v[18:21], v[158:161], v[190:193], v[18:21]
	v_mfma_f32_16x16x32_bf16 v[10:13], v[166:169], v[190:193], v[10:13]
	v_mfma_f32_16x16x32_bf16 v[6:9], v[158:161], v[198:201], v[6:9]
	v_mfma_f32_16x16x32_bf16 v[2:5], v[166:169], v[198:201], v[2:5]
	v_mfma_f32_16x16x32_bf16 v[50:53], v[162:165], v[178:181], v[50:53]
	v_mfma_f32_16x16x32_bf16 v[42:45], v[170:173], v[178:181], v[42:45]
	v_mfma_f32_16x16x32_bf16 v[34:37], v[162:165], v[186:189], v[34:37]
	v_mfma_f32_16x16x32_bf16 v[26:29], v[170:173], v[186:189], v[26:29]
	v_mfma_f32_16x16x32_bf16 v[18:21], v[162:165], v[194:197], v[18:21]
	v_mfma_f32_16x16x32_bf16 v[10:13], v[170:173], v[194:197], v[10:13]
	v_mfma_f32_16x16x32_bf16 v[6:9], v[162:165], v[204:207], v[6:9]
	v_mfma_f32_16x16x32_bf16 v[2:5], v[170:173], v[204:207], v[2:5]
	s_setprio 0
	s_barrier
	s_cbranch_scc0 .LBB0_784
	s_and_b64 vcc, exec, s[10:11]
	s_cbranch_vccz .LBB0_787
	s_barrier
